# P4 EpiBranch epilogue hand-pipelined (gate loads prefetched via 3-slot ring, last segment skips gb math), IEEE div -> rcp+NR in EpiPle/ret_out, on top of sg grouped reads + P8 rebalance
# speedup vs baseline: 1.0092x; 1.0092x over previous
; DEV bf16_t f2bf(float f) { return (bf16_t)(cvt_pk_bf16(f, 0.f) & 0xffffu); }
; DEV float bf2f(unsigned h) { return __uint_as_float(h << 16); }
; DEV float sigmoidf_(float x) { return 1.0f / (1.0f + __expf(-x)); }
; DEV void ret_out_item(const Params& p, int l, int item, unsigned char* smem) {
;     ...
;   float ss[4] = {0.f, 0.f, 0.f, 0.f};
; #pragma unroll
;   for (int j = 0; j < 4; ++j) {
;     const float qd = __expf(lg * (float)(w * 16 + fq * 4 + j + 1));
; #pragma unroll
;     for (int et = 0; et < 8; ++et) { const float o = a1[et][j] + qd * a2[et][j]; a1[et][j] = o; ss[j] += o * o; }
;   }
; #pragma unroll
;   for (int j = 0; j < 4; ++j) {
;     float v = ss[j];
;     v += __shfl_xor(v, 1); v += __shfl_xor(v, 2); v += __shfl_xor(v, 4); v += __shfl_xor(v, 8);
;     const float rstd = rsqrtf(v * (1.0f / 128.0f) + 1e-6f);
;     bf16_t* gp = Gs + (w * 16 + fq * 4 + j) * 136 + fr;
; #pragma unroll
;     for (int et = 0; et < 8; ++et) {
;       const float g = bf2f(gp[et * 16]);
;       gp[et * 16] = f2bf(g * sigmoidf_(g) * a1[et][j] * rstd);
;     }
;   }
.LBB0_84:
	s_or_b64 exec, exec, s[0:1]
	v_or_b32_e32 v77, v83, v80
	v_or_b32_e32 v64, 1, v77
	v_cvt_f32_i32_e32 v64, v64
	v_mov_b32_e32 v65, v8
	v_or_b32_e32 v8, 2, v77
	v_cvt_f32_i32_e32 v8, v8
	v_mul_f32_e32 v64, v90, v64
	v_mul_f32_e32 v64, 0x3fb8aa3b, v64
	v_exp_f32_e32 v74, v64
	v_mul_f32_e32 v8, v90, v8
	v_mul_f32_e32 v8, 0x3fb8aa3b, v8
	v_mov_b32_e32 v64, v12
	v_exp_f32_e32 v12, v8
	v_mov_b32_e32 v66, v60
	v_mov_b32_e32 v67, v56
	v_pk_fma_f32 v[88:89], v[64:65], v[74:75], v[66:67] op_sel_hi:[1,0,1]
	v_mov_b32_e32 v64, v20
	v_mov_b32_e32 v65, v16
	v_mov_b32_e32 v68, v48
	v_mov_b32_e32 v69, v40
	v_pk_fma_f32 v[86:87], v[64:65], v[74:75], v[68:69] op_sel_hi:[1,0,1]
	v_mov_b32_e32 v64, v28
	v_mov_b32_e32 v65, v24
	v_mov_b32_e32 v68, v52
	v_mov_b32_e32 v69, v44
	v_pk_fma_f32 v[84:85], v[64:65], v[74:75], v[68:69] op_sel_hi:[1,0,1]
	v_mov_b32_e32 v75, v12
	v_mov_b32_e32 v56, v61
	v_pk_fma_f32 v[60:61], v[4:5], v[74:75], v[36:37]
	v_pk_fma_f32 v[64:65], v[0:1], v[74:75], v[32:33]
	v_pk_mul_f32 v[0:1], v[60:61], v[60:61]
	v_mov_b32_e32 v8, v13
	v_pk_fma_f32 v[82:83], v[64:65], v[64:65], v[0:1]
	v_or_b32_e32 v0, 3, v77
	v_cvt_f32_i32_e32 v0, v0
	v_pk_fma_f32 v[56:57], v[8:9], v[12:13], v[56:57] op_sel_hi:[1,0,1]
	v_mov_b32_e32 v4, v14
	v_mov_b32_e32 v5, v10
	v_mul_f32_e32 v0, v90, v0
	v_mul_f32_e32 v0, 0x3fb8aa3b, v0
	v_exp_f32_e32 v0, v0
	v_mov_b32_e32 v8, v62
	v_mov_b32_e32 v9, v58
	v_mov_b32_e32 v24, v29
	v_pk_fma_f32 v[36:37], v[4:5], v[0:1], v[8:9] op_sel_hi:[1,0,1]
	v_mov_b32_e32 v4, v22
	v_mov_b32_e32 v5, v18
	v_mov_b32_e32 v8, v50
	v_mov_b32_e32 v9, v42
	v_pk_fma_f32 v[32:33], v[4:5], v[0:1], v[8:9] op_sel_hi:[1,0,1]
	v_mov_b32_e32 v4, v30
	v_mov_b32_e32 v5, v26
	v_mov_b32_e32 v8, v54
	v_mov_b32_e32 v9, v46
	v_pk_fma_f32 v[28:29], v[4:5], v[0:1], v[8:9] op_sel_hi:[1,0,1]
	v_add_u32_e32 v1, 4, v77
	v_cvt_f32_i32_e32 v1, v1
	v_mov_b32_e32 v18, v23
	v_and_b32_e32 v23, 64, v202
	v_xor_b32_e32 v22, 1, v202
	v_mul_f32_e32 v1, v90, v1
	v_mul_f32_e32 v1, 0x3fb8aa3b, v1
	v_exp_f32_e32 v14, v1
	v_add_u32_e32 v23, 64, v23
	v_cmp_lt_i32_e32 vcc, v22, v23
	v_mov_b32_e32 v26, v31
	v_mov_b32_e32 v1, v14
	v_cndmask_b32_e32 v22, v202, v22, vcc
	v_pk_fma_f32 v[8:9], v[2:3], v[0:1], v[34:35]
	v_lshlrev_b32_e32 v34, 2, v22
	v_xor_b32_e32 v22, 2, v202
	v_cmp_lt_i32_e32 vcc, v22, v23
	v_pk_fma_f32 v[6:7], v[6:7], v[0:1], v[38:39]
	v_mov_b32_e32 v16, v21
	v_cndmask_b32_e32 v22, v202, v22, vcc
	v_lshlrev_b32_e32 v31, 2, v22
	v_xor_b32_e32 v22, 4, v202
	v_cmp_lt_i32_e32 vcc, v22, v23
	v_mov_b32_e32 v40, v49
	v_mov_b32_e32 v44, v53
	v_cndmask_b32_e32 v22, v202, v22, vcc
	v_lshlrev_b32_e32 v30, 2, v22
	v_xor_b32_e32 v22, 8, v202
	v_cmp_lt_i32_e32 vcc, v22, v23
	v_pk_mul_f32 v[0:1], v[6:7], v[6:7]
	v_mov_b32_e32 v46, v55
	v_cndmask_b32_e32 v22, v202, v22, vcc
	s_movk_i32 s13, 0x110
	v_pk_fma_f32 v[48:49], v[16:17], v[12:13], v[40:41] op_sel_hi:[1,0,1]
	v_pk_fma_f32 v[40:41], v[24:25], v[12:13], v[44:45] op_sel_hi:[1,0,1]
	v_pk_fma_f32 v[24:25], v[8:9], v[8:9], v[0:1]
	v_pk_fma_f32 v[0:1], v[26:27], v[14:15], v[46:47] op_sel_hi:[1,0,1]
	v_lshlrev_b32_e32 v27, 2, v22
	v_lshlrev_b32_e32 v22, 1, v81
	v_mul_lo_u32 v23, v77, s13
	v_readlane_b32 s12, v248, 15
	v_mov_b32_e32 v42, v51
	v_pk_fma_f32 v[2:3], v[18:19], v[14:15], v[42:43] op_sel_hi:[1,0,1]
	v_add3_u32 v26, s12, v22, v23
	ds_read_u16 v22, v26
	ds_read_u16 v23, v26 offset:32
	v_pk_mul_f32 v[66:67], v[88:89], v[88:89]
	v_pk_mul_f32 v[72:73], v[56:57], v[56:57]
	v_pk_mul_f32 v[70:71], v[86:87], v[86:87]
	s_waitcnt lgkmcnt(1)
	v_lshlrev_b32_e32 v22, 16, v22
	v_mul_f32_e32 v35, 0xbfb8aa3b, v22
	v_exp_f32_e32 v35, v35
	v_pk_mul_f32 v[74:75], v[48:49], v[48:49]
	v_pk_mul_f32 v[68:69], v[84:85], v[84:85]
	v_pk_mul_f32 v[44:45], v[40:41], v[40:41]
	v_add_f32_e32 v35, 1.0, v35
	v_rcp_f32_e32 v39, v35
	s_brev_b32 s4, 60
	s_mov_b32 s2, 0x800000
	v_pk_mul_f32 v[20:21], v[36:37], v[36:37]
	v_fma_f32 v42, -v35, v39, 1.0
	v_fmac_f32_e32 v39, v42, v39
	v_mov_b32_e32 v35, v39
	v_mul_f32_e32 v22, v35, v22
	v_mul_f32_e32 v35, v64, v22
	s_waitcnt lgkmcnt(0)
	v_lshlrev_b32_e32 v22, 16, v23
	v_mul_f32_e32 v23, 0xbfb8aa3b, v22
	v_exp_f32_e32 v23, v23
	v_pk_mul_f32 v[16:17], v[32:33], v[32:33]
	v_pk_mul_f32 v[12:13], v[28:29], v[28:29]
	v_mov_b32_e32 v10, v15
	v_add_f32_e32 v23, 1.0, v23
	v_rcp_f32_e32 v39, v23
	v_mov_b32_e32 v58, v63
	v_pk_fma_f32 v[4:5], v[10:11], v[14:15], v[58:59] op_sel_hi:[1,0,1]
	v_pk_mul_f32 v[18:19], v[2:3], v[2:3]
	v_fma_f32 v42, -v23, v39, 1.0
	v_fmac_f32_e32 v39, v42, v39
	v_mov_b32_e32 v23, v39
	v_mul_f32_e32 v22, v23, v22
	v_mul_f32_e32 v38, v60, v22
	ds_read_u16 v22, v26 offset:64
	v_pk_mul_f32 v[10:11], v[4:5], v[4:5]
	v_pk_mul_f32 v[14:15], v[0:1], v[0:1]
	v_ashrrev_i32_e32 v81, 31, v80
	s_lshl_b32 s6, s6, 1
	s_waitcnt lgkmcnt(0)
	v_lshlrev_b32_e32 v22, 16, v22
	v_mul_f32_e32 v23, 0xbfb8aa3b, v22
	v_exp_f32_e32 v23, v23
	v_mov_b32_e32 v77, v169
	v_add_f32_e32 v23, 1.0, v23
	v_rcp_f32_e32 v42, v23
	s_nop 0
	v_fma_f32 v43, -v23, v42, 1.0
	v_fmac_f32_e32 v42, v43, v42
	v_mov_b32_e32 v23, v42
	v_mul_f32_e32 v22, v23, v22
	v_mul_f32_e32 v39, v89, v22
	ds_read_u16 v22, v26 offset:96
	s_waitcnt lgkmcnt(0)
	v_lshlrev_b32_e32 v22, 16, v22
	v_mul_f32_e32 v23, 0xbfb8aa3b, v22
	v_exp_f32_e32 v23, v23
	s_nop 0
	v_add_f32_e32 v23, 1.0, v23
	v_rcp_f32_e32 v43, v23
	s_nop 0
	v_fma_f32 v46, -v23, v43, 1.0
	v_fmac_f32_e32 v43, v46, v43
	v_mov_b32_e32 v23, v43
	v_mul_f32_e32 v22, v23, v22
	v_mul_f32_e32 v42, v88, v22
	ds_read_u16 v22, v26 offset:128
	s_waitcnt lgkmcnt(0)
; DEV bf16_t f2bf(float f) { return (bf16_t)(cvt_pk_bf16(f, 0.f) & 0xffffu); }
; DEV float bf2f(unsigned h) { return __uint_as_float(h << 16); }
; DEV float sigmoidf_(float x) { return 1.0f / (1.0f + __expf(-x)); }
; DEV void ret_out_item(const Params& p, int l, int item, unsigned char* smem) {
;     ...
; #pragma unroll
;   for (int j = 0; j < 4; ++j) {
;     float v = ss[j];
;     v += __shfl_xor(v, 1); v += __shfl_xor(v, 2); v += __shfl_xor(v, 4); v += __shfl_xor(v, 8);
;     const float rstd = rsqrtf(v * (1.0f / 128.0f) + 1e-6f);
;     bf16_t* gp = Gs + (w * 16 + fq * 4 + j) * 136 + fr;
; #pragma unroll
;     for (int et = 0; et < 8; ++et) {
;       const float g = bf2f(gp[et * 16]);
;       gp[et * 16] = f2bf(g * sigmoidf_(g) * a1[et][j] * rstd);
;     }
;   }
	v_lshlrev_b32_e32 v22, 16, v22
	v_mul_f32_e32 v23, 0xbfb8aa3b, v22
	v_exp_f32_e32 v23, v23
	s_nop 0
	v_add_f32_e32 v23, 1.0, v23
	v_rcp_f32_e32 v46, v23
	s_nop 0
	v_fma_f32 v47, -v23, v46, 1.0
	v_fmac_f32_e32 v46, v47, v46
	v_mov_b32_e32 v23, v46
	v_mul_f32_e32 v22, v23, v22
	v_mul_f32_e32 v43, v87, v22
	ds_read_u16 v22, v26 offset:160
	s_waitcnt lgkmcnt(0)
	v_lshlrev_b32_e32 v22, 16, v22
	v_mul_f32_e32 v23, 0xbfb8aa3b, v22
	v_exp_f32_e32 v23, v23
	s_nop 0
	v_add_f32_e32 v23, 1.0, v23
	v_rcp_f32_e32 v47, v23
	s_nop 0
	v_fma_f32 v50, -v23, v47, 1.0
	v_fmac_f32_e32 v47, v50, v47
	v_mov_b32_e32 v23, v47
	v_mul_f32_e32 v22, v23, v22
	v_mul_f32_e32 v46, v86, v22
	ds_read_u16 v22, v26 offset:192
	s_waitcnt lgkmcnt(0)
	v_lshlrev_b32_e32 v22, 16, v22
	v_mul_f32_e32 v23, 0xbfb8aa3b, v22
	v_exp_f32_e32 v23, v23
	s_nop 0
	v_add_f32_e32 v23, 1.0, v23
	v_rcp_f32_e32 v50, v23
	s_nop 0
	v_fma_f32 v51, -v23, v50, 1.0
	v_fmac_f32_e32 v50, v51, v50
	v_mov_b32_e32 v23, v50
	v_mul_f32_e32 v22, v23, v22
	v_mul_f32_e32 v47, v85, v22
	ds_read_u16 v22, v26 offset:224
	s_waitcnt lgkmcnt(0)
	v_lshlrev_b32_e32 v22, 16, v22
	v_mul_f32_e32 v23, 0xbfb8aa3b, v22
	v_exp_f32_e32 v23, v23
	s_nop 0
	v_add_f32_e32 v23, 1.0, v23
	v_rcp_f32_e32 v51, v23
	s_mov_b32 s0, 0x358637bd
	v_fma_f32 v52, -v23, v51, 1.0
	v_fmac_f32_e32 v51, v52, v51
	v_mov_b32_e32 v23, v51
	v_mul_f32_e32 v22, v23, v22
	v_mov_b32_e32 v23, v66
	v_mov_b32_e32 v66, v73
	v_mul_f32_e32 v52, v84, v22
	v_mov_b32_e32 v22, v72
	v_pk_add_f32 v[50:51], v[66:67], v[82:83] op_sel:[0,1] op_sel_hi:[1,0]
	s_nop 0
	v_pk_add_f32 v[22:23], v[22:23], v[50:51]
	v_mov_b32_e32 v50, v75
	v_mov_b32_e32 v51, v71
	v_pk_add_f32 v[22:23], v[50:51], v[22:23]
	v_mov_b32_e32 v75, v70
	v_pk_add_f32 v[22:23], v[74:75], v[22:23]
	v_mov_b32_e32 v50, v45
	v_mov_b32_e32 v51, v69
	v_pk_add_f32 v[22:23], v[50:51], v[22:23]
	v_mov_b32_e32 v45, v68
	v_pk_add_f32 v[22:23], v[44:45], v[22:23]
	ds_bpermute_b32 v45, v34, v23
	ds_bpermute_b32 v44, v34, v22
	s_waitcnt lgkmcnt(0)
	v_pk_add_f32 v[22:23], v[22:23], v[44:45]
	ds_bpermute_b32 v45, v31, v23
	ds_bpermute_b32 v44, v31, v22
	s_waitcnt lgkmcnt(0)
	v_pk_add_f32 v[22:23], v[22:23], v[44:45]
	ds_bpermute_b32 v45, v30, v23
	ds_bpermute_b32 v44, v30, v22
	s_waitcnt lgkmcnt(0)
	v_pk_add_f32 v[22:23], v[22:23], v[44:45]
	ds_bpermute_b32 v45, v27, v23
	ds_bpermute_b32 v44, v27, v22
	s_waitcnt lgkmcnt(0)
	v_pk_add_f32 v[44:45], v[22:23], v[44:45]
	v_mov_b64_e32 v[22:23], s[0:1]
	v_pk_fma_f32 v[44:45], v[44:45], s[4:5], v[22:23] op_sel_hi:[1,0,0]
	s_nop 0
	v_mul_f32_e32 v50, 0x4b800000, v45
	v_cmp_gt_f32_e64 s[0:1], s2, v45
	v_cmp_gt_f32_e32 vcc, s2, v44
	s_nop 0
	v_cndmask_b32_e64 v45, v45, v50, s[0:1]
	v_rsq_f32_e32 v45, v45
	s_nop 0
	v_mul_f32_e32 v50, 0x45800000, v45
	v_cndmask_b32_e64 v45, v45, v50, s[0:1]
	v_mul_f32_e32 v35, v35, v45
	v_cvt_pk_bf16_f32 v35, v35, s0
	ds_write_b16 v26, v35
	v_mul_f32_e32 v35, v38, v45
	v_cvt_pk_bf16_f32 v35, v35, s0
	ds_write_b16 v26, v35 offset:32
	v_mul_f32_e32 v35, v39, v45
	v_cvt_pk_bf16_f32 v35, v35, s0
	ds_write_b16 v26, v35 offset:64
	v_mul_f32_e32 v35, v42, v45
	v_cvt_pk_bf16_f32 v35, v35, s0
	ds_write_b16 v26, v35 offset:96
	v_mul_f32_e32 v35, v43, v45
	v_cvt_pk_bf16_f32 v35, v35, s0
	ds_write_b16 v26, v35 offset:128
	v_mul_f32_e32 v35, v45, v46
	v_cvt_pk_bf16_f32 v35, v35, s0
	ds_write_b16 v26, v35 offset:160
	v_mul_f32_e32 v35, v45, v47
	v_cvt_pk_bf16_f32 v35, v35, s0
	ds_write_b16 v26, v35 offset:192
	v_mul_f32_e32 v35, v45, v52
	v_cvt_pk_bf16_f32 v35, v35, s0
	ds_write_b16 v26, v35 offset:224
	v_mul_f32_e32 v35, 0x4b800000, v44
	v_cndmask_b32_e32 v35, v44, v35, vcc
	v_rsq_f32_e32 v35, v35
	s_nop 0
	v_mul_f32_e32 v38, 0x45800000, v35
	v_cndmask_b32_e32 v35, v35, v38, vcc
	ds_read_u16 v38, v26 offset:272
	s_waitcnt lgkmcnt(0)
	v_lshlrev_b32_e32 v38, 16, v38
	v_mul_f32_e32 v39, 0xbfb8aa3b, v38
	v_exp_f32_e32 v39, v39
	s_nop 0
	v_add_f32_e32 v39, 1.0, v39
	v_rcp_f32_e32 v43, v39
	s_nop 0
	v_fma_f32 v44, -v39, v43, 1.0
	v_fmac_f32_e32 v43, v44, v43
	v_mov_b32_e32 v39, v43
	v_mul_f32_e32 v38, v39, v38
	v_mul_f32_e32 v38, v65, v38
	v_mul_f32_e32 v38, v35, v38
	v_cvt_pk_bf16_f32 v38, v38, s0
	ds_write_b16 v26, v38 offset:272
	ds_read_u16 v38, v26 offset:304
	s_waitcnt lgkmcnt(0)
	v_lshlrev_b32_e32 v38, 16, v38
	v_mul_f32_e32 v39, 0xbfb8aa3b, v38
	v_exp_f32_e32 v39, v39
	s_nop 0
	v_add_f32_e32 v39, 1.0, v39
	v_rcp_f32_e32 v43, v39
	s_nop 0
	v_fma_f32 v44, -v39, v43, 1.0
	v_fmac_f32_e32 v43, v44, v43
	v_mov_b32_e32 v39, v43
	v_mul_f32_e32 v38, v39, v38
	v_mul_f32_e32 v38, v61, v38
	v_mul_f32_e32 v38, v35, v38
	v_cvt_pk_bf16_f32 v38, v38, s0
	ds_write_b16 v26, v38 offset:304
	ds_read_u16 v38, v26 offset:336
	s_waitcnt lgkmcnt(0)
	v_lshlrev_b32_e32 v38, 16, v38
	v_mul_f32_e32 v39, 0xbfb8aa3b, v38
	v_exp_f32_e32 v39, v39
	s_nop 0
	v_add_f32_e32 v39, 1.0, v39
	v_rcp_f32_e32 v43, v39
	s_nop 0
	v_fma_f32 v44, -v39, v43, 1.0
	v_fmac_f32_e32 v43, v44, v43
	v_mov_b32_e32 v39, v43
	v_mul_f32_e32 v38, v39, v38
	v_mul_f32_e32 v38, v57, v38
	v_mul_f32_e32 v38, v35, v38
	v_cvt_pk_bf16_f32 v38, v38, s0
	ds_write_b16 v26, v38 offset:336
	ds_read_u16 v38, v26 offset:368
	s_waitcnt lgkmcnt(0)
	v_lshlrev_b32_e32 v38, 16, v38
	v_mul_f32_e32 v39, 0xbfb8aa3b, v38
	v_exp_f32_e32 v39, v39
	s_nop 0
	v_add_f32_e32 v39, 1.0, v39
	v_rcp_f32_e32 v43, v39
	s_nop 0
	v_fma_f32 v44, -v39, v43, 1.0
	v_fmac_f32_e32 v43, v44, v43
	v_mov_b32_e32 v39, v43
	v_mul_f32_e32 v38, v39, v38
	v_mul_f32_e32 v38, v56, v38
	v_mul_f32_e32 v38, v35, v38
	v_cvt_pk_bf16_f32 v38, v38, s0
	ds_write_b16 v26, v38 offset:368
	ds_read_u16 v38, v26 offset:400
	s_waitcnt lgkmcnt(0)
; DEV bf16_t f2bf(float f) { return (bf16_t)(cvt_pk_bf16(f, 0.f) & 0xffffu); }
; DEV float bf2f(unsigned h) { return __uint_as_float(h << 16); }
; DEV float sigmoidf_(float x) { return 1.0f / (1.0f + __expf(-x)); }
; DEV void ret_out_item(const Params& p, int l, int item, unsigned char* smem) {
;     ...
; #pragma unroll
;   for (int j = 0; j < 4; ++j) {
;     float v = ss[j];
;     v += __shfl_xor(v, 1); v += __shfl_xor(v, 2); v += __shfl_xor(v, 4); v += __shfl_xor(v, 8);
;     const float rstd = rsqrtf(v * (1.0f / 128.0f) + 1e-6f);
;     bf16_t* gp = Gs + (w * 16 + fq * 4 + j) * 136 + fr;
; #pragma unroll
;     for (int et = 0; et < 8; ++et) {
;       const float g = bf2f(gp[et * 16]);
;       gp[et * 16] = f2bf(g * sigmoidf_(g) * a1[et][j] * rstd);
;     }
;   }
	v_lshlrev_b32_e32 v38, 16, v38
	v_mul_f32_e32 v39, 0xbfb8aa3b, v38
	v_exp_f32_e32 v39, v39
	s_nop 0
	v_add_f32_e32 v39, 1.0, v39
	v_rcp_f32_e32 v43, v39
	s_nop 0
	v_fma_f32 v44, -v39, v43, 1.0
	v_fmac_f32_e32 v43, v44, v43
	v_mov_b32_e32 v39, v43
	v_mul_f32_e32 v38, v39, v38
	v_mul_f32_e32 v38, v49, v38
	v_mul_f32_e32 v38, v35, v38
	v_cvt_pk_bf16_f32 v38, v38, s0
	ds_write_b16 v26, v38 offset:400
	ds_read_u16 v38, v26 offset:432
	s_waitcnt lgkmcnt(0)
	v_lshlrev_b32_e32 v38, 16, v38
	v_mul_f32_e32 v39, 0xbfb8aa3b, v38
	v_exp_f32_e32 v39, v39
	s_nop 0
	v_add_f32_e32 v39, 1.0, v39
	v_rcp_f32_e32 v43, v39
	s_nop 0
	v_fma_f32 v44, -v39, v43, 1.0
	v_fmac_f32_e32 v43, v44, v43
	v_mov_b32_e32 v39, v43
	v_mul_f32_e32 v38, v39, v38
	v_mul_f32_e32 v38, v48, v38
	v_mul_f32_e32 v38, v35, v38
	v_cvt_pk_bf16_f32 v38, v38, s0
	ds_write_b16 v26, v38 offset:432
	ds_read_u16 v38, v26 offset:464
	s_waitcnt lgkmcnt(0)
	v_lshlrev_b32_e32 v38, 16, v38
	v_mul_f32_e32 v39, 0xbfb8aa3b, v38
	v_exp_f32_e32 v39, v39
	s_nop 0
	v_add_f32_e32 v39, 1.0, v39
	v_rcp_f32_e32 v43, v39
	s_nop 0
	v_fma_f32 v44, -v39, v43, 1.0
	v_fmac_f32_e32 v43, v44, v43
	v_mov_b32_e32 v39, v43
	v_mul_f32_e32 v38, v39, v38
	v_mul_f32_e32 v38, v41, v38
	v_mul_f32_e32 v38, v35, v38
	v_cvt_pk_bf16_f32 v38, v38, s0
	ds_write_b16 v26, v38 offset:464
	ds_read_u16 v38, v26 offset:496
	s_waitcnt lgkmcnt(0)
	v_lshlrev_b32_e32 v38, 16, v38
	v_mul_f32_e32 v39, 0xbfb8aa3b, v38
	v_exp_f32_e32 v39, v39
	s_nop 0
	v_add_f32_e32 v39, 1.0, v39
	v_rcp_f32_e32 v42, v39
	s_nop 0
	v_fma_f32 v43, -v39, v42, 1.0
	v_fmac_f32_e32 v42, v43, v42
	v_mov_b32_e32 v39, v42
	v_mul_f32_e32 v38, v39, v38
	v_mul_f32_e32 v38, v40, v38
	v_mul_f32_e32 v35, v35, v38
	v_cvt_pk_bf16_f32 v35, v35, s0
	ds_write_b16 v26, v35 offset:496
	ds_read_u16 v35, v26 offset:544
	ds_read_u16 v38, v26 offset:576
	s_waitcnt lgkmcnt(1)
	v_lshlrev_b32_e32 v35, 16, v35
	v_mul_f32_e32 v39, 0xbfb8aa3b, v35
	v_exp_f32_e32 v39, v39
	s_nop 0
	v_add_f32_e32 v39, 1.0, v39
	v_rcp_f32_e32 v41, v39
	s_nop 0
	v_fma_f32 v42, -v39, v41, 1.0
	v_fmac_f32_e32 v41, v42, v41
	v_mov_b32_e32 v39, v41
	v_mul_f32_e32 v35, v39, v35
	v_mul_f32_e32 v8, v8, v35
	s_waitcnt lgkmcnt(0)
	v_lshlrev_b32_e32 v35, 16, v38
	v_mul_f32_e32 v38, 0xbfb8aa3b, v35
	v_exp_f32_e32 v38, v38
	s_nop 0
	v_add_f32_e32 v38, 1.0, v38
	v_rcp_f32_e32 v40, v38
	s_nop 0
	v_fma_f32 v41, -v38, v40, 1.0
	v_fmac_f32_e32 v40, v41, v40
	v_mov_b32_e32 v38, v40
	v_mul_f32_e32 v35, v38, v35
	v_mul_f32_e32 v6, v6, v35
	ds_read_u16 v35, v26 offset:608
	s_waitcnt lgkmcnt(0)
	v_lshlrev_b32_e32 v35, 16, v35
	v_mul_f32_e32 v38, 0xbfb8aa3b, v35
	v_exp_f32_e32 v38, v38
	s_nop 0
	v_add_f32_e32 v38, 1.0, v38
	v_rcp_f32_e32 v40, v38
	s_nop 0
	v_fma_f32 v41, -v38, v40, 1.0
	v_fmac_f32_e32 v40, v41, v40
	v_mov_b32_e32 v38, v40
	v_mul_f32_e32 v35, v38, v35
	v_mul_f32_e32 v35, v37, v35
	ds_read_u16 v37, v26 offset:640
	s_waitcnt lgkmcnt(0)
	v_lshlrev_b32_e32 v37, 16, v37
	v_mul_f32_e32 v38, 0xbfb8aa3b, v37
	v_exp_f32_e32 v38, v38
	s_nop 0
	v_add_f32_e32 v38, 1.0, v38
	v_rcp_f32_e32 v40, v38
	s_nop 0
	v_fma_f32 v41, -v38, v40, 1.0
	v_fmac_f32_e32 v40, v41, v40
	v_mov_b32_e32 v38, v40
	v_mul_f32_e32 v37, v38, v37
	v_mul_f32_e32 v36, v36, v37
	ds_read_u16 v37, v26 offset:672
	s_waitcnt lgkmcnt(0)
	v_lshlrev_b32_e32 v37, 16, v37
	v_mul_f32_e32 v38, 0xbfb8aa3b, v37
	v_exp_f32_e32 v38, v38
	s_nop 0
	v_add_f32_e32 v38, 1.0, v38
	v_rcp_f32_e32 v40, v38
	s_nop 0
	v_fma_f32 v41, -v38, v40, 1.0
	v_fmac_f32_e32 v40, v41, v40
	v_mov_b32_e32 v38, v40
	v_mul_f32_e32 v37, v38, v37
	v_mul_f32_e32 v33, v33, v37
	ds_read_u16 v37, v26 offset:704
	s_waitcnt lgkmcnt(0)
	v_lshlrev_b32_e32 v37, 16, v37
	v_mul_f32_e32 v38, 0xbfb8aa3b, v37
	v_exp_f32_e32 v38, v38
	s_nop 0
	v_add_f32_e32 v38, 1.0, v38
	v_rcp_f32_e32 v40, v38
	s_nop 0
	v_fma_f32 v41, -v38, v40, 1.0
	v_fmac_f32_e32 v40, v41, v40
	v_mov_b32_e32 v38, v40
	v_mul_f32_e32 v37, v38, v37
	v_mul_f32_e32 v32, v32, v37
	ds_read_u16 v37, v26 offset:736
	s_waitcnt lgkmcnt(0)
	v_lshlrev_b32_e32 v37, 16, v37
	v_mul_f32_e32 v38, 0xbfb8aa3b, v37
	v_exp_f32_e32 v38, v38
	s_nop 0
	v_add_f32_e32 v38, 1.0, v38
	v_rcp_f32_e32 v40, v38
	s_nop 0
	v_fma_f32 v41, -v38, v40, 1.0
	v_fmac_f32_e32 v40, v41, v40
	v_mov_b32_e32 v38, v40
	v_mul_f32_e32 v37, v38, v37
	v_mul_f32_e32 v29, v29, v37
	ds_read_u16 v37, v26 offset:768
	s_waitcnt lgkmcnt(0)
	v_lshlrev_b32_e32 v37, 16, v37
	v_mul_f32_e32 v38, 0xbfb8aa3b, v37
	v_exp_f32_e32 v38, v38
	s_nop 0
	v_add_f32_e32 v38, 1.0, v38
	v_rcp_f32_e32 v40, v38
	s_nop 0
	v_fma_f32 v41, -v38, v40, 1.0
	v_fmac_f32_e32 v40, v41, v40
	v_mov_b32_e32 v38, v40
	v_mov_b32_e32 v39, v20
	v_mov_b32_e32 v20, v11
	v_mul_f32_e32 v37, v38, v37
	v_mov_b32_e32 v38, v10
	v_pk_add_f32 v[10:11], v[20:21], v[24:25] op_sel:[0,1] op_sel_hi:[1,0]
	v_mov_b32_e32 v20, v19
	v_pk_add_f32 v[10:11], v[38:39], v[10:11]
	v_mov_b32_e32 v21, v17
	v_pk_add_f32 v[10:11], v[20:21], v[10:11]
	v_mov_b32_e32 v19, v16
	v_pk_add_f32 v[10:11], v[18:19], v[10:11]
	v_mov_b32_e32 v16, v15
	v_mov_b32_e32 v17, v13
	v_pk_add_f32 v[10:11], v[16:17], v[10:11]
	v_mov_b32_e32 v15, v12
	v_pk_add_f32 v[10:11], v[14:15], v[10:11]
	ds_bpermute_b32 v13, v34, v11
	ds_bpermute_b32 v12, v34, v10
	v_mul_f32_e32 v28, v28, v37
	s_waitcnt lgkmcnt(0)
	v_pk_add_f32 v[10:11], v[10:11], v[12:13]
	ds_bpermute_b32 v13, v31, v11
	ds_bpermute_b32 v12, v31, v10
	s_waitcnt lgkmcnt(0)
	v_pk_add_f32 v[10:11], v[10:11], v[12:13]
	ds_bpermute_b32 v13, v30, v11
	ds_bpermute_b32 v12, v30, v10
	s_waitcnt lgkmcnt(0)
	v_pk_add_f32 v[10:11], v[10:11], v[12:13]
	ds_bpermute_b32 v13, v27, v11
	ds_bpermute_b32 v12, v27, v10
	s_waitcnt lgkmcnt(0)
; DEV bf16_t f2bf(float f) { return (bf16_t)(cvt_pk_bf16(f, 0.f) & 0xffffu); }
; DEV float bf2f(unsigned h) { return __uint_as_float(h << 16); }
; DEV float sigmoidf_(float x) { return 1.0f / (1.0f + __expf(-x)); }
; DEV void ret_out_item(const Params& p, int l, int item, unsigned char* smem) {
;     ...
; #pragma unroll
;   for (int j = 0; j < 4; ++j) {
;     float v = ss[j];
;     v += __shfl_xor(v, 1); v += __shfl_xor(v, 2); v += __shfl_xor(v, 4); v += __shfl_xor(v, 8);
;     const float rstd = rsqrtf(v * (1.0f / 128.0f) + 1e-6f);
;     bf16_t* gp = Gs + (w * 16 + fq * 4 + j) * 136 + fr;
; #pragma unroll
;     for (int et = 0; et < 8; ++et) {
;       const float g = bf2f(gp[et * 16]);
;       gp[et * 16] = f2bf(g * sigmoidf_(g) * a1[et][j] * rstd);
;     }
;   }
;   asm volatile("s_waitcnt lgkmcnt(0)" ::: "memory");
; #pragma unroll
;   for (int i = 0; i < 4; ++i) {
;     const int c = lane + i * 64, r = c >> 4, kc = c & 15;
;     const u32x4 v = *(const u32x4*)(Gs + (w * 16 + r) * 136 + kc * 8);
;     *(u32x4*)(Z + (rowbase + w * 16 + r) * NIN + RG + h * 128 + kc * 8) = v;
;   }
;   __syncthreads();
	v_pk_add_f32 v[10:11], v[10:11], v[12:13]
	s_nop 0
	v_pk_fma_f32 v[10:11], v[10:11], s[4:5], v[22:23] op_sel_hi:[1,0,0]
	s_nop 0
	v_mul_f32_e32 v12, 0x4b800000, v11
	v_cmp_gt_f32_e64 s[0:1], s2, v11
	v_cmp_gt_f32_e32 vcc, s2, v10
	s_nop 0
	v_cndmask_b32_e64 v11, v11, v12, s[0:1]
	v_rsq_f32_e32 v11, v11
	s_nop 0
	v_mul_f32_e32 v12, 0x45800000, v11
	v_cndmask_b32_e64 v11, v11, v12, s[0:1]
	v_mul_f32_e32 v6, v11, v6
	v_cvt_pk_bf16_f32 v6, v6, s0
	ds_write_b16 v26, v6 offset:576
	v_mul_f32_e32 v6, v11, v35
	v_cvt_pk_bf16_f32 v6, v6, s0
	ds_write_b16 v26, v6 offset:608
	v_mul_f32_e32 v6, v11, v36
	v_cvt_pk_bf16_f32 v6, v6, s0
	ds_write_b16 v26, v6 offset:640
	v_mul_f32_e32 v6, v11, v33
	v_cvt_pk_bf16_f32 v6, v6, s0
	ds_write_b16 v26, v6 offset:672
	v_mul_f32_e32 v6, v11, v32
	v_cvt_pk_bf16_f32 v6, v6, s0
	ds_write_b16 v26, v6 offset:704
	v_mul_f32_e32 v6, v11, v29
	v_cvt_pk_bf16_f32 v6, v6, s0
	ds_write_b16 v26, v6 offset:736
	v_mul_f32_e32 v6, v11, v28
	v_cvt_pk_bf16_f32 v6, v6, s0
	ds_write_b16 v26, v6 offset:768
	v_mul_f32_e32 v6, 0x4b800000, v10
	v_cndmask_b32_e32 v6, v10, v6, vcc
	v_rsq_f32_e32 v6, v6
	v_mul_f32_e32 v8, v11, v8
	v_cvt_pk_bf16_f32 v8, v8, s0
	ds_write_b16 v26, v8 offset:544
	v_mul_f32_e32 v8, 0x45800000, v6
	v_cndmask_b32_e32 v6, v6, v8, vcc
	ds_read_u16 v8, v26 offset:816
	s_waitcnt lgkmcnt(0)
	v_lshlrev_b32_e32 v8, 16, v8
	v_mul_f32_e32 v10, 0xbfb8aa3b, v8
	v_exp_f32_e32 v10, v10
	s_nop 0
	v_add_f32_e32 v10, 1.0, v10
	v_rcp_f32_e32 v12, v10
	s_nop 0
	v_fma_f32 v13, -v10, v12, 1.0
	v_fmac_f32_e32 v12, v13, v12
	v_mov_b32_e32 v10, v12
	v_mul_f32_e32 v8, v10, v8
	v_mul_f32_e32 v8, v9, v8
	v_mul_f32_e32 v8, v6, v8
	v_cvt_pk_bf16_f32 v8, v8, s0
	ds_write_b16 v26, v8 offset:816
	ds_read_u16 v8, v26 offset:848
	s_waitcnt lgkmcnt(0)
	v_lshlrev_b32_e32 v8, 16, v8
	v_mul_f32_e32 v9, 0xbfb8aa3b, v8
	v_exp_f32_e32 v9, v9
	s_nop 0
	v_add_f32_e32 v9, 1.0, v9
	v_rcp_f32_e32 v11, v9
	s_nop 0
	v_fma_f32 v12, -v9, v11, 1.0
	v_fmac_f32_e32 v11, v12, v11
	v_mov_b32_e32 v9, v11
	v_mul_f32_e32 v8, v9, v8
	v_mul_f32_e32 v7, v7, v8
	v_mul_f32_e32 v7, v6, v7
	v_cvt_pk_bf16_f32 v7, v7, s0
	ds_write_b16 v26, v7 offset:848
	ds_read_u16 v7, v26 offset:880
	s_waitcnt lgkmcnt(0)
	v_lshlrev_b32_e32 v7, 16, v7
	v_mul_f32_e32 v8, 0xbfb8aa3b, v7
	v_exp_f32_e32 v8, v8
	s_nop 0
	v_add_f32_e32 v8, 1.0, v8
	v_rcp_f32_e32 v10, v8
	s_nop 0
	v_fma_f32 v11, -v8, v10, 1.0
	v_fmac_f32_e32 v10, v11, v10
	v_mov_b32_e32 v8, v10
	v_mul_f32_e32 v7, v8, v7
	v_mul_f32_e32 v5, v5, v7
	v_mul_f32_e32 v5, v6, v5
	v_cvt_pk_bf16_f32 v5, v5, s0
	ds_write_b16 v26, v5 offset:880
	ds_read_u16 v5, v26 offset:912
	s_waitcnt lgkmcnt(0)
	v_lshlrev_b32_e32 v5, 16, v5
	v_mul_f32_e32 v7, 0xbfb8aa3b, v5
	v_exp_f32_e32 v7, v7
	s_nop 0
	v_add_f32_e32 v7, 1.0, v7
	v_rcp_f32_e32 v9, v7
	s_nop 0
	v_fma_f32 v10, -v7, v9, 1.0
	v_fmac_f32_e32 v9, v10, v9
	v_mov_b32_e32 v7, v9
	v_mul_f32_e32 v5, v7, v5
	v_mul_f32_e32 v4, v4, v5
	v_mul_f32_e32 v4, v6, v4
	v_cvt_pk_bf16_f32 v4, v4, s0
	ds_write_b16 v26, v4 offset:912
	ds_read_u16 v4, v26 offset:944
	s_waitcnt lgkmcnt(0)
	v_lshlrev_b32_e32 v4, 16, v4
	v_mul_f32_e32 v5, 0xbfb8aa3b, v4
	v_exp_f32_e32 v5, v5
	s_nop 0
	v_add_f32_e32 v5, 1.0, v5
	v_rcp_f32_e32 v8, v5
	s_nop 0
	v_fma_f32 v9, -v5, v8, 1.0
	v_fmac_f32_e32 v8, v9, v8
	v_mov_b32_e32 v5, v8
	v_mul_f32_e32 v4, v5, v4
	v_mul_f32_e32 v3, v3, v4
	v_mul_f32_e32 v3, v6, v3
	v_cvt_pk_bf16_f32 v3, v3, s0
	ds_write_b16 v26, v3 offset:944
	ds_read_u16 v3, v26 offset:976
	s_waitcnt lgkmcnt(0)
	v_lshlrev_b32_e32 v3, 16, v3
	v_mul_f32_e32 v4, 0xbfb8aa3b, v3
	v_exp_f32_e32 v4, v4
	s_nop 0
	v_add_f32_e32 v4, 1.0, v4
	v_rcp_f32_e32 v7, v4
	s_nop 0
	v_fma_f32 v8, -v4, v7, 1.0
	v_fmac_f32_e32 v7, v8, v7
	v_mov_b32_e32 v4, v7
	v_mul_f32_e32 v3, v4, v3
	v_mul_f32_e32 v2, v2, v3
	v_mul_f32_e32 v2, v6, v2
	v_cvt_pk_bf16_f32 v2, v2, s0
	ds_write_b16 v26, v2 offset:976
	ds_read_u16 v2, v26 offset:1008
	s_waitcnt lgkmcnt(0)
	v_lshlrev_b32_e32 v2, 16, v2
	v_mul_f32_e32 v3, 0xbfb8aa3b, v2
	v_exp_f32_e32 v3, v3
	s_nop 0
	v_add_f32_e32 v3, 1.0, v3
	v_rcp_f32_e32 v5, v3
	s_nop 0
	v_fma_f32 v7, -v3, v5, 1.0
	v_fmac_f32_e32 v5, v7, v5
	v_mov_b32_e32 v3, v5
	v_mul_f32_e32 v2, v3, v2
	v_mul_f32_e32 v1, v1, v2
	v_mul_f32_e32 v1, v6, v1
	v_cvt_pk_bf16_f32 v1, v1, s0
	ds_write_b16 v26, v1 offset:1008
	ds_read_u16 v1, v26 offset:1040
	s_waitcnt lgkmcnt(0)
	v_lshlrev_b32_e32 v1, 16, v1
	v_mul_f32_e32 v2, 0xbfb8aa3b, v1
	v_exp_f32_e32 v2, v2
	s_nop 0
	v_add_f32_e32 v2, 1.0, v2
	v_rcp_f32_e32 v4, v2
	s_nop 0
	v_fma_f32 v5, -v2, v4, 1.0
	v_fmac_f32_e32 v4, v5, v4
	v_mov_b32_e32 v2, v4
	v_mul_f32_e32 v1, v2, v1
	v_mul_f32_e32 v0, v0, v1
	v_mul_f32_e32 v0, v6, v0
	v_cvt_pk_bf16_f32 v0, v0, s0
	ds_write_b16 v26, v0 offset:1040
	v_or_b32_e32 v0, v79, v80
	s_waitcnt lgkmcnt(0)
	v_lshl_add_u64 v[4:5], s[38:39], 0, v[80:81]
	v_mad_u64_u32 v[0:1], s[0:1], v0, s13, v[78:79]
	ds_read_b128 v[0:3], v0
	v_or_b32_e32 v8, v4, v79
	v_mov_b64_e32 v[6:7], s[30:31]
	v_mul_lo_u32 v10, v5, s95
	v_mad_u64_u32 v[8:9], s[0:1], v8, s95, v[6:7]
	v_add_u32_e32 v9, v10, v9
	v_lshl_add_u64 v[8:9], v[8:9], 0, s[6:7]
	v_lshl_add_u64 v[8:9], v[8:9], 0, v[76:77]
	v_or_b32_e32 v5, 4, v79
	s_waitcnt lgkmcnt(0)
	global_store_dwordx4 v[8:9], v[0:3], off offset:2048
	s_nop 1
	v_or_b32_e32 v0, v5, v80
	v_mad_u64_u32 v[0:1], s[0:1], v0, s13, v[78:79]
	ds_read_b128 v[0:3], v0
	v_or_b32_e32 v5, v4, v5
	v_mad_u64_u32 v[8:9], s[0:1], v5, s95, v[6:7]
	v_add_u32_e32 v9, v10, v9
	v_lshl_add_u64 v[8:9], v[8:9], 0, s[6:7]
	v_lshl_add_u64 v[8:9], v[8:9], 0, v[76:77]
	v_or_b32_e32 v5, 8, v79
	s_waitcnt lgkmcnt(0)
	global_store_dwordx4 v[8:9], v[0:3], off offset:2048
	s_nop 1
	v_or_b32_e32 v0, v5, v80
	v_mad_u64_u32 v[0:1], s[0:1], v0, s13, v[78:79]
	ds_read_b128 v[0:3], v0
	v_or_b32_e32 v5, v4, v5
	v_mad_u64_u32 v[8:9], s[0:1], v5, s95, v[6:7]
	v_add_u32_e32 v9, v10, v9
	v_lshl_add_u64 v[8:9], v[8:9], 0, s[6:7]
	v_lshl_add_u64 v[8:9], v[8:9], 0, v[76:77]
	v_or_b32_e32 v5, 12, v79
	s_waitcnt lgkmcnt(0)
	global_store_dwordx4 v[8:9], v[0:3], off offset:2048
	v_or_b32_e32 v4, v4, v5
	s_nop 0
	v_or_b32_e32 v0, v5, v80
	v_mad_u64_u32 v[0:1], s[0:1], v0, s13, v[78:79]
	ds_read_b128 v[0:3], v0
	v_mad_u64_u32 v[4:5], s[0:1], v4, s95, v[6:7]
	v_readlane_b32 s0, v248, 37
	v_add_u32_e32 v5, v10, v5
	v_readlane_b32 s2, v248, 39
	v_lshl_add_u64 v[4:5], v[4:5], 0, s[6:7]
	s_add_i32 s18, s18, s2
	v_lshl_add_u64 v[4:5], v[4:5], 0, v[76:77]
	s_cmpk_gt_i32 s18, 0x1ff
	s_waitcnt lgkmcnt(0)
	global_store_dwordx4 v[4:5], v[0:3], off offset:2048
	s_barrier
	v_readlane_b32 s1, v248, 38
	v_readlane_b32 s3, v248, 40
	s_cbranch_scc1 .LBB0_93

; DEV float bflo(unsigned w) { return __uint_as_float(w << 16); }
; DEV float bfhi(unsigned w) { return __uint_as_float(w & 0xffff0000u); }
; DEV float sigmoidf_(float x) { return 1.0f / (1.0f + __expf(-x)); }
;   DEV void operator()(const f32x4 (&acc)[2][2][4][2], const Unit& u, int wr, int wc, int fr, int fq) const {
;     ...
;               const size_t o = (size_t)(row0 + ai * HALF + (mp * 2 + mm) * 16) * D + col0 + bj * HALF + n * 16;
;               pw[mm][bj][n] = *(const u32x2*)(PROJ + o);
;               xv[mm][bj][n] = *(const f32x4*)(X + o);
;             }
; #pragma unroll
;         for (int mm = 0; mm < 2; ++mm)
; #pragma unroll
;           for (int bj = 0; bj < 2; ++bj)
; #pragma unroll
;             for (int n = 0; n < 2; ++n) {
;               const size_t o = (size_t)(row0 + ai * HALF + (mp * 2 + mm) * 16) * D + col0 + bj * HALF + n * 16;
;               const f32x4 v = acc[ai][bj][mp * 2 + mm][n];
;               f32x4 x = xv[mm][bj][n]; const u32x2 w = pw[mm][bj][n];
;               x[0] += sigmoidf_(v[0]) * bflo(w.x); x[1] += sigmoidf_(v[1]) * bfhi(w.x); x[2] += sigmoidf_(v[2]) * bflo(w.y); x[3] += sigmoidf_(v[3]) * bfhi(w.y);
;               *(f32x4*)(X + o) = x;
;             }
.LBB0_133:
	v_lshl_add_u32 v180, s27, 8, v177
	v_lshl_or_b32 v166, s42, 8, v218
	v_ashrrev_i32_e32 v181, 31, v180
	v_ashrrev_i32_e32 v167, 31, v166
	v_lshlrev_b64 v[108:109], 10, v[180:181]
	v_lshl_add_u64 v[108:109], v[108:109], 0, v[166:167]
	v_lshlrev_b64 v[110:111], 1, v[108:109]
	v_lshl_add_u64 v[120:121], s[40:41], 0, v[110:111]
	global_load_dwordx2 v[198:199], v[120:121], off
	v_lshl_add_u64 v[108:109], v[108:109], 2, s[22:23]
	global_load_dwordx4 v[156:159], v[108:109], off
	v_mul_f32_e32 v144, 0xbfb8aa3b, v144
	v_mul_f32_e32 v145, 0xbfb8aa3b, v145
	v_exp_f32_e32 v144, v144
	v_exp_f32_e32 v145, v145
	v_lshlrev_b64 v[220:221], 12, v[180:181]
	v_or_b32_e32 v120, 32, v110
	v_mov_b32_e32 v121, v111
	v_pk_add_f32 v[144:145], v[144:145], 1.0 op_sel_hi:[1,0]
	v_lshl_add_u64 v[120:121], s[40:41], 0, v[120:121]
	v_rcp_f32_e32 v222, v145
	global_load_dwordx2 v[196:197], v[120:121], off
	global_load_dwordx4 v[152:155], v[108:109], off offset:64
	v_or_b32_e32 v120, 0x100, v110
	v_mov_b32_e32 v121, v111
	v_fma_f32 v223, -v145, v222, 1.0
	v_fmac_f32_e32 v222, v223, v222
	v_mov_b32_e32 v145, v222
	v_rcp_f32_e32 v222, v144
	v_or_b32_e32 v110, 0x120, v110
	v_or_b32_e32 v192, 16, v180
	v_lshl_add_u64 v[120:121], s[40:41], 0, v[120:121]
	v_fma_f32 v223, -v144, v222, 1.0
	v_fmac_f32_e32 v222, v223, v222
	v_mov_b32_e32 v144, v222
	v_lshl_add_u64 v[110:111], s[40:41], 0, v[110:111]
	v_ashrrev_i32_e32 v193, 31, v192
	global_load_dwordx2 v[194:195], v[120:121], off
	global_load_dwordx4 v[148:151], v[108:109], off offset:512
	global_load_dwordx2 v[190:191], v[110:111], off
	global_load_dwordx4 v[140:143], v[108:109], off offset:576
	v_lshlrev_b64 v[108:109], 10, v[192:193]
	v_lshl_add_u64 v[108:109], v[108:109], 0, v[166:167]
	v_lshlrev_b64 v[110:111], 1, v[108:109]
	v_mul_f32_e32 v136, 0xbfb8aa3b, v136
	v_mul_f32_e32 v137, 0xbfb8aa3b, v137
	v_lshl_add_u64 v[120:121], s[40:41], 0, v[110:111]
	v_exp_f32_e32 v136, v136
	v_exp_f32_e32 v137, v137
	global_load_dwordx2 v[188:189], v[120:121], off
	v_or_b32_e32 v120, 32, v110
	v_mov_b32_e32 v121, v111
	v_lshl_add_u64 v[108:109], v[108:109], 2, s[22:23]
	v_lshl_add_u64 v[120:121], s[40:41], 0, v[120:121]
	global_load_dwordx4 v[132:135], v[108:109], off
	global_load_dwordx2 v[186:187], v[120:121], off
	global_load_dwordx4 v[128:131], v[108:109], off offset:64
	v_or_b32_e32 v120, 0x100, v110
	v_mov_b32_e32 v121, v111
	v_or_b32_e32 v110, 0x120, v110
	v_lshl_add_u64 v[120:121], s[40:41], 0, v[120:121]
	v_lshl_add_u64 v[110:111], s[40:41], 0, v[110:111]
	v_pk_add_f32 v[136:137], v[136:137], 1.0 op_sel_hi:[1,0]
	global_load_dwordx2 v[184:185], v[120:121], off
	s_nop 0
	global_load_dwordx4 v[120:123], v[108:109], off offset:512
	global_load_dwordx2 v[182:183], v[110:111], off
	s_nop 0
	global_load_dwordx4 v[108:111], v[108:109], off offset:576
	v_mul_f32_e32 v138, 0xbfb8aa3b, v138
	v_mul_f32_e32 v139, 0xbfb8aa3b, v139
	v_exp_f32_e32 v138, v138
	v_exp_f32_e32 v139, v139
	v_mul_f32_e32 v124, 0xbfb8aa3b, v124
	v_mul_f32_e32 v125, 0xbfb8aa3b, v125
	v_exp_f32_e32 v124, v124
	v_pk_add_f32 v[138:139], v[138:139], 1.0 op_sel_hi:[1,0]
	v_exp_f32_e32 v125, v125
	s_waitcnt vmcnt(0)
	v_lshlrev_b32_e32 v222, 16, v198
	v_and_b32_e32 v223, 0xffff0000, v198
	v_pk_fma_f32 v[156:157], v[144:145], v[222:223], v[156:157]
	v_mul_f32_e32 v144, 0xbfb8aa3b, v146
	v_mul_f32_e32 v145, 0xbfb8aa3b, v147
	v_exp_f32_e32 v144, v144
	v_exp_f32_e32 v145, v145
	v_pk_add_f32 v[124:125], v[124:125], 1.0 op_sel_hi:[1,0]
	v_mul_f32_e32 v126, 0xbfb8aa3b, v126
	v_mul_f32_e32 v127, 0xbfb8aa3b, v127
	v_pk_add_f32 v[144:145], v[144:145], 1.0 op_sel_hi:[1,0]
	v_exp_f32_e32 v126, v126
	v_rcp_f32_e32 v147, v145
	v_exp_f32_e32 v127, v127
	v_mul_f32_e32 v116, 0xbfb8aa3b, v116
	v_mul_f32_e32 v117, 0xbfb8aa3b, v117
	v_fma_f32 v181, -v145, v147, 1.0
	v_fmac_f32_e32 v147, v181, v147
	v_mov_b32_e32 v145, v147
	v_rcp_f32_e32 v147, v144
	v_pk_add_f32 v[126:127], v[126:127], 1.0 op_sel_hi:[1,0]
	v_exp_f32_e32 v116, v116
	v_exp_f32_e32 v117, v117
	v_fma_f32 v181, -v144, v147, 1.0
	v_fmac_f32_e32 v147, v181, v147
	v_mov_b32_e32 v144, v147
	v_lshlrev_b32_e32 v146, 16, v199
	v_and_b32_e32 v147, 0xffff0000, v199
	v_pk_fma_f32 v[158:159], v[144:145], v[146:147], v[158:159]
	v_lshl_add_u64 v[146:147], s[22:23], 0, v[220:221]
	v_lshlrev_b64 v[144:145], 2, v[166:167]
	v_lshl_add_u64 v[146:147], v[146:147], 0, v[144:145]
	global_store_dwordx4 v[146:147], v[156:159], off
	v_pk_add_f32 v[116:117], v[116:117], 1.0 op_sel_hi:[1,0]
	v_mul_f32_e32 v118, 0xbfb8aa3b, v118
	v_rcp_f32_e32 v157, v137
	v_mul_f32_e32 v119, 0xbfb8aa3b, v119
	v_exp_f32_e32 v118, v118
	v_exp_f32_e32 v119, v119
	v_fma_f32 v158, -v137, v157, 1.0
	v_fmac_f32_e32 v157, v158, v157
	v_mov_b32_e32 v137, v157
	v_rcp_f32_e32 v157, v136
	v_pk_add_f32 v[118:119], v[118:119], 1.0 op_sel_hi:[1,0]
	v_mul_f32_e32 v112, 0xbfb8aa3b, v112
	v_mul_f32_e32 v113, 0xbfb8aa3b, v113
	v_fma_f32 v158, -v136, v157, 1.0
	v_fmac_f32_e32 v157, v158, v157
	v_mov_b32_e32 v136, v157
	v_lshlrev_b32_e32 v156, 16, v196
	v_and_b32_e32 v157, 0xffff0000, v196
	v_pk_fma_f32 v[136:137], v[136:137], v[156:157], v[152:153]
	v_rcp_f32_e32 v153, v139
	v_exp_f32_e32 v112, v112
	v_exp_f32_e32 v113, v113
	v_mul_f32_e32 v104, 0xbfb8aa3b, v104
	v_fma_f32 v156, -v139, v153, 1.0
	v_fmac_f32_e32 v153, v156, v153
	v_mov_b32_e32 v139, v153
	v_rcp_f32_e32 v153, v138
	v_pk_add_f32 v[112:113], v[112:113], 1.0 op_sel_hi:[1,0]
	v_mul_f32_e32 v105, 0xbfb8aa3b, v105
	v_exp_f32_e32 v104, v104
	v_fma_f32 v156, -v138, v153, 1.0
	v_fmac_f32_e32 v153, v156, v153
	v_mov_b32_e32 v138, v153
	v_lshlrev_b32_e32 v152, 16, v197
	v_and_b32_e32 v153, 0xffff0000, v197
; DEV float bflo(unsigned w) { return __uint_as_float(w << 16); }
; DEV float bfhi(unsigned w) { return __uint_as_float(w & 0xffff0000u); }
; DEV float sigmoidf_(float x) { return 1.0f / (1.0f + __expf(-x)); }
;   DEV void operator()(const f32x4 (&acc)[2][2][4][2], const Unit& u, int wr, int wc, int fr, int fq) const {
;     ...
;               const size_t o = (size_t)(row0 + ai * HALF + (mp * 2 + mm) * 16) * D + col0 + bj * HALF + n * 16;
;               pw[mm][bj][n] = *(const u32x2*)(PROJ + o);
;               xv[mm][bj][n] = *(const f32x4*)(X + o);
;             }
; #pragma unroll
;         for (int mm = 0; mm < 2; ++mm)
; #pragma unroll
;           for (int bj = 0; bj < 2; ++bj)
; #pragma unroll
;             for (int n = 0; n < 2; ++n) {
;               const size_t o = (size_t)(row0 + ai * HALF + (mp * 2 + mm) * 16) * D + col0 + bj * HALF + n * 16;
;               const f32x4 v = acc[ai][bj][mp * 2 + mm][n];
;               f32x4 x = xv[mm][bj][n]; const u32x2 w = pw[mm][bj][n];
;               x[0] += sigmoidf_(v[0]) * bflo(w.x); x[1] += sigmoidf_(v[1]) * bfhi(w.x); x[2] += sigmoidf_(v[2]) * bflo(w.y); x[3] += sigmoidf_(v[3]) * bfhi(w.y);
;               *(f32x4*)(X + o) = x;
;             }
	v_pk_fma_f32 v[138:139], v[138:139], v[152:153], v[154:155]
	global_store_dwordx4 v[146:147], v[136:139], off offset:64
	v_exp_f32_e32 v105, v105
	v_mul_f32_e32 v106, 0xbfb8aa3b, v106
	v_rcp_f32_e32 v137, v125
	v_pk_add_f32 v[104:105], v[104:105], 1.0 op_sel_hi:[1,0]
	v_mul_f32_e32 v107, 0xbfb8aa3b, v107
	v_exp_f32_e32 v106, v106
	v_fma_f32 v138, -v125, v137, 1.0
	v_fmac_f32_e32 v137, v138, v137
	v_mov_b32_e32 v125, v137
	v_rcp_f32_e32 v137, v124
	v_exp_f32_e32 v107, v107
	v_mul_f32_e32 v100, 0xbfb8aa3b, v100
	v_mul_f32_e32 v101, 0xbfb8aa3b, v101
	v_fma_f32 v138, -v124, v137, 1.0
	v_fmac_f32_e32 v137, v138, v137
	v_mov_b32_e32 v124, v137
	v_lshlrev_b32_e32 v136, 16, v194
	v_and_b32_e32 v137, 0xffff0000, v194
	v_pk_fma_f32 v[124:125], v[124:125], v[136:137], v[148:149]
	v_rcp_f32_e32 v137, v127
	v_pk_add_f32 v[106:107], v[106:107], 1.0 op_sel_hi:[1,0]
	v_exp_f32_e32 v100, v100
	v_exp_f32_e32 v101, v101
	v_fma_f32 v138, -v127, v137, 1.0
	v_fmac_f32_e32 v137, v138, v137
	v_mov_b32_e32 v127, v137
	v_rcp_f32_e32 v137, v126
	v_pk_add_f32 v[100:101], v[100:101], 1.0 op_sel_hi:[1,0]
	v_mul_f32_e32 v102, 0xbfb8aa3b, v102
	v_mul_f32_e32 v103, 0xbfb8aa3b, v103
	v_fma_f32 v138, -v126, v137, 1.0
	v_fmac_f32_e32 v137, v138, v137
	v_mov_b32_e32 v126, v137
	v_lshlrev_b32_e32 v136, 16, v195
	v_and_b32_e32 v137, 0xffff0000, v195
	v_pk_fma_f32 v[126:127], v[126:127], v[136:137], v[150:151]
	global_store_dwordx4 v[146:147], v[124:127], off offset:512
	v_exp_f32_e32 v102, v102
	v_exp_f32_e32 v103, v103
	v_rcp_f32_e32 v125, v117
	v_pk_add_f32 v[102:103], v[102:103], 1.0 op_sel_hi:[1,0]
	v_mul_f32_e32 v96, 0xbfb8aa3b, v96
	v_mul_f32_e32 v97, 0xbfb8aa3b, v97
	v_fma_f32 v126, -v117, v125, 1.0
	v_fmac_f32_e32 v125, v126, v125
	v_mov_b32_e32 v117, v125
	v_rcp_f32_e32 v125, v116
	v_exp_f32_e32 v96, v96
	v_exp_f32_e32 v97, v97
	v_mul_f32_e32 v98, 0xbfb8aa3b, v98
	v_fma_f32 v126, -v116, v125, 1.0
	v_fmac_f32_e32 v125, v126, v125
	v_mov_b32_e32 v116, v125
	v_lshlrev_b32_e32 v124, 16, v190
	v_and_b32_e32 v125, 0xffff0000, v190
	v_pk_fma_f32 v[116:117], v[116:117], v[124:125], v[140:141]
	v_rcp_f32_e32 v125, v119
	v_pk_add_f32 v[96:97], v[96:97], 1.0 op_sel_hi:[1,0]
	v_mul_f32_e32 v99, 0xbfb8aa3b, v99
	v_exp_f32_e32 v98, v98
	v_fma_f32 v126, -v119, v125, 1.0
	v_fmac_f32_e32 v125, v126, v125
	v_mov_b32_e32 v119, v125
	v_rcp_f32_e32 v125, v118
	v_exp_f32_e32 v99, v99
	v_or_b32_e32 v148, 32, v180
	v_ashrrev_i32_e32 v149, 31, v148
	v_fma_f32 v126, -v118, v125, 1.0
	v_fmac_f32_e32 v125, v126, v125
	v_mov_b32_e32 v118, v125
	v_lshlrev_b32_e32 v124, 16, v191
	v_and_b32_e32 v125, 0xffff0000, v191
	v_pk_fma_f32 v[118:119], v[118:119], v[124:125], v[142:143]
	global_store_dwordx4 v[146:147], v[116:119], off offset:576
	v_lshlrev_b64 v[124:125], 12, v[192:193]
	v_pk_add_f32 v[98:99], v[98:99], 1.0 op_sel_hi:[1,0]
	v_rcp_f32_e32 v117, v113
	v_mul_f32_e32 v92, 0xbfb8aa3b, v92
	v_mul_f32_e32 v93, 0xbfb8aa3b, v93
	v_exp_f32_e32 v92, v92
	v_fma_f32 v118, -v113, v117, 1.0
	v_fmac_f32_e32 v117, v118, v117
	v_mov_b32_e32 v113, v117
	v_rcp_f32_e32 v117, v112
	v_exp_f32_e32 v93, v93
	v_mul_f32_e32 v88, 0xbfb8aa3b, v88
	v_mul_f32_e32 v89, 0xbfb8aa3b, v89
	v_fma_f32 v118, -v112, v117, 1.0
	v_fmac_f32_e32 v117, v118, v117
	v_mov_b32_e32 v112, v117
	v_lshlrev_b32_e32 v116, 16, v188
	v_and_b32_e32 v117, 0xffff0000, v188
	v_pk_fma_f32 v[116:117], v[112:113], v[116:117], v[132:133]
	v_mul_f32_e32 v112, 0xbfb8aa3b, v114
	v_mul_f32_e32 v113, 0xbfb8aa3b, v115
	v_exp_f32_e32 v112, v112
	v_exp_f32_e32 v113, v113
	v_pk_add_f32 v[92:93], v[92:93], 1.0 op_sel_hi:[1,0]
	v_or_b32_e32 v138, 48, v180
	v_pk_add_f32 v[112:113], v[112:113], 1.0 op_sel_hi:[1,0]
	v_rcp_f32_e32 v151, v93
	v_rcp_f32_e32 v115, v113
	v_fma_f32 v152, -v93, v151, 1.0
	v_fmac_f32_e32 v151, v152, v151
	v_exp_f32_e32 v88, v88
	v_fma_f32 v118, -v113, v115, 1.0
	v_fmac_f32_e32 v115, v118, v115
	v_mov_b32_e32 v113, v115
	v_rcp_f32_e32 v115, v112
	v_exp_f32_e32 v89, v89
	v_ashrrev_i32_e32 v139, 31, v138
	v_mul_f32_e32 v90, 0xbfb8aa3b, v90
	v_fma_f32 v118, -v112, v115, 1.0
	v_fmac_f32_e32 v115, v118, v115
	v_mov_b32_e32 v112, v115
	v_lshlrev_b32_e32 v114, 16, v189
	v_and_b32_e32 v115, 0xffff0000, v189
	v_pk_fma_f32 v[118:119], v[112:113], v[114:115], v[134:135]
	v_rcp_f32_e32 v115, v105
	v_lshl_add_u64 v[112:113], s[22:23], 0, v[124:125]
	v_lshl_add_u64 v[112:113], v[112:113], 0, v[144:145]
	global_store_dwordx4 v[112:113], v[116:119], off
	v_pk_add_f32 v[88:89], v[88:89], 1.0 op_sel_hi:[1,0]
	v_mul_f32_e32 v91, 0xbfb8aa3b, v91
	v_fma_f32 v116, -v105, v115, 1.0
	v_fmac_f32_e32 v115, v116, v115
	v_mov_b32_e32 v105, v115
	v_rcp_f32_e32 v115, v104
	v_exp_f32_e32 v90, v90
	v_exp_f32_e32 v91, v91
	v_mul_f32_e32 v84, 0xbfb8aa3b, v84
	v_fma_f32 v116, -v104, v115, 1.0
	v_fmac_f32_e32 v115, v116, v115
	v_mov_b32_e32 v104, v115
	v_lshlrev_b32_e32 v114, 16, v186
	v_and_b32_e32 v115, 0xffff0000, v186
	v_pk_fma_f32 v[104:105], v[104:105], v[114:115], v[128:129]
	v_rcp_f32_e32 v115, v107
	v_pk_add_f32 v[90:91], v[90:91], 1.0 op_sel_hi:[1,0]
	v_mul_f32_e32 v85, 0xbfb8aa3b, v85
	v_exp_f32_e32 v84, v84
	v_fma_f32 v116, -v107, v115, 1.0
	v_fmac_f32_e32 v115, v116, v115
	v_mov_b32_e32 v107, v115
	v_rcp_f32_e32 v115, v106
	v_exp_f32_e32 v85, v85
	v_mul_f32_e32 v86, 0xbfb8aa3b, v86
	v_mul_f32_e32 v87, 0xbfb8aa3b, v87
	v_fma_f32 v116, -v106, v115, 1.0
	v_fmac_f32_e32 v115, v116, v115
	v_mov_b32_e32 v106, v115
	v_lshlrev_b32_e32 v114, 16, v187
	v_and_b32_e32 v115, 0xffff0000, v187
	v_pk_fma_f32 v[106:107], v[106:107], v[114:115], v[130:131]
	global_store_dwordx4 v[112:113], v[104:107], off offset:64
	v_pk_add_f32 v[84:85], v[84:85], 1.0 op_sel_hi:[1,0]
; DEV float bflo(unsigned w) { return __uint_as_float(w << 16); }
; DEV float bfhi(unsigned w) { return __uint_as_float(w & 0xffff0000u); }
; DEV float sigmoidf_(float x) { return 1.0f / (1.0f + __expf(-x)); }
;   DEV void operator()(const f32x4 (&acc)[2][2][4][2], const Unit& u, int wr, int wc, int fr, int fq) const {
;     ...
;               const size_t o = (size_t)(row0 + ai * HALF + (mp * 2 + mm) * 16) * D + col0 + bj * HALF + n * 16;
;               pw[mm][bj][n] = *(const u32x2*)(PROJ + o);
;               xv[mm][bj][n] = *(const f32x4*)(X + o);
;             }
; #pragma unroll
;         for (int mm = 0; mm < 2; ++mm)
; #pragma unroll
;           for (int bj = 0; bj < 2; ++bj)
; #pragma unroll
;             for (int n = 0; n < 2; ++n) {
;               const size_t o = (size_t)(row0 + ai * HALF + (mp * 2 + mm) * 16) * D + col0 + bj * HALF + n * 16;
;               const f32x4 v = acc[ai][bj][mp * 2 + mm][n];
;               f32x4 x = xv[mm][bj][n]; const u32x2 w = pw[mm][bj][n];
;               x[0] += sigmoidf_(v[0]) * bflo(w.x); x[1] += sigmoidf_(v[1]) * bfhi(w.x); x[2] += sigmoidf_(v[2]) * bflo(w.y); x[3] += sigmoidf_(v[3]) * bfhi(w.y);
;               *(f32x4*)(X + o) = x;
;             }
	v_exp_f32_e32 v86, v86
	v_rcp_f32_e32 v105, v101
	v_exp_f32_e32 v87, v87
	v_mul_f32_e32 v80, 0xbfb8aa3b, v80
	v_mul_f32_e32 v81, 0xbfb8aa3b, v81
	v_fma_f32 v106, -v101, v105, 1.0
	v_fmac_f32_e32 v105, v106, v105
	v_mov_b32_e32 v101, v105
	v_rcp_f32_e32 v105, v100
	v_pk_add_f32 v[86:87], v[86:87], 1.0 op_sel_hi:[1,0]
	v_exp_f32_e32 v80, v80
	v_exp_f32_e32 v81, v81
	v_fma_f32 v106, -v100, v105, 1.0
	v_fmac_f32_e32 v105, v106, v105
	v_mov_b32_e32 v100, v105
	v_lshlrev_b32_e32 v104, 16, v184
	v_and_b32_e32 v105, 0xffff0000, v184
	v_pk_fma_f32 v[100:101], v[100:101], v[104:105], v[120:121]
	v_rcp_f32_e32 v105, v103
	v_pk_add_f32 v[80:81], v[80:81], 1.0 op_sel_hi:[1,0]
	v_mul_f32_e32 v82, 0xbfb8aa3b, v82
	v_mul_f32_e32 v83, 0xbfb8aa3b, v83
	v_fma_f32 v106, -v103, v105, 1.0
	v_fmac_f32_e32 v105, v106, v105
	v_mov_b32_e32 v103, v105
	v_rcp_f32_e32 v105, v102
	v_exp_f32_e32 v82, v82
	v_exp_f32_e32 v83, v83
	v_mul_f32_e32 v76, 0xbfb8aa3b, v76
	v_fma_f32 v106, -v102, v105, 1.0
	v_fmac_f32_e32 v105, v106, v105
	v_mov_b32_e32 v102, v105
	v_lshlrev_b32_e32 v104, 16, v185
	v_and_b32_e32 v105, 0xffff0000, v185
	v_pk_fma_f32 v[102:103], v[102:103], v[104:105], v[122:123]
	global_store_dwordx4 v[112:113], v[100:103], off offset:512
	v_pk_add_f32 v[82:83], v[82:83], 1.0 op_sel_hi:[1,0]
	v_mul_f32_e32 v77, 0xbfb8aa3b, v77
	v_rcp_f32_e32 v101, v97
	v_exp_f32_e32 v76, v76
	v_exp_f32_e32 v77, v77
	v_mul_f32_e32 v72, 0xbfb8aa3b, v72
	v_fma_f32 v102, -v97, v101, 1.0
	v_fmac_f32_e32 v101, v102, v101
	v_mov_b32_e32 v97, v101
	v_rcp_f32_e32 v101, v96
	v_pk_add_f32 v[76:77], v[76:77], 1.0 op_sel_hi:[1,0]
	v_mul_f32_e32 v73, 0xbfb8aa3b, v73
	v_exp_f32_e32 v72, v72
	v_fma_f32 v102, -v96, v101, 1.0
	v_fmac_f32_e32 v101, v102, v101
	v_mov_b32_e32 v96, v101
	v_lshlrev_b32_e32 v100, 16, v182
	v_and_b32_e32 v101, 0xffff0000, v182
	v_pk_fma_f32 v[96:97], v[96:97], v[100:101], v[108:109]
	v_rcp_f32_e32 v101, v99
	v_exp_f32_e32 v73, v73
	v_mul_f32_e32 v74, 0xbfb8aa3b, v74
	v_mul_f32_e32 v75, 0xbfb8aa3b, v75
	v_fma_f32 v102, -v99, v101, 1.0
	v_fmac_f32_e32 v101, v102, v101
	v_mov_b32_e32 v99, v101
	v_rcp_f32_e32 v101, v98
	v_pk_add_f32 v[72:73], v[72:73], 1.0 op_sel_hi:[1,0]
	v_exp_f32_e32 v74, v74
	v_exp_f32_e32 v75, v75
	v_fma_f32 v102, -v98, v101, 1.0
	v_fmac_f32_e32 v101, v102, v101
	v_mov_b32_e32 v98, v101
	v_lshlrev_b32_e32 v100, 16, v183
	v_and_b32_e32 v101, 0xffff0000, v183
	v_pk_fma_f32 v[98:99], v[98:99], v[100:101], v[110:111]
	global_store_dwordx4 v[112:113], v[96:99], off offset:576
	s_nop 0
	s_nop 0
	v_lshlrev_b64 v[96:97], 10, v[148:149]
	v_lshl_add_u64 v[96:97], v[96:97], 0, v[166:167]
	v_lshlrev_b64 v[98:99], 1, v[96:97]
	v_lshl_add_u64 v[100:101], s[40:41], 0, v[98:99]
	global_load_dwordx2 v[146:147], v[100:101], off
	v_lshl_add_u64 v[96:97], v[96:97], 2, s[22:23]
	global_load_dwordx4 v[124:127], v[96:97], off
	v_or_b32_e32 v100, 32, v98
	v_mov_b32_e32 v101, v99
	v_lshl_add_u64 v[100:101], s[40:41], 0, v[100:101]
	global_load_dwordx2 v[142:143], v[100:101], off
	global_load_dwordx4 v[120:123], v[96:97], off offset:64
	v_mov_b32_e32 v93, v151
	v_rcp_f32_e32 v151, v92
	v_or_b32_e32 v100, 0x100, v98
	v_mov_b32_e32 v101, v99
	v_lshl_add_u64 v[100:101], s[40:41], 0, v[100:101]
	v_fma_f32 v152, -v92, v151, 1.0
	v_fmac_f32_e32 v151, v152, v151
	v_mov_b32_e32 v92, v151
	v_or_b32_e32 v98, 0x120, v98
	global_load_dwordx2 v[140:141], v[100:101], off
	global_load_dwordx4 v[116:119], v[96:97], off offset:512
	v_lshl_add_u64 v[98:99], s[40:41], 0, v[98:99]
	global_load_dwordx2 v[136:137], v[98:99], off
	global_load_dwordx4 v[112:115], v[96:97], off offset:576
	v_lshlrev_b64 v[96:97], 10, v[138:139]
	v_lshl_add_u64 v[96:97], v[96:97], 0, v[166:167]
	v_lshlrev_b64 v[98:99], 1, v[96:97]
	v_lshl_add_u64 v[100:101], s[40:41], 0, v[98:99]
	global_load_dwordx2 v[134:135], v[100:101], off
	v_or_b32_e32 v100, 32, v98
	v_mov_b32_e32 v101, v99
	v_lshl_add_u64 v[96:97], v[96:97], 2, s[22:23]
	v_lshl_add_u64 v[100:101], s[40:41], 0, v[100:101]
	v_lshlrev_b64 v[148:149], 12, v[148:149]
	global_load_dwordx4 v[108:111], v[96:97], off
	global_load_dwordx2 v[132:133], v[100:101], off
	global_load_dwordx4 v[104:107], v[96:97], off offset:64
	v_or_b32_e32 v100, 0x100, v98
	v_mov_b32_e32 v101, v99
	v_or_b32_e32 v98, 0x120, v98
	v_lshl_add_u64 v[100:101], s[40:41], 0, v[100:101]
	v_lshl_add_u64 v[98:99], s[40:41], 0, v[98:99]
	global_load_dwordx2 v[130:131], v[100:101], off
	s_nop 0
	global_load_dwordx4 v[100:103], v[96:97], off offset:512
	global_load_dwordx2 v[128:129], v[98:99], off
	s_nop 0
	global_load_dwordx4 v[96:99], v[96:97], off offset:576
	v_pk_add_f32 v[74:75], v[74:75], 1.0 op_sel_hi:[1,0]
	v_mul_f32_e32 v68, 0xbfb8aa3b, v68
	v_mul_f32_e32 v69, 0xbfb8aa3b, v69
	v_exp_f32_e32 v68, v68
	v_exp_f32_e32 v69, v69
	v_mul_f32_e32 v70, 0xbfb8aa3b, v70
	v_mul_f32_e32 v71, 0xbfb8aa3b, v71
	v_exp_f32_e32 v70, v70
	v_pk_add_f32 v[68:69], v[68:69], 1.0 op_sel_hi:[1,0]
	v_exp_f32_e32 v71, v71
	v_mul_f32_e32 v64, 0xbfb8aa3b, v64
	v_mul_f32_e32 v65, 0xbfb8aa3b, v65
	v_exp_f32_e32 v64, v64
	v_pk_add_f32 v[70:71], v[70:71], 1.0 op_sel_hi:[1,0]
	v_exp_f32_e32 v65, v65
	v_mul_f32_e32 v66, 0xbfb8aa3b, v66
	v_mul_f32_e32 v67, 0xbfb8aa3b, v67
	v_exp_f32_e32 v66, v66
	v_pk_add_f32 v[64:65], v[64:65], 1.0 op_sel_hi:[1,0]
	v_exp_f32_e32 v67, v67
	v_mul_f32_e32 v60, 0xbfb8aa3b, v60
	v_mul_f32_e32 v61, 0xbfb8aa3b, v61
	v_exp_f32_e32 v60, v60
	v_pk_add_f32 v[66:67], v[66:67], 1.0 op_sel_hi:[1,0]
	v_exp_f32_e32 v61, v61
	v_mul_f32_e32 v56, 0xbfb8aa3b, v56
	v_mul_f32_e32 v57, 0xbfb8aa3b, v57
	v_exp_f32_e32 v56, v56
	s_waitcnt vmcnt(15)
	v_lshlrev_b32_e32 v150, 16, v146
	v_and_b32_e32 v151, 0xffff0000, v146
	s_waitcnt vmcnt(14)
; DEV float bflo(unsigned w) { return __uint_as_float(w << 16); }
; DEV float bfhi(unsigned w) { return __uint_as_float(w & 0xffff0000u); }
; DEV float sigmoidf_(float x) { return 1.0f / (1.0f + __expf(-x)); }
;   DEV void operator()(const f32x4 (&acc)[2][2][4][2], const Unit& u, int wr, int wc, int fr, int fq) const {
;     ...
;               const size_t o = (size_t)(row0 + ai * HALF + (mp * 2 + mm) * 16) * D + col0 + bj * HALF + n * 16;
;               pw[mm][bj][n] = *(const u32x2*)(PROJ + o);
;               xv[mm][bj][n] = *(const f32x4*)(X + o);
;             }
; #pragma unroll
;         for (int mm = 0; mm < 2; ++mm)
; #pragma unroll
;           for (int bj = 0; bj < 2; ++bj)
; #pragma unroll
;             for (int n = 0; n < 2; ++n) {
;               const size_t o = (size_t)(row0 + ai * HALF + (mp * 2 + mm) * 16) * D + col0 + bj * HALF + n * 16;
;               const f32x4 v = acc[ai][bj][mp * 2 + mm][n];
;               f32x4 x = xv[mm][bj][n]; const u32x2 w = pw[mm][bj][n];
;               x[0] += sigmoidf_(v[0]) * bflo(w.x); x[1] += sigmoidf_(v[1]) * bfhi(w.x); x[2] += sigmoidf_(v[2]) * bflo(w.y); x[3] += sigmoidf_(v[3]) * bfhi(w.y);
;               *(f32x4*)(X + o) = x;
;             }
	v_pk_fma_f32 v[124:125], v[92:93], v[150:151], v[124:125]
	v_mul_f32_e32 v92, 0xbfb8aa3b, v94
	v_mul_f32_e32 v93, 0xbfb8aa3b, v95
	v_exp_f32_e32 v92, v92
	v_exp_f32_e32 v93, v93
	v_pk_add_f32 v[60:61], v[60:61], 1.0 op_sel_hi:[1,0]
	v_exp_f32_e32 v57, v57
	v_mul_f32_e32 v58, 0xbfb8aa3b, v58
	v_pk_add_f32 v[92:93], v[92:93], 1.0 op_sel_hi:[1,0]
	v_mul_f32_e32 v59, 0xbfb8aa3b, v59
	v_rcp_f32_e32 v95, v93
	v_pk_add_f32 v[56:57], v[56:57], 1.0 op_sel_hi:[1,0]
	v_exp_f32_e32 v58, v58
	v_exp_f32_e32 v59, v59
	v_fma_f32 v146, -v93, v95, 1.0
	v_fmac_f32_e32 v95, v146, v95
	v_mov_b32_e32 v93, v95
	v_rcp_f32_e32 v95, v92
	v_pk_add_f32 v[58:59], v[58:59], 1.0 op_sel_hi:[1,0]
	v_mul_f32_e32 v52, 0xbfb8aa3b, v52
	v_mul_f32_e32 v53, 0xbfb8aa3b, v53
	v_fma_f32 v146, -v92, v95, 1.0
	v_fmac_f32_e32 v95, v146, v95
	v_mov_b32_e32 v92, v95
	v_lshlrev_b32_e32 v94, 16, v147
	v_and_b32_e32 v95, 0xffff0000, v147
	v_pk_fma_f32 v[126:127], v[92:93], v[94:95], v[126:127]
	v_rcp_f32_e32 v95, v89
	v_lshl_add_u64 v[92:93], s[22:23], 0, v[148:149]
	v_lshl_add_u64 v[92:93], v[92:93], 0, v[144:145]
	global_store_dwordx4 v[92:93], v[124:127], off
	v_exp_f32_e32 v52, v52
	v_exp_f32_e32 v53, v53
	v_fma_f32 v124, -v89, v95, 1.0
	v_fmac_f32_e32 v95, v124, v95
	v_mov_b32_e32 v89, v95
	v_rcp_f32_e32 v95, v88
	v_pk_add_f32 v[52:53], v[52:53], 1.0 op_sel_hi:[1,0]
	v_mul_f32_e32 v54, 0xbfb8aa3b, v54
	v_mul_f32_e32 v55, 0xbfb8aa3b, v55
	v_fma_f32 v124, -v88, v95, 1.0
	v_fmac_f32_e32 v95, v124, v95
	v_mov_b32_e32 v88, v95
	s_waitcnt vmcnt(14)
	v_lshlrev_b32_e32 v94, 16, v142
	v_and_b32_e32 v95, 0xffff0000, v142
	s_waitcnt vmcnt(13)
	v_pk_fma_f32 v[88:89], v[88:89], v[94:95], v[120:121]
	v_rcp_f32_e32 v95, v91
	v_exp_f32_e32 v54, v54
	v_exp_f32_e32 v55, v55
	v_mul_f32_e32 v48, 0xbfb8aa3b, v48
	v_fma_f32 v120, -v91, v95, 1.0
	v_fmac_f32_e32 v95, v120, v95
	v_mov_b32_e32 v91, v95
	v_rcp_f32_e32 v95, v90
	v_pk_add_f32 v[54:55], v[54:55], 1.0 op_sel_hi:[1,0]
	v_mul_f32_e32 v49, 0xbfb8aa3b, v49
	v_exp_f32_e32 v48, v48
	v_fma_f32 v120, -v90, v95, 1.0
	v_fmac_f32_e32 v95, v120, v95
	v_mov_b32_e32 v90, v95
	v_lshlrev_b32_e32 v94, 16, v143
	v_and_b32_e32 v95, 0xffff0000, v143
	v_pk_fma_f32 v[90:91], v[90:91], v[94:95], v[122:123]
	global_store_dwordx4 v[92:93], v[88:91], off offset:64
	v_exp_f32_e32 v49, v49
	v_mul_f32_e32 v50, 0xbfb8aa3b, v50
	v_rcp_f32_e32 v89, v85
	v_pk_add_f32 v[48:49], v[48:49], 1.0 op_sel_hi:[1,0]
	v_mul_f32_e32 v51, 0xbfb8aa3b, v51
	v_exp_f32_e32 v50, v50
	v_fma_f32 v90, -v85, v89, 1.0
	v_fmac_f32_e32 v89, v90, v89
	v_mov_b32_e32 v85, v89
	v_rcp_f32_e32 v89, v84
	v_exp_f32_e32 v51, v51
	v_mul_f32_e32 v44, 0xbfb8aa3b, v44
	v_mul_f32_e32 v45, 0xbfb8aa3b, v45
	v_fma_f32 v90, -v84, v89, 1.0
	v_fmac_f32_e32 v89, v90, v89
	v_mov_b32_e32 v84, v89
	s_waitcnt vmcnt(13)
	v_lshlrev_b32_e32 v88, 16, v140
	v_and_b32_e32 v89, 0xffff0000, v140
	s_waitcnt vmcnt(12)
	v_pk_fma_f32 v[84:85], v[84:85], v[88:89], v[116:117]
	v_rcp_f32_e32 v89, v87
	v_rcp_f32_e32 v117, v61
	v_fma_f32 v90, -v87, v89, 1.0
	v_fmac_f32_e32 v89, v90, v89
	v_mov_b32_e32 v87, v89
	v_rcp_f32_e32 v89, v86
	v_pk_add_f32 v[50:51], v[50:51], 1.0 op_sel_hi:[1,0]
	v_exp_f32_e32 v44, v44
	v_exp_f32_e32 v45, v45
	v_fma_f32 v90, -v86, v89, 1.0
	v_fmac_f32_e32 v89, v90, v89
	v_mov_b32_e32 v86, v89
	v_lshlrev_b32_e32 v88, 16, v141
	v_and_b32_e32 v89, 0xffff0000, v141
	v_pk_fma_f32 v[86:87], v[86:87], v[88:89], v[118:119]
	global_store_dwordx4 v[92:93], v[84:87], off offset:512
	v_fma_f32 v118, -v61, v117, 1.0
	v_fmac_f32_e32 v117, v118, v117
	v_rcp_f32_e32 v85, v81
	v_pk_add_f32 v[44:45], v[44:45], 1.0 op_sel_hi:[1,0]
	v_mul_f32_e32 v40, 0xbfb8aa3b, v40
	v_mul_f32_e32 v41, 0xbfb8aa3b, v41
	v_fma_f32 v86, -v81, v85, 1.0
	v_fmac_f32_e32 v85, v86, v85
	v_mov_b32_e32 v81, v85
	v_rcp_f32_e32 v85, v80
	v_exp_f32_e32 v40, v40
	v_exp_f32_e32 v41, v41
	v_mul_f32_e32 v42, 0xbfb8aa3b, v42
	v_fma_f32 v86, -v80, v85, 1.0
	v_fmac_f32_e32 v85, v86, v85
	v_mov_b32_e32 v80, v85
	s_waitcnt vmcnt(12)
	v_lshlrev_b32_e32 v84, 16, v136
	v_and_b32_e32 v85, 0xffff0000, v136
	s_waitcnt vmcnt(11)
	v_pk_fma_f32 v[80:81], v[80:81], v[84:85], v[112:113]
	v_rcp_f32_e32 v85, v83
	v_pk_add_f32 v[40:41], v[40:41], 1.0 op_sel_hi:[1,0]
	v_mul_f32_e32 v43, 0xbfb8aa3b, v43
	v_exp_f32_e32 v42, v42
	v_fma_f32 v86, -v83, v85, 1.0
	v_fmac_f32_e32 v85, v86, v85
	v_mov_b32_e32 v83, v85
	v_rcp_f32_e32 v85, v82
	v_exp_f32_e32 v43, v43
	v_mul_f32_e32 v36, 0xbfb8aa3b, v36
	v_mul_f32_e32 v37, 0xbfb8aa3b, v37
	v_fma_f32 v86, -v82, v85, 1.0
	v_fmac_f32_e32 v85, v86, v85
	v_mov_b32_e32 v82, v85
	v_lshlrev_b32_e32 v84, 16, v137
	v_and_b32_e32 v85, 0xffff0000, v137
	v_pk_fma_f32 v[82:83], v[82:83], v[84:85], v[114:115]
	global_store_dwordx4 v[92:93], v[80:83], off offset:576
	v_lshlrev_b64 v[84:85], 12, v[138:139]
	v_add_u32_e32 v114, 0x80, v180
	v_rcp_f32_e32 v81, v77
	v_ashrrev_i32_e32 v115, 31, v114
	v_pk_add_f32 v[42:43], v[42:43], 1.0 op_sel_hi:[1,0]
	v_exp_f32_e32 v36, v36
	v_fma_f32 v82, -v77, v81, 1.0
	v_fmac_f32_e32 v81, v82, v81
	v_mov_b32_e32 v77, v81
	v_rcp_f32_e32 v81, v76
	v_exp_f32_e32 v37, v37
	v_mul_f32_e32 v38, 0xbfb8aa3b, v38
	v_mul_f32_e32 v39, 0xbfb8aa3b, v39
	v_fma_f32 v82, -v76, v81, 1.0
	v_fmac_f32_e32 v81, v82, v81
	v_mov_b32_e32 v76, v81
	s_waitcnt vmcnt(11)
	v_lshlrev_b32_e32 v80, 16, v134
	v_and_b32_e32 v81, 0xffff0000, v134
	s_waitcnt vmcnt(10)
; DEV float bflo(unsigned w) { return __uint_as_float(w << 16); }
; DEV float bfhi(unsigned w) { return __uint_as_float(w & 0xffff0000u); }
; DEV float sigmoidf_(float x) { return 1.0f / (1.0f + __expf(-x)); }
;   DEV void operator()(const f32x4 (&acc)[2][2][4][2], const Unit& u, int wr, int wc, int fr, int fq) const {
;     const int row0 = u.pm * BM + wr * 64 + fr, col0 = u.pn * BM + wc * 32 + 4 * fq;
; #pragma unroll
;     for (int ai = 0; ai < 2; ++ai)
; #pragma unroll
;       for (int mp = 0; mp < 2; ++mp) {
;         f32x4 xv[2][2][2]; u32x2 pw[2][2][2];
; #pragma unroll
;         for (int mm = 0; mm < 2; ++mm)
; #pragma unroll
;           for (int bj = 0; bj < 2; ++bj)
; #pragma unroll
;             for (int n = 0; n < 2; ++n) {
;               const size_t o = (size_t)(row0 + ai * HALF + (mp * 2 + mm) * 16) * D + col0 + bj * HALF + n * 16;
;               pw[mm][bj][n] = *(const u32x2*)(PROJ + o);
;               xv[mm][bj][n] = *(const f32x4*)(X + o);
;             }
; #pragma unroll
;         for (int mm = 0; mm < 2; ++mm)
; #pragma unroll
;           for (int bj = 0; bj < 2; ++bj)
; #pragma unroll
;             for (int n = 0; n < 2; ++n) {
;               const size_t o = (size_t)(row0 + ai * HALF + (mp * 2 + mm) * 16) * D + col0 + bj * HALF + n * 16;
;               const f32x4 v = acc[ai][bj][mp * 2 + mm][n];
;               f32x4 x = xv[mm][bj][n]; const u32x2 w = pw[mm][bj][n];
;               x[0] += sigmoidf_(v[0]) * bflo(w.x); x[1] += sigmoidf_(v[1]) * bfhi(w.x); x[2] += sigmoidf_(v[2]) * bflo(w.y); x[3] += sigmoidf_(v[3]) * bfhi(w.y);
;               *(f32x4*)(X + o) = x;
	v_pk_fma_f32 v[80:81], v[76:77], v[80:81], v[108:109]
	v_mul_f32_e32 v76, 0xbfb8aa3b, v78
	v_mul_f32_e32 v77, 0xbfb8aa3b, v79
	v_exp_f32_e32 v76, v76
	v_exp_f32_e32 v77, v77
	v_pk_add_f32 v[36:37], v[36:37], 1.0 op_sel_hi:[1,0]
	v_exp_f32_e32 v38, v38
	v_exp_f32_e32 v39, v39
	v_pk_add_f32 v[76:77], v[76:77], 1.0 op_sel_hi:[1,0]
	v_mul_f32_e32 v32, 0xbfb8aa3b, v32
	v_rcp_f32_e32 v79, v77
	v_pk_add_f32 v[38:39], v[38:39], 1.0 op_sel_hi:[1,0]
	v_mul_f32_e32 v33, 0xbfb8aa3b, v33
	v_exp_f32_e32 v32, v32
	v_fma_f32 v82, -v77, v79, 1.0
	v_fmac_f32_e32 v79, v82, v79
	v_mov_b32_e32 v77, v79
	v_rcp_f32_e32 v79, v76
	v_exp_f32_e32 v33, v33
	v_mul_f32_e32 v34, 0xbfb8aa3b, v34
	v_mul_f32_e32 v35, 0xbfb8aa3b, v35
	v_fma_f32 v82, -v76, v79, 1.0
	v_fmac_f32_e32 v79, v82, v79
	v_mov_b32_e32 v76, v79
	v_lshlrev_b32_e32 v78, 16, v135
	v_and_b32_e32 v79, 0xffff0000, v135
	v_pk_fma_f32 v[82:83], v[76:77], v[78:79], v[110:111]
	v_rcp_f32_e32 v79, v73
	v_lshl_add_u64 v[76:77], s[22:23], 0, v[84:85]
	v_lshl_add_u64 v[76:77], v[76:77], 0, v[144:145]
	global_store_dwordx4 v[76:77], v[80:83], off
	v_pk_add_f32 v[32:33], v[32:33], 1.0 op_sel_hi:[1,0]
	v_exp_f32_e32 v34, v34
	v_fma_f32 v80, -v73, v79, 1.0
	v_fmac_f32_e32 v79, v80, v79
	v_mov_b32_e32 v73, v79
	v_rcp_f32_e32 v79, v72
	v_exp_f32_e32 v35, v35
	v_mul_f32_e32 v28, 0xbfb8aa3b, v28
	v_mul_f32_e32 v29, 0xbfb8aa3b, v29
	v_fma_f32 v80, -v72, v79, 1.0
	v_fmac_f32_e32 v79, v80, v79
	v_mov_b32_e32 v72, v79
	s_waitcnt vmcnt(10)
	v_lshlrev_b32_e32 v78, 16, v132
	v_and_b32_e32 v79, 0xffff0000, v132
	s_waitcnt vmcnt(9)
	v_pk_fma_f32 v[72:73], v[72:73], v[78:79], v[104:105]
	v_rcp_f32_e32 v79, v75
	v_pk_add_f32 v[34:35], v[34:35], 1.0 op_sel_hi:[1,0]
	v_exp_f32_e32 v28, v28
	v_exp_f32_e32 v29, v29
	v_fma_f32 v80, -v75, v79, 1.0
	v_fmac_f32_e32 v79, v80, v79
	v_mov_b32_e32 v75, v79
	v_rcp_f32_e32 v79, v74
	v_pk_add_f32 v[28:29], v[28:29], 1.0 op_sel_hi:[1,0]
	v_mul_f32_e32 v24, 0xbfb8aa3b, v24
	v_mul_f32_e32 v25, 0xbfb8aa3b, v25
	v_fma_f32 v80, -v74, v79, 1.0
	v_fmac_f32_e32 v79, v80, v79
	v_mov_b32_e32 v74, v79
	v_lshlrev_b32_e32 v78, 16, v133
	v_and_b32_e32 v79, 0xffff0000, v133
	v_pk_fma_f32 v[74:75], v[74:75], v[78:79], v[106:107]
	global_store_dwordx4 v[76:77], v[72:75], off offset:64
	v_add_u32_e32 v106, 0x90, v180
	v_ashrrev_i32_e32 v107, 31, v106
	v_rcp_f32_e32 v73, v69
	v_exp_f32_e32 v24, v24
	v_exp_f32_e32 v25, v25
	v_mul_f32_e32 v26, 0xbfb8aa3b, v26
	v_fma_f32 v74, -v69, v73, 1.0
	v_fmac_f32_e32 v73, v74, v73
	v_mov_b32_e32 v69, v73
	v_rcp_f32_e32 v73, v68
	v_pk_add_f32 v[24:25], v[24:25], 1.0 op_sel_hi:[1,0]
	v_mul_f32_e32 v27, 0xbfb8aa3b, v27
	v_exp_f32_e32 v26, v26
	v_fma_f32 v74, -v68, v73, 1.0
	v_fmac_f32_e32 v73, v74, v73
	v_mov_b32_e32 v68, v73
	s_waitcnt vmcnt(9)
	v_lshlrev_b32_e32 v72, 16, v130
	v_and_b32_e32 v73, 0xffff0000, v130
	s_waitcnt vmcnt(8)
	v_pk_fma_f32 v[68:69], v[68:69], v[72:73], v[100:101]
	v_rcp_f32_e32 v73, v71
	v_exp_f32_e32 v27, v27
	v_mul_f32_e32 v20, 0xbfb8aa3b, v20
	v_mul_f32_e32 v21, 0xbfb8aa3b, v21
	v_fma_f32 v74, -v71, v73, 1.0
	v_fmac_f32_e32 v73, v74, v73
	v_mov_b32_e32 v71, v73
	v_rcp_f32_e32 v73, v70
	v_pk_add_f32 v[26:27], v[26:27], 1.0 op_sel_hi:[1,0]
	v_exp_f32_e32 v20, v20
	v_exp_f32_e32 v21, v21
	v_fma_f32 v74, -v70, v73, 1.0
	v_fmac_f32_e32 v73, v74, v73
	v_mov_b32_e32 v70, v73
	v_lshlrev_b32_e32 v72, 16, v131
	v_and_b32_e32 v73, 0xffff0000, v131
	v_pk_fma_f32 v[70:71], v[70:71], v[72:73], v[102:103]
	global_store_dwordx4 v[76:77], v[68:71], off offset:512
	v_pk_add_f32 v[20:21], v[20:21], 1.0 op_sel_hi:[1,0]
	v_mul_f32_e32 v22, 0xbfb8aa3b, v22
	v_rcp_f32_e32 v69, v65
	v_mul_f32_e32 v23, 0xbfb8aa3b, v23
	v_exp_f32_e32 v22, v22
	v_exp_f32_e32 v23, v23
	v_fma_f32 v70, -v65, v69, 1.0
	v_fmac_f32_e32 v69, v70, v69
	v_mov_b32_e32 v65, v69
	v_rcp_f32_e32 v69, v64
	v_pk_add_f32 v[22:23], v[22:23], 1.0 op_sel_hi:[1,0]
	v_mul_f32_e32 v16, 0xbfb8aa3b, v16
	v_mul_f32_e32 v17, 0xbfb8aa3b, v17
	v_fma_f32 v70, -v64, v69, 1.0
	v_fmac_f32_e32 v69, v70, v69
	v_mov_b32_e32 v64, v69
	s_waitcnt vmcnt(8)
	v_lshlrev_b32_e32 v68, 16, v128
	v_and_b32_e32 v69, 0xffff0000, v128
	s_waitcnt vmcnt(7)
	v_pk_fma_f32 v[64:65], v[64:65], v[68:69], v[96:97]
	v_rcp_f32_e32 v69, v67
	v_exp_f32_e32 v16, v16
	v_exp_f32_e32 v17, v17
	v_mul_f32_e32 v18, 0xbfb8aa3b, v18
	v_fma_f32 v70, -v67, v69, 1.0
	v_fmac_f32_e32 v69, v70, v69
	v_mov_b32_e32 v67, v69
	v_rcp_f32_e32 v69, v66
	v_pk_add_f32 v[16:17], v[16:17], 1.0 op_sel_hi:[1,0]
	v_mul_f32_e32 v19, 0xbfb8aa3b, v19
	v_exp_f32_e32 v18, v18
	v_fma_f32 v70, -v66, v69, 1.0
	v_fmac_f32_e32 v69, v70, v69
	v_mov_b32_e32 v66, v69
	v_lshlrev_b32_e32 v68, 16, v129
	v_and_b32_e32 v69, 0xffff0000, v129
	v_pk_fma_f32 v[66:67], v[66:67], v[68:69], v[98:99]
	global_store_dwordx4 v[76:77], v[64:67], off offset:576
	s_nop 0
	s_nop 0
	v_lshlrev_b64 v[64:65], 10, v[114:115]
	v_lshl_add_u64 v[64:65], v[64:65], 0, v[166:167]
	v_lshlrev_b64 v[66:67], 1, v[64:65]
	v_lshl_add_u64 v[68:69], s[40:41], 0, v[66:67]
	global_load_dwordx2 v[112:113], v[68:69], off
	v_lshl_add_u64 v[64:65], v[64:65], 2, s[22:23]
	global_load_dwordx4 v[92:95], v[64:65], off
	v_or_b32_e32 v68, 32, v66
	v_mov_b32_e32 v69, v67
	v_lshl_add_u64 v[68:69], s[40:41], 0, v[68:69]
	global_load_dwordx2 v[110:111], v[68:69], off
	global_load_dwordx4 v[88:91], v[64:65], off offset:64
	v_mov_b32_e32 v61, v117
	v_rcp_f32_e32 v117, v60
	v_or_b32_e32 v68, 0x100, v66
	v_mov_b32_e32 v69, v67
	v_lshl_add_u64 v[68:69], s[40:41], 0, v[68:69]
	v_fma_f32 v118, -v60, v117, 1.0
	v_fmac_f32_e32 v117, v118, v117
	v_mov_b32_e32 v60, v117
	v_or_b32_e32 v66, 0x120, v66
	global_load_dwordx2 v[108:109], v[68:69], off
; DEV float bflo(unsigned w) { return __uint_as_float(w << 16); }
; DEV float bfhi(unsigned w) { return __uint_as_float(w & 0xffff0000u); }
; DEV float sigmoidf_(float x) { return 1.0f / (1.0f + __expf(-x)); }
;   DEV void operator()(const f32x4 (&acc)[2][2][4][2], const Unit& u, int wr, int wc, int fr, int fq) const {
;     const int row0 = u.pm * BM + wr * 64 + fr, col0 = u.pn * BM + wc * 32 + 4 * fq;
; #pragma unroll
;     for (int ai = 0; ai < 2; ++ai)
; #pragma unroll
;       for (int mp = 0; mp < 2; ++mp) {
;         f32x4 xv[2][2][2]; u32x2 pw[2][2][2];
; #pragma unroll
;         for (int mm = 0; mm < 2; ++mm)
; #pragma unroll
;           for (int bj = 0; bj < 2; ++bj)
; #pragma unroll
;             for (int n = 0; n < 2; ++n) {
;               const size_t o = (size_t)(row0 + ai * HALF + (mp * 2 + mm) * 16) * D + col0 + bj * HALF + n * 16;
;               pw[mm][bj][n] = *(const u32x2*)(PROJ + o);
;               xv[mm][bj][n] = *(const f32x4*)(X + o);
;             }
; #pragma unroll
;         for (int mm = 0; mm < 2; ++mm)
; #pragma unroll
;           for (int bj = 0; bj < 2; ++bj)
; #pragma unroll
;             for (int n = 0; n < 2; ++n) {
;               const size_t o = (size_t)(row0 + ai * HALF + (mp * 2 + mm) * 16) * D + col0 + bj * HALF + n * 16;
;               const f32x4 v = acc[ai][bj][mp * 2 + mm][n];
;               f32x4 x = xv[mm][bj][n]; const u32x2 w = pw[mm][bj][n];
;               x[0] += sigmoidf_(v[0]) * bflo(w.x); x[1] += sigmoidf_(v[1]) * bfhi(w.x); x[2] += sigmoidf_(v[2]) * bflo(w.y); x[3] += sigmoidf_(v[3]) * bfhi(w.y);
;               *(f32x4*)(X + o) = x;
	global_load_dwordx4 v[84:87], v[64:65], off offset:512
	v_lshl_add_u64 v[66:67], s[40:41], 0, v[66:67]
	global_load_dwordx2 v[104:105], v[66:67], off
	global_load_dwordx4 v[80:83], v[64:65], off offset:576
	v_lshlrev_b64 v[64:65], 10, v[106:107]
	v_lshl_add_u64 v[64:65], v[64:65], 0, v[166:167]
	v_lshlrev_b64 v[66:67], 1, v[64:65]
	v_lshl_add_u64 v[68:69], s[40:41], 0, v[66:67]
	global_load_dwordx2 v[102:103], v[68:69], off
	v_or_b32_e32 v68, 32, v66
	v_mov_b32_e32 v69, v67
	v_lshl_add_u64 v[64:65], v[64:65], 2, s[22:23]
	v_lshl_add_u64 v[68:69], s[40:41], 0, v[68:69]
	v_lshlrev_b64 v[114:115], 12, v[114:115]
	global_load_dwordx4 v[76:79], v[64:65], off
	global_load_dwordx2 v[100:101], v[68:69], off
	global_load_dwordx4 v[72:75], v[64:65], off offset:64
	v_or_b32_e32 v68, 0x100, v66
	v_mov_b32_e32 v69, v67
	v_or_b32_e32 v66, 0x120, v66
	v_lshl_add_u64 v[68:69], s[40:41], 0, v[68:69]
	v_lshl_add_u64 v[66:67], s[40:41], 0, v[66:67]
	global_load_dwordx2 v[98:99], v[68:69], off
	s_nop 0
	global_load_dwordx4 v[68:71], v[64:65], off offset:512
	global_load_dwordx2 v[96:97], v[66:67], off
	s_nop 0
	global_load_dwordx4 v[64:67], v[64:65], off offset:576
	v_exp_f32_e32 v19, v19
	v_mul_f32_e32 v12, 0xbfb8aa3b, v12
	v_mul_f32_e32 v13, 0xbfb8aa3b, v13
	v_exp_f32_e32 v12, v12
	v_pk_add_f32 v[18:19], v[18:19], 1.0 op_sel_hi:[1,0]
	v_exp_f32_e32 v13, v13
	v_mul_f32_e32 v8, 0xbfb8aa3b, v8
	v_mul_f32_e32 v9, 0xbfb8aa3b, v9
	v_exp_f32_e32 v8, v8
	v_pk_add_f32 v[12:13], v[12:13], 1.0 op_sel_hi:[1,0]
	v_exp_f32_e32 v9, v9
	v_mul_f32_e32 v10, 0xbfb8aa3b, v10
	v_mul_f32_e32 v11, 0xbfb8aa3b, v11
	v_exp_f32_e32 v10, v10
	v_pk_add_f32 v[8:9], v[8:9], 1.0 op_sel_hi:[1,0]
	v_exp_f32_e32 v11, v11
	v_mul_f32_e32 v4, 0xbfb8aa3b, v4
	v_mul_f32_e32 v5, 0xbfb8aa3b, v5
	v_exp_f32_e32 v4, v4
	v_pk_add_f32 v[10:11], v[10:11], 1.0 op_sel_hi:[1,0]
	v_exp_f32_e32 v5, v5
	v_mul_f32_e32 v6, 0xbfb8aa3b, v6
	v_mul_f32_e32 v7, 0xbfb8aa3b, v7
	v_exp_f32_e32 v6, v6
	v_pk_add_f32 v[4:5], v[4:5], 1.0 op_sel_hi:[1,0]
	v_exp_f32_e32 v7, v7
	v_mul_f32_e32 v0, 0xbfb8aa3b, v0
	v_mul_f32_e32 v1, 0xbfb8aa3b, v1
	s_waitcnt vmcnt(15)
	v_lshlrev_b32_e32 v116, 16, v112
	v_and_b32_e32 v117, 0xffff0000, v112
	s_waitcnt vmcnt(14)
	v_pk_fma_f32 v[92:93], v[60:61], v[116:117], v[92:93]
	v_mul_f32_e32 v60, 0xbfb8aa3b, v62
	v_mul_f32_e32 v61, 0xbfb8aa3b, v63
	v_exp_f32_e32 v60, v60
	v_exp_f32_e32 v61, v61
	v_pk_add_f32 v[6:7], v[6:7], 1.0 op_sel_hi:[1,0]
	v_exp_f32_e32 v0, v0
	v_exp_f32_e32 v1, v1
	v_pk_add_f32 v[60:61], v[60:61], 1.0 op_sel_hi:[1,0]
	v_mul_f32_e32 v2, 0xbfb8aa3b, v2
	v_rcp_f32_e32 v63, v61
	v_pk_add_f32 v[0:1], v[0:1], 1.0 op_sel_hi:[1,0]
	v_mul_f32_e32 v3, 0xbfb8aa3b, v3
	v_exp_f32_e32 v2, v2
	v_fma_f32 v112, -v61, v63, 1.0
	v_fmac_f32_e32 v63, v112, v63
	v_mov_b32_e32 v61, v63
	v_rcp_f32_e32 v63, v60
	v_exp_f32_e32 v3, v3
	v_fma_f32 v112, -v60, v63, 1.0
	v_fmac_f32_e32 v63, v112, v63
	v_mov_b32_e32 v60, v63
	v_lshlrev_b32_e32 v62, 16, v113
	v_and_b32_e32 v63, 0xffff0000, v113
	v_pk_fma_f32 v[94:95], v[60:61], v[62:63], v[94:95]
	v_rcp_f32_e32 v63, v57
	v_lshl_add_u64 v[60:61], s[22:23], 0, v[114:115]
	v_lshl_add_u64 v[60:61], v[60:61], 0, v[144:145]
	global_store_dwordx4 v[60:61], v[92:95], off
	v_pk_add_f32 v[2:3], v[2:3], 1.0 op_sel_hi:[1,0]
	s_nop 0
	v_fma_f32 v92, -v57, v63, 1.0
	v_fmac_f32_e32 v63, v92, v63
	v_mov_b32_e32 v57, v63
	v_rcp_f32_e32 v63, v56
	s_nop 0
	v_fma_f32 v92, -v56, v63, 1.0
	v_fmac_f32_e32 v63, v92, v63
	v_mov_b32_e32 v56, v63
	s_waitcnt vmcnt(14)
	v_lshlrev_b32_e32 v62, 16, v110
	v_and_b32_e32 v63, 0xffff0000, v110
	s_waitcnt vmcnt(13)
	v_pk_fma_f32 v[56:57], v[56:57], v[62:63], v[88:89]
	v_rcp_f32_e32 v63, v59
	s_nop 0
	v_fma_f32 v88, -v59, v63, 1.0
	v_fmac_f32_e32 v63, v88, v63
	v_mov_b32_e32 v59, v63
	v_rcp_f32_e32 v63, v58
	s_nop 0
	v_fma_f32 v88, -v58, v63, 1.0
	v_fmac_f32_e32 v63, v88, v63
	v_mov_b32_e32 v58, v63
	v_lshlrev_b32_e32 v62, 16, v111
	v_and_b32_e32 v63, 0xffff0000, v111
	v_pk_fma_f32 v[58:59], v[58:59], v[62:63], v[90:91]
	global_store_dwordx4 v[60:61], v[56:59], off offset:64
	s_nop 1
	v_rcp_f32_e32 v57, v53
	s_nop 0
	v_fma_f32 v58, -v53, v57, 1.0
	v_fmac_f32_e32 v57, v58, v57
	v_mov_b32_e32 v53, v57
	v_rcp_f32_e32 v57, v52
	s_nop 0
	v_fma_f32 v58, -v52, v57, 1.0
	v_fmac_f32_e32 v57, v58, v57
	v_mov_b32_e32 v52, v57
	s_waitcnt vmcnt(13)
	v_lshlrev_b32_e32 v56, 16, v108
	v_and_b32_e32 v57, 0xffff0000, v108
	s_waitcnt vmcnt(12)
	v_pk_fma_f32 v[52:53], v[52:53], v[56:57], v[84:85]
	v_rcp_f32_e32 v57, v55
	v_rcp_f32_e32 v85, v29
	v_fma_f32 v58, -v55, v57, 1.0
	v_fmac_f32_e32 v57, v58, v57
	v_mov_b32_e32 v55, v57
	v_rcp_f32_e32 v57, v54
	s_nop 0
	v_fma_f32 v58, -v54, v57, 1.0
	v_fmac_f32_e32 v57, v58, v57
	v_mov_b32_e32 v54, v57
	v_lshlrev_b32_e32 v56, 16, v109
	v_and_b32_e32 v57, 0xffff0000, v109
	v_pk_fma_f32 v[54:55], v[54:55], v[56:57], v[86:87]
	global_store_dwordx4 v[60:61], v[52:55], off offset:512
	v_fma_f32 v86, -v29, v85, 1.0
	v_fmac_f32_e32 v85, v86, v85
	v_rcp_f32_e32 v53, v49
	s_nop 0
	v_fma_f32 v54, -v49, v53, 1.0
	v_fmac_f32_e32 v53, v54, v53
	v_mov_b32_e32 v49, v53
	v_rcp_f32_e32 v53, v48
	s_nop 0
	v_fma_f32 v54, -v48, v53, 1.0
	v_fmac_f32_e32 v53, v54, v53
	v_mov_b32_e32 v48, v53
	s_waitcnt vmcnt(12)
	v_lshlrev_b32_e32 v52, 16, v104
	v_and_b32_e32 v53, 0xffff0000, v104
	s_waitcnt vmcnt(11)
; DEV float bflo(unsigned w) { return __uint_as_float(w << 16); }
; DEV float bfhi(unsigned w) { return __uint_as_float(w & 0xffff0000u); }
; DEV float sigmoidf_(float x) { return 1.0f / (1.0f + __expf(-x)); }
;   DEV void operator()(const f32x4 (&acc)[2][2][4][2], const Unit& u, int wr, int wc, int fr, int fq) const {
;     ...
;               const size_t o = (size_t)(row0 + ai * HALF + (mp * 2 + mm) * 16) * D + col0 + bj * HALF + n * 16;
;               pw[mm][bj][n] = *(const u32x2*)(PROJ + o);
;               xv[mm][bj][n] = *(const f32x4*)(X + o);
;             }
; #pragma unroll
;         for (int mm = 0; mm < 2; ++mm)
; #pragma unroll
;           for (int bj = 0; bj < 2; ++bj)
; #pragma unroll
;             for (int n = 0; n < 2; ++n) {
;               const size_t o = (size_t)(row0 + ai * HALF + (mp * 2 + mm) * 16) * D + col0 + bj * HALF + n * 16;
;               const f32x4 v = acc[ai][bj][mp * 2 + mm][n];
;               f32x4 x = xv[mm][bj][n]; const u32x2 w = pw[mm][bj][n];
;               x[0] += sigmoidf_(v[0]) * bflo(w.x); x[1] += sigmoidf_(v[1]) * bfhi(w.x); x[2] += sigmoidf_(v[2]) * bflo(w.y); x[3] += sigmoidf_(v[3]) * bfhi(w.y);
;               *(f32x4*)(X + o) = x;
	v_pk_fma_f32 v[48:49], v[48:49], v[52:53], v[80:81]
	v_rcp_f32_e32 v53, v51
	s_nop 0
	v_fma_f32 v54, -v51, v53, 1.0
	v_fmac_f32_e32 v53, v54, v53
	v_mov_b32_e32 v51, v53
	v_rcp_f32_e32 v53, v50
	s_nop 0
	v_fma_f32 v54, -v50, v53, 1.0
	v_fmac_f32_e32 v53, v54, v53
	v_mov_b32_e32 v50, v53
	v_lshlrev_b32_e32 v52, 16, v105
	v_and_b32_e32 v53, 0xffff0000, v105
	v_pk_fma_f32 v[50:51], v[50:51], v[52:53], v[82:83]
	global_store_dwordx4 v[60:61], v[48:51], off offset:576
	v_lshlrev_b64 v[52:53], 12, v[106:107]
	v_add_u32_e32 v82, 0xa0, v180
	v_rcp_f32_e32 v49, v45
	v_ashrrev_i32_e32 v83, 31, v82
	v_fma_f32 v50, -v45, v49, 1.0
	v_fmac_f32_e32 v49, v50, v49
	v_mov_b32_e32 v45, v49
	v_rcp_f32_e32 v49, v44
	s_nop 0
	v_fma_f32 v50, -v44, v49, 1.0
	v_fmac_f32_e32 v49, v50, v49
	v_mov_b32_e32 v44, v49
	s_waitcnt vmcnt(11)
	v_lshlrev_b32_e32 v48, 16, v102
	v_and_b32_e32 v49, 0xffff0000, v102
	s_waitcnt vmcnt(10)
	v_pk_fma_f32 v[48:49], v[44:45], v[48:49], v[76:77]
	v_mul_f32_e32 v44, 0xbfb8aa3b, v46
	v_mul_f32_e32 v45, 0xbfb8aa3b, v47
	v_exp_f32_e32 v44, v44
	v_exp_f32_e32 v45, v45
	s_nop 0
	v_pk_add_f32 v[44:45], v[44:45], 1.0 op_sel_hi:[1,0]
	s_nop 0
	v_rcp_f32_e32 v47, v45
	s_nop 0
	v_fma_f32 v50, -v45, v47, 1.0
	v_fmac_f32_e32 v47, v50, v47
	v_mov_b32_e32 v45, v47
	v_rcp_f32_e32 v47, v44
	s_nop 0
	v_fma_f32 v50, -v44, v47, 1.0
	v_fmac_f32_e32 v47, v50, v47
	v_mov_b32_e32 v44, v47
	v_lshlrev_b32_e32 v46, 16, v103
	v_and_b32_e32 v47, 0xffff0000, v103
	v_pk_fma_f32 v[50:51], v[44:45], v[46:47], v[78:79]
	v_rcp_f32_e32 v47, v41
	v_lshl_add_u64 v[44:45], s[22:23], 0, v[52:53]
	v_lshl_add_u64 v[44:45], v[44:45], 0, v[144:145]
	global_store_dwordx4 v[44:45], v[48:51], off
	s_nop 1
	v_fma_f32 v48, -v41, v47, 1.0
	v_fmac_f32_e32 v47, v48, v47
	v_mov_b32_e32 v41, v47
	v_rcp_f32_e32 v47, v40
	s_nop 0
	v_fma_f32 v48, -v40, v47, 1.0
	v_fmac_f32_e32 v47, v48, v47
	v_mov_b32_e32 v40, v47
	s_waitcnt vmcnt(10)
	v_lshlrev_b32_e32 v46, 16, v100
	v_and_b32_e32 v47, 0xffff0000, v100
	s_waitcnt vmcnt(9)
	v_pk_fma_f32 v[40:41], v[40:41], v[46:47], v[72:73]
	v_rcp_f32_e32 v47, v43
	s_nop 0
	v_fma_f32 v48, -v43, v47, 1.0
	v_fmac_f32_e32 v47, v48, v47
	v_mov_b32_e32 v43, v47
	v_rcp_f32_e32 v47, v42
	s_nop 0
	v_fma_f32 v48, -v42, v47, 1.0
	v_fmac_f32_e32 v47, v48, v47
	v_mov_b32_e32 v42, v47
	v_lshlrev_b32_e32 v46, 16, v101
	v_and_b32_e32 v47, 0xffff0000, v101
	v_pk_fma_f32 v[42:43], v[42:43], v[46:47], v[74:75]
	global_store_dwordx4 v[44:45], v[40:43], off offset:64
	v_add_u32_e32 v74, 0xb0, v180
	v_ashrrev_i32_e32 v75, 31, v74
	v_rcp_f32_e32 v41, v37
	s_nop 0
	v_fma_f32 v42, -v37, v41, 1.0
	v_fmac_f32_e32 v41, v42, v41
	v_mov_b32_e32 v37, v41
	v_rcp_f32_e32 v41, v36
	s_nop 0
	v_fma_f32 v42, -v36, v41, 1.0
	v_fmac_f32_e32 v41, v42, v41
	v_mov_b32_e32 v36, v41
	s_waitcnt vmcnt(9)
	v_lshlrev_b32_e32 v40, 16, v98
	v_and_b32_e32 v41, 0xffff0000, v98
	s_waitcnt vmcnt(8)
	v_pk_fma_f32 v[36:37], v[36:37], v[40:41], v[68:69]
	v_rcp_f32_e32 v41, v39
	s_nop 0
	v_fma_f32 v42, -v39, v41, 1.0
	v_fmac_f32_e32 v41, v42, v41
	v_mov_b32_e32 v39, v41
	v_rcp_f32_e32 v41, v38
	s_nop 0
	v_fma_f32 v42, -v38, v41, 1.0
	v_fmac_f32_e32 v41, v42, v41
	v_mov_b32_e32 v38, v41
	v_lshlrev_b32_e32 v40, 16, v99
	v_and_b32_e32 v41, 0xffff0000, v99
	v_pk_fma_f32 v[38:39], v[38:39], v[40:41], v[70:71]
	global_store_dwordx4 v[44:45], v[36:39], off offset:512
	s_nop 1
	v_rcp_f32_e32 v37, v33
	s_nop 0
	v_fma_f32 v38, -v33, v37, 1.0
	v_fmac_f32_e32 v37, v38, v37
	v_mov_b32_e32 v33, v37
	v_rcp_f32_e32 v37, v32
	s_nop 0
	v_fma_f32 v38, -v32, v37, 1.0
	v_fmac_f32_e32 v37, v38, v37
	v_mov_b32_e32 v32, v37
	s_waitcnt vmcnt(8)
	v_lshlrev_b32_e32 v36, 16, v96
	v_and_b32_e32 v37, 0xffff0000, v96
	s_waitcnt vmcnt(7)
	v_pk_fma_f32 v[32:33], v[32:33], v[36:37], v[64:65]
	v_rcp_f32_e32 v37, v35
	s_nop 0
	v_fma_f32 v38, -v35, v37, 1.0
	v_fmac_f32_e32 v37, v38, v37
	v_mov_b32_e32 v35, v37
	v_rcp_f32_e32 v37, v34
	s_nop 0
	v_fma_f32 v38, -v34, v37, 1.0
	v_fmac_f32_e32 v37, v38, v37
	v_mov_b32_e32 v34, v37
	v_lshlrev_b32_e32 v36, 16, v97
	v_and_b32_e32 v37, 0xffff0000, v97
	v_pk_fma_f32 v[34:35], v[34:35], v[36:37], v[66:67]
	global_store_dwordx4 v[44:45], v[32:35], off offset:576
	s_nop 0
	s_nop 0
	v_lshlrev_b64 v[32:33], 10, v[82:83]
	v_lshl_add_u64 v[32:33], v[32:33], 0, v[166:167]
	v_lshlrev_b64 v[34:35], 1, v[32:33]
	v_lshl_add_u64 v[36:37], s[40:41], 0, v[34:35]
	global_load_dwordx2 v[80:81], v[36:37], off
	v_lshl_add_u64 v[32:33], v[32:33], 2, s[22:23]
	global_load_dwordx4 v[60:63], v[32:33], off
	v_or_b32_e32 v36, 32, v34
	v_mov_b32_e32 v37, v35
	v_lshl_add_u64 v[36:37], s[40:41], 0, v[36:37]
	global_load_dwordx2 v[78:79], v[36:37], off
	global_load_dwordx4 v[56:59], v[32:33], off offset:64
	v_mov_b32_e32 v29, v85
	v_rcp_f32_e32 v85, v28
	v_or_b32_e32 v36, 0x100, v34
	v_mov_b32_e32 v37, v35
	v_lshl_add_u64 v[36:37], s[40:41], 0, v[36:37]
	v_fma_f32 v86, -v28, v85, 1.0
	v_fmac_f32_e32 v85, v86, v85
	v_mov_b32_e32 v28, v85
	v_or_b32_e32 v34, 0x120, v34
	global_load_dwordx2 v[76:77], v[36:37], off
	global_load_dwordx4 v[52:55], v[32:33], off offset:512
	v_lshl_add_u64 v[34:35], s[40:41], 0, v[34:35]
	global_load_dwordx2 v[72:73], v[34:35], off
	global_load_dwordx4 v[48:51], v[32:33], off offset:576
	v_lshlrev_b64 v[32:33], 10, v[74:75]
	v_lshl_add_u64 v[32:33], v[32:33], 0, v[166:167]
	v_lshlrev_b64 v[34:35], 1, v[32:33]
	v_lshl_add_u64 v[36:37], s[40:41], 0, v[34:35]
	global_load_dwordx2 v[70:71], v[36:37], off
	v_or_b32_e32 v36, 32, v34
	v_mov_b32_e32 v37, v35
	v_lshl_add_u64 v[32:33], v[32:33], 2, s[22:23]
	v_lshl_add_u64 v[36:37], s[40:41], 0, v[36:37]
	v_lshlrev_b64 v[82:83], 12, v[82:83]
	global_load_dwordx4 v[44:47], v[32:33], off
	global_load_dwordx2 v[68:69], v[36:37], off
	global_load_dwordx4 v[40:43], v[32:33], off offset:64
	v_or_b32_e32 v36, 0x100, v34
	v_mov_b32_e32 v37, v35
	v_or_b32_e32 v34, 0x120, v34
	v_lshl_add_u64 v[36:37], s[40:41], 0, v[36:37]
	v_lshl_add_u64 v[34:35], s[40:41], 0, v[34:35]
	global_load_dwordx2 v[66:67], v[36:37], off
	s_nop 0
	global_load_dwordx4 v[36:39], v[32:33], off offset:512
	global_load_dwordx2 v[64:65], v[34:35], off
	s_nop 0
	global_load_dwordx4 v[32:35], v[32:33], off offset:576
	s_waitcnt vmcnt(15)
; DEV float bflo(unsigned w) { return __uint_as_float(w << 16); }
; DEV float bfhi(unsigned w) { return __uint_as_float(w & 0xffff0000u); }
; DEV float sigmoidf_(float x) { return 1.0f / (1.0f + __expf(-x)); }
; #define PG8_BAR __builtin_amdgcn_s_barrier()
; template <class Epi, bool SEQ>
; DEV void gemm_phase(PG8_LAS unsigned char* lds, const Gemm g, const Epi& E) {
;     ...
;     if (!keep) E(acc, cur, wr, wc, fr, fq);
;     if (!has_next) break;
;     if (!keep) {
; #pragma unroll
;       for (int a = 0; a < 2; ++a)
; #pragma unroll
;         for (int b = 0; b < 2; ++b)
; #pragma unroll
;           for (int m = 0; m < 4; ++m)
; #pragma unroll
;             for (int n = 0; n < 2; ++n) acc[a][b][m][n] = (f32x4){0.f, 0.f, 0.f, 0.f};
;     }
;     cur = nxt; cA = nA; cB = nB; ++ui;
;     if (wr == 1) PG8_BAR;
;   DEV void operator()(const f32x4 (&acc)[2][2][4][2], const Unit& u, int wr, int wc, int fr, int fq) const {
;     ...
;               const f32x4 v = acc[ai][bj][mp * 2 + mm][n];
;               f32x4 x = xv[mm][bj][n]; const u32x2 w = pw[mm][bj][n];
;               x[0] += sigmoidf_(v[0]) * bflo(w.x); x[1] += sigmoidf_(v[1]) * bfhi(w.x); x[2] += sigmoidf_(v[2]) * bflo(w.y); x[3] += sigmoidf_(v[3]) * bfhi(w.y);
;               *(f32x4*)(X + o) = x;
;             }
;         asm volatile("" ::: "memory");
;       }
;   }
	v_lshlrev_b32_e32 v84, 16, v80
	v_and_b32_e32 v85, 0xffff0000, v80
	s_waitcnt vmcnt(14)
	v_pk_fma_f32 v[60:61], v[28:29], v[84:85], v[60:61]
	v_mul_f32_e32 v28, 0xbfb8aa3b, v30
	v_mul_f32_e32 v29, 0xbfb8aa3b, v31
	v_exp_f32_e32 v28, v28
	v_exp_f32_e32 v29, v29
	s_nop 0
	v_pk_add_f32 v[28:29], v[28:29], 1.0 op_sel_hi:[1,0]
	s_nop 0
	v_rcp_f32_e32 v31, v29
	s_nop 0
	v_fma_f32 v80, -v29, v31, 1.0
	v_fmac_f32_e32 v31, v80, v31
	v_mov_b32_e32 v29, v31
	v_rcp_f32_e32 v31, v28
	s_nop 0
	v_fma_f32 v80, -v28, v31, 1.0
	v_fmac_f32_e32 v31, v80, v31
	v_mov_b32_e32 v28, v31
	v_lshlrev_b32_e32 v30, 16, v81
	v_and_b32_e32 v31, 0xffff0000, v81
	v_pk_fma_f32 v[62:63], v[28:29], v[30:31], v[62:63]
	v_rcp_f32_e32 v31, v25
	v_lshl_add_u64 v[28:29], s[22:23], 0, v[82:83]
	v_lshl_add_u64 v[28:29], v[28:29], 0, v[144:145]
	global_store_dwordx4 v[28:29], v[60:63], off
	s_nop 1
	v_fma_f32 v60, -v25, v31, 1.0
	v_fmac_f32_e32 v31, v60, v31
	v_mov_b32_e32 v25, v31
	v_rcp_f32_e32 v31, v24
	s_nop 0
	v_fma_f32 v60, -v24, v31, 1.0
	v_fmac_f32_e32 v31, v60, v31
	v_mov_b32_e32 v24, v31
	s_waitcnt vmcnt(14)
	v_lshlrev_b32_e32 v30, 16, v78
	v_and_b32_e32 v31, 0xffff0000, v78
	s_waitcnt vmcnt(13)
	v_pk_fma_f32 v[24:25], v[24:25], v[30:31], v[56:57]
	v_rcp_f32_e32 v31, v27
	s_nop 0
	v_fma_f32 v56, -v27, v31, 1.0
	v_fmac_f32_e32 v31, v56, v31
	v_mov_b32_e32 v27, v31
	v_rcp_f32_e32 v31, v26
	s_nop 0
	v_fma_f32 v56, -v26, v31, 1.0
	v_fmac_f32_e32 v31, v56, v31
	v_mov_b32_e32 v26, v31
	v_lshlrev_b32_e32 v30, 16, v79
	v_and_b32_e32 v31, 0xffff0000, v79
	v_pk_fma_f32 v[26:27], v[26:27], v[30:31], v[58:59]
	global_store_dwordx4 v[28:29], v[24:27], off offset:64
	s_nop 1
	v_rcp_f32_e32 v25, v21
	s_nop 0
	v_fma_f32 v26, -v21, v25, 1.0
	v_fmac_f32_e32 v25, v26, v25
	v_mov_b32_e32 v21, v25
	v_rcp_f32_e32 v25, v20
	s_nop 0
	v_fma_f32 v26, -v20, v25, 1.0
	v_fmac_f32_e32 v25, v26, v25
	v_mov_b32_e32 v20, v25
	s_waitcnt vmcnt(13)
	v_lshlrev_b32_e32 v24, 16, v76
	v_and_b32_e32 v25, 0xffff0000, v76
	s_waitcnt vmcnt(12)
	v_pk_fma_f32 v[20:21], v[20:21], v[24:25], v[52:53]
	v_rcp_f32_e32 v25, v23
	s_nop 0
	v_fma_f32 v26, -v23, v25, 1.0
	v_fmac_f32_e32 v25, v26, v25
	v_mov_b32_e32 v23, v25
	v_rcp_f32_e32 v25, v22
	s_nop 0
	v_fma_f32 v26, -v22, v25, 1.0
	v_fmac_f32_e32 v25, v26, v25
	v_mov_b32_e32 v22, v25
	v_lshlrev_b32_e32 v24, 16, v77
	v_and_b32_e32 v25, 0xffff0000, v77
	v_pk_fma_f32 v[22:23], v[22:23], v[24:25], v[54:55]
	global_store_dwordx4 v[28:29], v[20:23], off offset:512
	s_nop 1
	v_rcp_f32_e32 v21, v17
	s_nop 0
	v_fma_f32 v22, -v17, v21, 1.0
	v_fmac_f32_e32 v21, v22, v21
	v_mov_b32_e32 v17, v21
	v_rcp_f32_e32 v21, v16
	s_nop 0
	v_fma_f32 v22, -v16, v21, 1.0
	v_fmac_f32_e32 v21, v22, v21
	v_mov_b32_e32 v16, v21
	s_waitcnt vmcnt(12)
	v_lshlrev_b32_e32 v20, 16, v72
	v_and_b32_e32 v21, 0xffff0000, v72
	s_waitcnt vmcnt(11)
	v_pk_fma_f32 v[16:17], v[16:17], v[20:21], v[48:49]
	v_rcp_f32_e32 v21, v19
	s_nop 0
	v_fma_f32 v22, -v19, v21, 1.0
	v_fmac_f32_e32 v21, v22, v21
	v_mov_b32_e32 v19, v21
	v_rcp_f32_e32 v21, v18
	s_nop 0
	v_fma_f32 v22, -v18, v21, 1.0
	v_fmac_f32_e32 v21, v22, v21
	v_mov_b32_e32 v18, v21
	v_lshlrev_b32_e32 v20, 16, v73
	v_and_b32_e32 v21, 0xffff0000, v73
	v_pk_fma_f32 v[18:19], v[18:19], v[20:21], v[50:51]
	global_store_dwordx4 v[28:29], v[16:19], off offset:576
	v_lshlrev_b64 v[20:21], 12, v[74:75]
	s_nop 0
	v_rcp_f32_e32 v17, v13
	s_nop 0
	v_fma_f32 v18, -v13, v17, 1.0
	v_fmac_f32_e32 v17, v18, v17
	v_mov_b32_e32 v13, v17
	v_rcp_f32_e32 v17, v12
	s_nop 0
	v_fma_f32 v18, -v12, v17, 1.0
	v_fmac_f32_e32 v17, v18, v17
	v_mov_b32_e32 v12, v17
	s_waitcnt vmcnt(11)
	v_lshlrev_b32_e32 v16, 16, v70
	v_and_b32_e32 v17, 0xffff0000, v70
	s_waitcnt vmcnt(10)
	v_pk_fma_f32 v[16:17], v[12:13], v[16:17], v[44:45]
	v_mul_f32_e32 v12, 0xbfb8aa3b, v14
	v_mul_f32_e32 v13, 0xbfb8aa3b, v15
	v_exp_f32_e32 v12, v12
	v_exp_f32_e32 v13, v13
	s_nop 0
	v_pk_add_f32 v[12:13], v[12:13], 1.0 op_sel_hi:[1,0]
	s_nop 0
	v_rcp_f32_e32 v15, v13
	s_nop 0
	v_fma_f32 v18, -v13, v15, 1.0
	v_fmac_f32_e32 v15, v18, v15
	v_mov_b32_e32 v13, v15
	v_rcp_f32_e32 v15, v12
	s_nop 0
	v_fma_f32 v18, -v12, v15, 1.0
	v_fmac_f32_e32 v15, v18, v15
	v_mov_b32_e32 v12, v15
	v_lshlrev_b32_e32 v14, 16, v71
	v_and_b32_e32 v15, 0xffff0000, v71
	v_pk_fma_f32 v[18:19], v[12:13], v[14:15], v[46:47]
	v_rcp_f32_e32 v15, v9
	v_lshl_add_u64 v[12:13], s[22:23], 0, v[20:21]
	v_lshl_add_u64 v[12:13], v[12:13], 0, v[144:145]
	global_store_dwordx4 v[12:13], v[16:19], off
	s_nop 1
	v_fma_f32 v16, -v9, v15, 1.0
	v_fmac_f32_e32 v15, v16, v15
	v_mov_b32_e32 v9, v15
	v_rcp_f32_e32 v15, v8
	s_nop 0
	v_fma_f32 v16, -v8, v15, 1.0
	v_fmac_f32_e32 v15, v16, v15
	v_mov_b32_e32 v8, v15
	s_waitcnt vmcnt(10)
	v_lshlrev_b32_e32 v14, 16, v68
	v_and_b32_e32 v15, 0xffff0000, v68
	s_waitcnt vmcnt(9)
	v_pk_fma_f32 v[8:9], v[8:9], v[14:15], v[40:41]
	v_rcp_f32_e32 v15, v11
	s_nop 0
	v_fma_f32 v16, -v11, v15, 1.0
	v_fmac_f32_e32 v15, v16, v15
	v_mov_b32_e32 v11, v15
	v_rcp_f32_e32 v15, v10
	s_nop 0
	v_fma_f32 v16, -v10, v15, 1.0
	v_fmac_f32_e32 v15, v16, v15
	v_mov_b32_e32 v10, v15
	v_lshlrev_b32_e32 v14, 16, v69
	v_and_b32_e32 v15, 0xffff0000, v69
	v_pk_fma_f32 v[10:11], v[10:11], v[14:15], v[42:43]
	global_store_dwordx4 v[12:13], v[8:11], off offset:64
	s_nop 1
	v_rcp_f32_e32 v9, v5
	s_nop 0
	v_fma_f32 v10, -v5, v9, 1.0
	v_fmac_f32_e32 v9, v10, v9
	v_mov_b32_e32 v5, v9
	v_rcp_f32_e32 v9, v4
	s_nop 0
	v_fma_f32 v10, -v4, v9, 1.0
	v_fmac_f32_e32 v9, v10, v9
	v_mov_b32_e32 v4, v9
	s_waitcnt vmcnt(9)
	v_lshlrev_b32_e32 v8, 16, v66
	v_and_b32_e32 v9, 0xffff0000, v66
	s_waitcnt vmcnt(8)
	v_pk_fma_f32 v[4:5], v[4:5], v[8:9], v[36:37]
	v_rcp_f32_e32 v9, v7
	s_nop 0
	v_fma_f32 v10, -v7, v9, 1.0
	v_fmac_f32_e32 v9, v10, v9
	v_mov_b32_e32 v7, v9
	v_rcp_f32_e32 v9, v6
	s_nop 0
	v_fma_f32 v10, -v6, v9, 1.0
	v_fmac_f32_e32 v9, v10, v9
	v_mov_b32_e32 v6, v9
	v_lshlrev_b32_e32 v8, 16, v67
	v_and_b32_e32 v9, 0xffff0000, v67
	v_pk_fma_f32 v[6:7], v[6:7], v[8:9], v[38:39]
	global_store_dwordx4 v[12:13], v[4:7], off offset:512
	s_nop 1
	v_rcp_f32_e32 v5, v1
	s_nop 0
	v_fma_f32 v6, -v1, v5, 1.0
	v_fmac_f32_e32 v5, v6, v5
	v_mov_b32_e32 v1, v5
	v_rcp_f32_e32 v5, v0
	s_nop 0
	v_fma_f32 v6, -v0, v5, 1.0
	v_fmac_f32_e32 v5, v6, v5
	v_mov_b32_e32 v0, v5
	s_waitcnt vmcnt(8)
	v_lshlrev_b32_e32 v4, 16, v64
	v_and_b32_e32 v5, 0xffff0000, v64
	s_waitcnt vmcnt(7)
	v_pk_fma_f32 v[0:1], v[0:1], v[4:5], v[32:33]
	v_rcp_f32_e32 v5, v3
	s_nop 0
	v_fma_f32 v6, -v3, v5, 1.0
	v_fmac_f32_e32 v5, v6, v5
	v_mov_b32_e32 v3, v5
	v_rcp_f32_e32 v5, v2
	s_mov_b64 s[2:3], -1
	v_fma_f32 v6, -v2, v5, 1.0
	v_fmac_f32_e32 v5, v6, v5
	v_mov_b32_e32 v2, v5
	v_lshlrev_b32_e32 v4, 16, v65
	v_and_b32_e32 v5, 0xffff0000, v65
	v_pk_fma_f32 v[2:3], v[2:3], v[4:5], v[34:35]
	global_store_dwordx4 v[12:13], v[0:3], off offset:576
	s_andn2_b64 vcc, exec, s[62:63]
	s_cbranch_vccnz .LBB0_122
	s_andn2_b64 vcc, exec, s[54:55]
	s_cbranch_vccnz .LBB0_121
	s_barrier
	s_branch .LBB0_121

; DEV float bflo(unsigned w) { return __uint_as_float(w << 16); }
; DEV float bfhi(unsigned w) { return __uint_as_float(w & 0xffff0000u); }
; #define RS_(xa, xb) ((1.0f + one * __expf(-(xb))) * __builtin_amdgcn_rcpf(1.0f + __expf(-(xa))))
;   DEV bool rescale(f32x4 (&acc)[2][2][4][2], const Unit& u, int wr, int wc, int fr, int fq) const {
;     const int row0 = u.pm * BM + wr * 64 + fr, col0 = u.pn * BM + wc * 32 + 8 * fq;
;     const bool lastseg = u.seg == 2;
;     const int sb = lastseg ? 2 : u.seg + 1;
;     const float one = lastseg ? 0.f : 1.f;
; #pragma unroll
;     for (int ai = 0; ai < 2; ++ai)
; #pragma unroll
;       for (int m = 0; m < 4; ++m) {
;         const size_t r = (size_t)(row0 + ai * HALF + m * 16);
; #pragma unroll
;         for (int bj = 0; bj < 2; ++bj) {
;           const int c = col0 + bj * HALF;
;           const u32x4 ga = *(const u32x4*)(Z + r * NIN + GT + u.seg * D + c);
;           const u32x4 gb = *(const u32x4*)(Z + r * NIN + GT + sb * D + c);
;     ...
;           acc[ai][bj][m][0][0] *= RS_(bflo(ga.x), bflo(gb.x)); acc[ai][bj][m][0][1] *= RS_(bfhi(ga.x), bfhi(gb.x));
;           acc[ai][bj][m][0][2] *= RS_(bflo(ga.y), bflo(gb.y)); acc[ai][bj][m][0][3] *= RS_(bfhi(ga.y), bfhi(gb.y));
;           acc[ai][bj][m][1][0] *= RS_(bflo(ga.z), bflo(gb.z)); acc[ai][bj][m][1][1] *= RS_(bfhi(ga.z), bfhi(gb.z));
;           acc[ai][bj][m][1][2] *= RS_(bflo(ga.w), bflo(gb.w)); acc[ai][bj][m][1][3] *= RS_(bfhi(ga.w), bfhi(gb.w));
.LBB0_320:
	v_lshl_add_u32 v144, s49, 8, v147
	v_lshl_or_b32 v145, s50, 8, v163
	v_mov_b64_e32 v[218:219], s[30:31]
	s_lshl_b32 s18, s48, 11
	s_add_i32 s18, s18, 0x1e00
	s_mov_b32 s19, 0
	v_lshlrev_b32_e32 v145, 1, v145
	v_mad_i64_i32 v[142:143], s[26:27], v144, s95, v[218:219]
	s_mov_b32 s20, 0x36000
	s_mov_b32 s21, 0
	v_lshl_add_u64 v[142:143], v[142:143], 0, s[18:19]
	s_mov_b32 s26, 0x10e000
	s_mov_b32 s27, 0
	v_add_co_u32_e32 v218, vcc, v142, v145
	s_nop 1
	v_addc_co_u32_e32 v219, vcc, 0, v143, vcc
	s_cmp_eq_u32 s48, 2
	s_cselect_b64 s[0:1], -1, 0
	s_cbranch_scc1 .Lp4epi_last
	global_load_dwordx4 v[180:183], v[218:219], off
	global_load_dwordx4 v[188:191], v[218:219], off offset:2048
	global_load_dwordx4 v[184:187], v[218:219], off offset:256
	global_load_dwordx4 v[192:195], v[218:219], off offset:2304
	v_lshl_add_u64 v[218:219], v[218:219], 0, s[20:21]
	global_load_dwordx4 v[196:199], v[218:219], off
	global_load_dwordx4 v[224:227], v[218:219], off offset:2048
	global_load_dwordx4 v[220:223], v[218:219], off offset:256
	global_load_dwordx4 v[228:231], v[218:219], off offset:2304
	v_lshl_add_u64 v[218:219], v[218:219], 0, s[20:21]
	global_load_dwordx4 v[232:235], v[218:219], off
	global_load_dwordx4 v[240:243], v[218:219], off offset:2048
	global_load_dwordx4 v[236:239], v[218:219], off offset:256
	global_load_dwordx4 v[148:151], v[218:219], off offset:2304
	v_lshl_add_u64 v[218:219], v[218:219], 0, s[20:21]
	s_waitcnt vmcnt(8)
	v_lshlrev_b32_e32 v128, 16, v180
	v_and_b32_e32 v180, 0xffff0000, v180
	v_lshlrev_b32_e32 v152, 16, v188
	v_and_b32_e32 v188, 0xffff0000, v188
	v_lshlrev_b32_e32 v129, 16, v181
	v_and_b32_e32 v181, 0xffff0000, v181
	v_lshlrev_b32_e32 v153, 16, v189
	v_and_b32_e32 v189, 0xffff0000, v189
	v_lshlrev_b32_e32 v130, 16, v182
	v_and_b32_e32 v182, 0xffff0000, v182
	v_lshlrev_b32_e32 v154, 16, v190
	v_and_b32_e32 v190, 0xffff0000, v190
	v_lshlrev_b32_e32 v131, 16, v183
	v_and_b32_e32 v183, 0xffff0000, v183
	v_lshlrev_b32_e32 v155, 16, v191
	v_and_b32_e32 v191, 0xffff0000, v191
	v_mul_f32_e32 v128, 0xbfb8aa3b, v128
	v_mul_f32_e32 v180, 0xbfb8aa3b, v180
	v_mul_f32_e32 v152, 0xbfb8aa3b, v152
	v_mul_f32_e32 v188, 0xbfb8aa3b, v188
	v_mul_f32_e32 v129, 0xbfb8aa3b, v129
	v_mul_f32_e32 v181, 0xbfb8aa3b, v181
	v_mul_f32_e32 v153, 0xbfb8aa3b, v153
	v_mul_f32_e32 v189, 0xbfb8aa3b, v189
	v_mul_f32_e32 v130, 0xbfb8aa3b, v130
	v_mul_f32_e32 v182, 0xbfb8aa3b, v182
	v_mul_f32_e32 v154, 0xbfb8aa3b, v154
	v_mul_f32_e32 v190, 0xbfb8aa3b, v190
	v_mul_f32_e32 v131, 0xbfb8aa3b, v131
	v_mul_f32_e32 v183, 0xbfb8aa3b, v183
	v_mul_f32_e32 v155, 0xbfb8aa3b, v155
	v_mul_f32_e32 v191, 0xbfb8aa3b, v191
	v_exp_f32_e32 v128, v128
	v_exp_f32_e32 v180, v180
	v_exp_f32_e32 v152, v152
	v_exp_f32_e32 v188, v188
	v_exp_f32_e32 v129, v129
	v_exp_f32_e32 v181, v181
	v_exp_f32_e32 v153, v153
	v_exp_f32_e32 v189, v189
	v_exp_f32_e32 v130, v130
	v_exp_f32_e32 v182, v182
	v_exp_f32_e32 v154, v154
	v_exp_f32_e32 v190, v190
	v_exp_f32_e32 v131, v131
	v_exp_f32_e32 v183, v183
	v_exp_f32_e32 v155, v155
	v_exp_f32_e32 v191, v191
	v_add_f32_e32 v128, 1.0, v128
	v_add_f32_e32 v180, 1.0, v180
	v_add_f32_e32 v152, 1.0, v152
	v_add_f32_e32 v188, 1.0, v188
	v_add_f32_e32 v129, 1.0, v129
	v_add_f32_e32 v181, 1.0, v181
	v_add_f32_e32 v153, 1.0, v153
	v_add_f32_e32 v189, 1.0, v189
	v_add_f32_e32 v130, 1.0, v130
	v_add_f32_e32 v182, 1.0, v182
	v_add_f32_e32 v154, 1.0, v154
	v_add_f32_e32 v190, 1.0, v190
	v_add_f32_e32 v131, 1.0, v131
	v_add_f32_e32 v183, 1.0, v183
	v_add_f32_e32 v155, 1.0, v155
	v_add_f32_e32 v191, 1.0, v191
	v_rcp_f32_e32 v128, v128
	v_rcp_f32_e32 v180, v180
	v_rcp_f32_e32 v129, v129
	v_rcp_f32_e32 v181, v181
	v_rcp_f32_e32 v130, v130
	v_rcp_f32_e32 v182, v182
	v_rcp_f32_e32 v131, v131
	v_rcp_f32_e32 v183, v183
	v_mul_f32_e32 v128, v128, v152
	v_mul_f32_e32 v180, v180, v188
	v_mul_f32_e32 v129, v129, v153
	v_mul_f32_e32 v181, v181, v189
	v_mul_f32_e32 v130, v130, v154
	v_mul_f32_e32 v182, v182, v190
	v_mul_f32_e32 v131, v131, v155
	v_mul_f32_e32 v183, v183, v191
	v_mul_f32_e32 v124, v124, v128
	v_mul_f32_e32 v125, v125, v180
	v_mul_f32_e32 v126, v126, v129
	v_mul_f32_e32 v127, v127, v181
	v_mul_f32_e32 v120, v120, v130
	v_mul_f32_e32 v121, v121, v182
	v_mul_f32_e32 v122, v122, v131
	v_mul_f32_e32 v123, v123, v183
	v_lshlrev_b32_e32 v128, 16, v184
	v_and_b32_e32 v184, 0xffff0000, v184
	v_lshlrev_b32_e32 v152, 16, v192
	v_and_b32_e32 v192, 0xffff0000, v192
	v_lshlrev_b32_e32 v129, 16, v185
	v_and_b32_e32 v185, 0xffff0000, v185
	v_lshlrev_b32_e32 v153, 16, v193
	v_and_b32_e32 v193, 0xffff0000, v193
	v_lshlrev_b32_e32 v130, 16, v186
	v_and_b32_e32 v186, 0xffff0000, v186
	v_lshlrev_b32_e32 v154, 16, v194
	v_and_b32_e32 v194, 0xffff0000, v194
	v_lshlrev_b32_e32 v131, 16, v187
	v_and_b32_e32 v187, 0xffff0000, v187
	v_lshlrev_b32_e32 v155, 16, v195
	v_and_b32_e32 v195, 0xffff0000, v195
	v_mul_f32_e32 v128, 0xbfb8aa3b, v128
	v_mul_f32_e32 v184, 0xbfb8aa3b, v184
	v_mul_f32_e32 v152, 0xbfb8aa3b, v152
	v_mul_f32_e32 v192, 0xbfb8aa3b, v192
	v_mul_f32_e32 v129, 0xbfb8aa3b, v129
	v_mul_f32_e32 v185, 0xbfb8aa3b, v185
	v_mul_f32_e32 v153, 0xbfb8aa3b, v153
	v_mul_f32_e32 v193, 0xbfb8aa3b, v193
	v_mul_f32_e32 v130, 0xbfb8aa3b, v130
	v_mul_f32_e32 v186, 0xbfb8aa3b, v186
	v_mul_f32_e32 v154, 0xbfb8aa3b, v154
	v_mul_f32_e32 v194, 0xbfb8aa3b, v194
	v_mul_f32_e32 v131, 0xbfb8aa3b, v131
	v_mul_f32_e32 v187, 0xbfb8aa3b, v187
	v_mul_f32_e32 v155, 0xbfb8aa3b, v155
	v_mul_f32_e32 v195, 0xbfb8aa3b, v195
	v_exp_f32_e32 v128, v128
	v_exp_f32_e32 v184, v184
	v_exp_f32_e32 v152, v152
	v_exp_f32_e32 v192, v192
	v_exp_f32_e32 v129, v129
	v_exp_f32_e32 v185, v185
	v_exp_f32_e32 v153, v153
; DEV float bflo(unsigned w) { return __uint_as_float(w << 16); }
; DEV float bfhi(unsigned w) { return __uint_as_float(w & 0xffff0000u); }
; #define RS_(xa, xb) ((1.0f + one * __expf(-(xb))) * __builtin_amdgcn_rcpf(1.0f + __expf(-(xa))))
;   DEV bool rescale(f32x4 (&acc)[2][2][4][2], const Unit& u, int wr, int wc, int fr, int fq) const {
;     ...
;         for (int bj = 0; bj < 2; ++bj) {
;           const int c = col0 + bj * HALF;
;           const u32x4 ga = *(const u32x4*)(Z + r * NIN + GT + u.seg * D + c);
;           const u32x4 gb = *(const u32x4*)(Z + r * NIN + GT + sb * D + c);
;     ...
;           acc[ai][bj][m][0][0] *= RS_(bflo(ga.x), bflo(gb.x)); acc[ai][bj][m][0][1] *= RS_(bfhi(ga.x), bfhi(gb.x));
;           acc[ai][bj][m][0][2] *= RS_(bflo(ga.y), bflo(gb.y)); acc[ai][bj][m][0][3] *= RS_(bfhi(ga.y), bfhi(gb.y));
;           acc[ai][bj][m][1][0] *= RS_(bflo(ga.z), bflo(gb.z)); acc[ai][bj][m][1][1] *= RS_(bfhi(ga.z), bfhi(gb.z));
;           acc[ai][bj][m][1][2] *= RS_(bflo(ga.w), bflo(gb.w)); acc[ai][bj][m][1][3] *= RS_(bfhi(ga.w), bfhi(gb.w));
	v_exp_f32_e32 v193, v193
	v_exp_f32_e32 v130, v130
	v_exp_f32_e32 v186, v186
	v_exp_f32_e32 v154, v154
	v_exp_f32_e32 v194, v194
	v_exp_f32_e32 v131, v131
	v_exp_f32_e32 v187, v187
	v_exp_f32_e32 v155, v155
	v_exp_f32_e32 v195, v195
	v_add_f32_e32 v128, 1.0, v128
	v_add_f32_e32 v184, 1.0, v184
	v_add_f32_e32 v152, 1.0, v152
	v_add_f32_e32 v192, 1.0, v192
	v_add_f32_e32 v129, 1.0, v129
	v_add_f32_e32 v185, 1.0, v185
	v_add_f32_e32 v153, 1.0, v153
	v_add_f32_e32 v193, 1.0, v193
	v_add_f32_e32 v130, 1.0, v130
	v_add_f32_e32 v186, 1.0, v186
	v_add_f32_e32 v154, 1.0, v154
	v_add_f32_e32 v194, 1.0, v194
	v_add_f32_e32 v131, 1.0, v131
	v_add_f32_e32 v187, 1.0, v187
	v_add_f32_e32 v155, 1.0, v155
	v_add_f32_e32 v195, 1.0, v195
	v_rcp_f32_e32 v128, v128
	v_rcp_f32_e32 v184, v184
	v_rcp_f32_e32 v129, v129
	v_rcp_f32_e32 v185, v185
	v_rcp_f32_e32 v130, v130
	v_rcp_f32_e32 v186, v186
	v_rcp_f32_e32 v131, v131
	v_rcp_f32_e32 v187, v187
	v_mul_f32_e32 v128, v128, v152
	v_mul_f32_e32 v184, v184, v192
	v_mul_f32_e32 v129, v129, v153
	v_mul_f32_e32 v185, v185, v193
	v_mul_f32_e32 v130, v130, v154
	v_mul_f32_e32 v186, v186, v194
	v_mul_f32_e32 v131, v131, v155
	v_mul_f32_e32 v187, v187, v195
	v_mul_f32_e32 v92, v92, v128
	v_mul_f32_e32 v93, v93, v184
	v_mul_f32_e32 v94, v94, v129
	v_mul_f32_e32 v95, v95, v185
	v_mul_f32_e32 v88, v88, v130
	v_mul_f32_e32 v89, v89, v186
	v_mul_f32_e32 v90, v90, v131
	v_mul_f32_e32 v91, v91, v187
	global_load_dwordx4 v[180:183], v[218:219], off
	global_load_dwordx4 v[188:191], v[218:219], off offset:2048
	global_load_dwordx4 v[184:187], v[218:219], off offset:256
	global_load_dwordx4 v[192:195], v[218:219], off offset:2304
	v_lshl_add_u64 v[218:219], v[218:219], 0, s[26:27]
	s_waitcnt vmcnt(8)
	v_lshlrev_b32_e32 v128, 16, v196
	v_and_b32_e32 v196, 0xffff0000, v196
	v_lshlrev_b32_e32 v152, 16, v224
	v_and_b32_e32 v224, 0xffff0000, v224
	v_lshlrev_b32_e32 v129, 16, v197
	v_and_b32_e32 v197, 0xffff0000, v197
	v_lshlrev_b32_e32 v153, 16, v225
	v_and_b32_e32 v225, 0xffff0000, v225
	v_lshlrev_b32_e32 v130, 16, v198
	v_and_b32_e32 v198, 0xffff0000, v198
	v_lshlrev_b32_e32 v154, 16, v226
	v_and_b32_e32 v226, 0xffff0000, v226
	v_lshlrev_b32_e32 v131, 16, v199
	v_and_b32_e32 v199, 0xffff0000, v199
	v_lshlrev_b32_e32 v155, 16, v227
	v_and_b32_e32 v227, 0xffff0000, v227
	v_mul_f32_e32 v128, 0xbfb8aa3b, v128
	v_mul_f32_e32 v196, 0xbfb8aa3b, v196
	v_mul_f32_e32 v152, 0xbfb8aa3b, v152
	v_mul_f32_e32 v224, 0xbfb8aa3b, v224
	v_mul_f32_e32 v129, 0xbfb8aa3b, v129
	v_mul_f32_e32 v197, 0xbfb8aa3b, v197
	v_mul_f32_e32 v153, 0xbfb8aa3b, v153
	v_mul_f32_e32 v225, 0xbfb8aa3b, v225
	v_mul_f32_e32 v130, 0xbfb8aa3b, v130
	v_mul_f32_e32 v198, 0xbfb8aa3b, v198
	v_mul_f32_e32 v154, 0xbfb8aa3b, v154
	v_mul_f32_e32 v226, 0xbfb8aa3b, v226
	v_mul_f32_e32 v131, 0xbfb8aa3b, v131
	v_mul_f32_e32 v199, 0xbfb8aa3b, v199
	v_mul_f32_e32 v155, 0xbfb8aa3b, v155
	v_mul_f32_e32 v227, 0xbfb8aa3b, v227
	v_exp_f32_e32 v128, v128
	v_exp_f32_e32 v196, v196
	v_exp_f32_e32 v152, v152
	v_exp_f32_e32 v224, v224
	v_exp_f32_e32 v129, v129
	v_exp_f32_e32 v197, v197
	v_exp_f32_e32 v153, v153
	v_exp_f32_e32 v225, v225
	v_exp_f32_e32 v130, v130
	v_exp_f32_e32 v198, v198
	v_exp_f32_e32 v154, v154
	v_exp_f32_e32 v226, v226
	v_exp_f32_e32 v131, v131
	v_exp_f32_e32 v199, v199
	v_exp_f32_e32 v155, v155
	v_exp_f32_e32 v227, v227
	v_add_f32_e32 v128, 1.0, v128
	v_add_f32_e32 v196, 1.0, v196
	v_add_f32_e32 v152, 1.0, v152
	v_add_f32_e32 v224, 1.0, v224
	v_add_f32_e32 v129, 1.0, v129
	v_add_f32_e32 v197, 1.0, v197
	v_add_f32_e32 v153, 1.0, v153
	v_add_f32_e32 v225, 1.0, v225
	v_add_f32_e32 v130, 1.0, v130
	v_add_f32_e32 v198, 1.0, v198
	v_add_f32_e32 v154, 1.0, v154
	v_add_f32_e32 v226, 1.0, v226
	v_add_f32_e32 v131, 1.0, v131
	v_add_f32_e32 v199, 1.0, v199
	v_add_f32_e32 v155, 1.0, v155
	v_add_f32_e32 v227, 1.0, v227
	v_rcp_f32_e32 v128, v128
	v_rcp_f32_e32 v196, v196
	v_rcp_f32_e32 v129, v129
	v_rcp_f32_e32 v197, v197
	v_rcp_f32_e32 v130, v130
	v_rcp_f32_e32 v198, v198
	v_rcp_f32_e32 v131, v131
	v_rcp_f32_e32 v199, v199
	v_mul_f32_e32 v128, v128, v152
	v_mul_f32_e32 v196, v196, v224
	v_mul_f32_e32 v129, v129, v153
	v_mul_f32_e32 v197, v197, v225
	v_mul_f32_e32 v130, v130, v154
	v_mul_f32_e32 v198, v198, v226
	v_mul_f32_e32 v131, v131, v155
	v_mul_f32_e32 v199, v199, v227
	v_mul_f32_e32 v116, v116, v128
	v_mul_f32_e32 v117, v117, v196
	v_mul_f32_e32 v118, v118, v129
	v_mul_f32_e32 v119, v119, v197
	v_mul_f32_e32 v112, v112, v130
	v_mul_f32_e32 v113, v113, v198
	v_mul_f32_e32 v114, v114, v131
	v_mul_f32_e32 v115, v115, v199
	v_lshlrev_b32_e32 v128, 16, v220
	v_and_b32_e32 v220, 0xffff0000, v220
	v_lshlrev_b32_e32 v152, 16, v228
	v_and_b32_e32 v228, 0xffff0000, v228
	v_lshlrev_b32_e32 v129, 16, v221
	v_and_b32_e32 v221, 0xffff0000, v221
	v_lshlrev_b32_e32 v153, 16, v229
	v_and_b32_e32 v229, 0xffff0000, v229
	v_lshlrev_b32_e32 v130, 16, v222
	v_and_b32_e32 v222, 0xffff0000, v222
	v_lshlrev_b32_e32 v154, 16, v230
	v_and_b32_e32 v230, 0xffff0000, v230
	v_lshlrev_b32_e32 v131, 16, v223
	v_and_b32_e32 v223, 0xffff0000, v223
	v_lshlrev_b32_e32 v155, 16, v231
	v_and_b32_e32 v231, 0xffff0000, v231
	v_mul_f32_e32 v128, 0xbfb8aa3b, v128
	v_mul_f32_e32 v220, 0xbfb8aa3b, v220
	v_mul_f32_e32 v152, 0xbfb8aa3b, v152
	v_mul_f32_e32 v228, 0xbfb8aa3b, v228
	v_mul_f32_e32 v129, 0xbfb8aa3b, v129
	v_mul_f32_e32 v221, 0xbfb8aa3b, v221
	v_mul_f32_e32 v153, 0xbfb8aa3b, v153
	v_mul_f32_e32 v229, 0xbfb8aa3b, v229
	v_mul_f32_e32 v130, 0xbfb8aa3b, v130
	v_mul_f32_e32 v222, 0xbfb8aa3b, v222
	v_mul_f32_e32 v154, 0xbfb8aa3b, v154
	v_mul_f32_e32 v230, 0xbfb8aa3b, v230
	v_mul_f32_e32 v131, 0xbfb8aa3b, v131
; DEV float bflo(unsigned w) { return __uint_as_float(w << 16); }
; DEV float bfhi(unsigned w) { return __uint_as_float(w & 0xffff0000u); }
; #define RS_(xa, xb) ((1.0f + one * __expf(-(xb))) * __builtin_amdgcn_rcpf(1.0f + __expf(-(xa))))
;   DEV bool rescale(f32x4 (&acc)[2][2][4][2], const Unit& u, int wr, int wc, int fr, int fq) const {
;     ...
;         for (int bj = 0; bj < 2; ++bj) {
;           const int c = col0 + bj * HALF;
;           const u32x4 ga = *(const u32x4*)(Z + r * NIN + GT + u.seg * D + c);
;           const u32x4 gb = *(const u32x4*)(Z + r * NIN + GT + sb * D + c);
;     ...
;           acc[ai][bj][m][0][0] *= RS_(bflo(ga.x), bflo(gb.x)); acc[ai][bj][m][0][1] *= RS_(bfhi(ga.x), bfhi(gb.x));
;           acc[ai][bj][m][0][2] *= RS_(bflo(ga.y), bflo(gb.y)); acc[ai][bj][m][0][3] *= RS_(bfhi(ga.y), bfhi(gb.y));
;           acc[ai][bj][m][1][0] *= RS_(bflo(ga.z), bflo(gb.z)); acc[ai][bj][m][1][1] *= RS_(bfhi(ga.z), bfhi(gb.z));
;           acc[ai][bj][m][1][2] *= RS_(bflo(ga.w), bflo(gb.w)); acc[ai][bj][m][1][3] *= RS_(bfhi(ga.w), bfhi(gb.w));
	v_mul_f32_e32 v223, 0xbfb8aa3b, v223
	v_mul_f32_e32 v155, 0xbfb8aa3b, v155
	v_mul_f32_e32 v231, 0xbfb8aa3b, v231
	v_exp_f32_e32 v128, v128
	v_exp_f32_e32 v220, v220
	v_exp_f32_e32 v152, v152
	v_exp_f32_e32 v228, v228
	v_exp_f32_e32 v129, v129
	v_exp_f32_e32 v221, v221
	v_exp_f32_e32 v153, v153
	v_exp_f32_e32 v229, v229
	v_exp_f32_e32 v130, v130
	v_exp_f32_e32 v222, v222
	v_exp_f32_e32 v154, v154
	v_exp_f32_e32 v230, v230
	v_exp_f32_e32 v131, v131
	v_exp_f32_e32 v223, v223
	v_exp_f32_e32 v155, v155
	v_exp_f32_e32 v231, v231
	v_add_f32_e32 v128, 1.0, v128
	v_add_f32_e32 v220, 1.0, v220
	v_add_f32_e32 v152, 1.0, v152
	v_add_f32_e32 v228, 1.0, v228
	v_add_f32_e32 v129, 1.0, v129
	v_add_f32_e32 v221, 1.0, v221
	v_add_f32_e32 v153, 1.0, v153
	v_add_f32_e32 v229, 1.0, v229
	v_add_f32_e32 v130, 1.0, v130
	v_add_f32_e32 v222, 1.0, v222
	v_add_f32_e32 v154, 1.0, v154
	v_add_f32_e32 v230, 1.0, v230
	v_add_f32_e32 v131, 1.0, v131
	v_add_f32_e32 v223, 1.0, v223
	v_add_f32_e32 v155, 1.0, v155
	v_add_f32_e32 v231, 1.0, v231
	v_rcp_f32_e32 v128, v128
	v_rcp_f32_e32 v220, v220
	v_rcp_f32_e32 v129, v129
	v_rcp_f32_e32 v221, v221
	v_rcp_f32_e32 v130, v130
	v_rcp_f32_e32 v222, v222
	v_rcp_f32_e32 v131, v131
	v_rcp_f32_e32 v223, v223
	v_mul_f32_e32 v128, v128, v152
	v_mul_f32_e32 v220, v220, v228
	v_mul_f32_e32 v129, v129, v153
	v_mul_f32_e32 v221, v221, v229
	v_mul_f32_e32 v130, v130, v154
	v_mul_f32_e32 v222, v222, v230
	v_mul_f32_e32 v131, v131, v155
	v_mul_f32_e32 v223, v223, v231
	v_mul_f32_e32 v84, v84, v128
	v_mul_f32_e32 v85, v85, v220
	v_mul_f32_e32 v86, v86, v129
	v_mul_f32_e32 v87, v87, v221
	v_mul_f32_e32 v80, v80, v130
	v_mul_f32_e32 v81, v81, v222
	v_mul_f32_e32 v82, v82, v131
	v_mul_f32_e32 v83, v83, v223
	global_load_dwordx4 v[196:199], v[218:219], off
	global_load_dwordx4 v[224:227], v[218:219], off offset:2048
	global_load_dwordx4 v[220:223], v[218:219], off offset:256
	global_load_dwordx4 v[228:231], v[218:219], off offset:2304
	v_lshl_add_u64 v[218:219], v[218:219], 0, s[20:21]
	s_waitcnt vmcnt(8)
	v_lshlrev_b32_e32 v128, 16, v232
	v_and_b32_e32 v232, 0xffff0000, v232
	v_lshlrev_b32_e32 v152, 16, v240
	v_and_b32_e32 v240, 0xffff0000, v240
	v_lshlrev_b32_e32 v129, 16, v233
	v_and_b32_e32 v233, 0xffff0000, v233
	v_lshlrev_b32_e32 v153, 16, v241
	v_and_b32_e32 v241, 0xffff0000, v241
	v_lshlrev_b32_e32 v130, 16, v234
	v_and_b32_e32 v234, 0xffff0000, v234
	v_lshlrev_b32_e32 v154, 16, v242
	v_and_b32_e32 v242, 0xffff0000, v242
	v_lshlrev_b32_e32 v131, 16, v235
	v_and_b32_e32 v235, 0xffff0000, v235
	v_lshlrev_b32_e32 v155, 16, v243
	v_and_b32_e32 v243, 0xffff0000, v243
	v_mul_f32_e32 v128, 0xbfb8aa3b, v128
	v_mul_f32_e32 v232, 0xbfb8aa3b, v232
	v_mul_f32_e32 v152, 0xbfb8aa3b, v152
	v_mul_f32_e32 v240, 0xbfb8aa3b, v240
	v_mul_f32_e32 v129, 0xbfb8aa3b, v129
	v_mul_f32_e32 v233, 0xbfb8aa3b, v233
	v_mul_f32_e32 v153, 0xbfb8aa3b, v153
	v_mul_f32_e32 v241, 0xbfb8aa3b, v241
	v_mul_f32_e32 v130, 0xbfb8aa3b, v130
	v_mul_f32_e32 v234, 0xbfb8aa3b, v234
	v_mul_f32_e32 v154, 0xbfb8aa3b, v154
	v_mul_f32_e32 v242, 0xbfb8aa3b, v242
	v_mul_f32_e32 v131, 0xbfb8aa3b, v131
	v_mul_f32_e32 v235, 0xbfb8aa3b, v235
	v_mul_f32_e32 v155, 0xbfb8aa3b, v155
	v_mul_f32_e32 v243, 0xbfb8aa3b, v243
	v_exp_f32_e32 v128, v128
	v_exp_f32_e32 v232, v232
	v_exp_f32_e32 v152, v152
	v_exp_f32_e32 v240, v240
	v_exp_f32_e32 v129, v129
	v_exp_f32_e32 v233, v233
	v_exp_f32_e32 v153, v153
	v_exp_f32_e32 v241, v241
	v_exp_f32_e32 v130, v130
	v_exp_f32_e32 v234, v234
	v_exp_f32_e32 v154, v154
	v_exp_f32_e32 v242, v242
	v_exp_f32_e32 v131, v131
	v_exp_f32_e32 v235, v235
	v_exp_f32_e32 v155, v155
	v_exp_f32_e32 v243, v243
	v_add_f32_e32 v128, 1.0, v128
	v_add_f32_e32 v232, 1.0, v232
	v_add_f32_e32 v152, 1.0, v152
	v_add_f32_e32 v240, 1.0, v240
	v_add_f32_e32 v129, 1.0, v129
	v_add_f32_e32 v233, 1.0, v233
	v_add_f32_e32 v153, 1.0, v153
	v_add_f32_e32 v241, 1.0, v241
	v_add_f32_e32 v130, 1.0, v130
	v_add_f32_e32 v234, 1.0, v234
	v_add_f32_e32 v154, 1.0, v154
	v_add_f32_e32 v242, 1.0, v242
	v_add_f32_e32 v131, 1.0, v131
	v_add_f32_e32 v235, 1.0, v235
	v_add_f32_e32 v155, 1.0, v155
	v_add_f32_e32 v243, 1.0, v243
	v_rcp_f32_e32 v128, v128
	v_rcp_f32_e32 v232, v232
	v_rcp_f32_e32 v129, v129
	v_rcp_f32_e32 v233, v233
	v_rcp_f32_e32 v130, v130
	v_rcp_f32_e32 v234, v234
	v_rcp_f32_e32 v131, v131
	v_rcp_f32_e32 v235, v235
	v_mul_f32_e32 v128, v128, v152
	v_mul_f32_e32 v232, v232, v240
	v_mul_f32_e32 v129, v129, v153
	v_mul_f32_e32 v233, v233, v241
	v_mul_f32_e32 v130, v130, v154
	v_mul_f32_e32 v234, v234, v242
	v_mul_f32_e32 v131, v131, v155
	v_mul_f32_e32 v235, v235, v243
	v_mul_f32_e32 v108, v108, v128
	v_mul_f32_e32 v109, v109, v232
	v_mul_f32_e32 v110, v110, v129
	v_mul_f32_e32 v111, v111, v233
	v_mul_f32_e32 v104, v104, v130
	v_mul_f32_e32 v105, v105, v234
	v_mul_f32_e32 v106, v106, v131
	v_mul_f32_e32 v107, v107, v235
	v_lshlrev_b32_e32 v128, 16, v236
	v_and_b32_e32 v236, 0xffff0000, v236
	v_lshlrev_b32_e32 v152, 16, v148
	v_and_b32_e32 v148, 0xffff0000, v148
	v_lshlrev_b32_e32 v129, 16, v237
	v_and_b32_e32 v237, 0xffff0000, v237
	v_lshlrev_b32_e32 v153, 16, v149
	v_and_b32_e32 v149, 0xffff0000, v149
	v_lshlrev_b32_e32 v130, 16, v238
	v_and_b32_e32 v238, 0xffff0000, v238
	v_lshlrev_b32_e32 v154, 16, v150
	v_and_b32_e32 v150, 0xffff0000, v150
	v_lshlrev_b32_e32 v131, 16, v239
	v_and_b32_e32 v239, 0xffff0000, v239
	v_lshlrev_b32_e32 v155, 16, v151
	v_and_b32_e32 v151, 0xffff0000, v151
	v_mul_f32_e32 v128, 0xbfb8aa3b, v128
	v_mul_f32_e32 v236, 0xbfb8aa3b, v236
	v_mul_f32_e32 v152, 0xbfb8aa3b, v152
	v_mul_f32_e32 v148, 0xbfb8aa3b, v148
	v_mul_f32_e32 v129, 0xbfb8aa3b, v129
	v_mul_f32_e32 v237, 0xbfb8aa3b, v237
; DEV float bflo(unsigned w) { return __uint_as_float(w << 16); }
; DEV float bfhi(unsigned w) { return __uint_as_float(w & 0xffff0000u); }
; #define RS_(xa, xb) ((1.0f + one * __expf(-(xb))) * __builtin_amdgcn_rcpf(1.0f + __expf(-(xa))))
;   DEV bool rescale(f32x4 (&acc)[2][2][4][2], const Unit& u, int wr, int wc, int fr, int fq) const {
;     ...
;         for (int bj = 0; bj < 2; ++bj) {
;           const int c = col0 + bj * HALF;
;           const u32x4 ga = *(const u32x4*)(Z + r * NIN + GT + u.seg * D + c);
;           const u32x4 gb = *(const u32x4*)(Z + r * NIN + GT + sb * D + c);
;     ...
;           acc[ai][bj][m][0][0] *= RS_(bflo(ga.x), bflo(gb.x)); acc[ai][bj][m][0][1] *= RS_(bfhi(ga.x), bfhi(gb.x));
;           acc[ai][bj][m][0][2] *= RS_(bflo(ga.y), bflo(gb.y)); acc[ai][bj][m][0][3] *= RS_(bfhi(ga.y), bfhi(gb.y));
;           acc[ai][bj][m][1][0] *= RS_(bflo(ga.z), bflo(gb.z)); acc[ai][bj][m][1][1] *= RS_(bfhi(ga.z), bfhi(gb.z));
;           acc[ai][bj][m][1][2] *= RS_(bflo(ga.w), bflo(gb.w)); acc[ai][bj][m][1][3] *= RS_(bfhi(ga.w), bfhi(gb.w));
	v_mul_f32_e32 v153, 0xbfb8aa3b, v153
	v_mul_f32_e32 v149, 0xbfb8aa3b, v149
	v_mul_f32_e32 v130, 0xbfb8aa3b, v130
	v_mul_f32_e32 v238, 0xbfb8aa3b, v238
	v_mul_f32_e32 v154, 0xbfb8aa3b, v154
	v_mul_f32_e32 v150, 0xbfb8aa3b, v150
	v_mul_f32_e32 v131, 0xbfb8aa3b, v131
	v_mul_f32_e32 v239, 0xbfb8aa3b, v239
	v_mul_f32_e32 v155, 0xbfb8aa3b, v155
	v_mul_f32_e32 v151, 0xbfb8aa3b, v151
	v_exp_f32_e32 v128, v128
	v_exp_f32_e32 v236, v236
	v_exp_f32_e32 v152, v152
	v_exp_f32_e32 v148, v148
	v_exp_f32_e32 v129, v129
	v_exp_f32_e32 v237, v237
	v_exp_f32_e32 v153, v153
	v_exp_f32_e32 v149, v149
	v_exp_f32_e32 v130, v130
	v_exp_f32_e32 v238, v238
	v_exp_f32_e32 v154, v154
	v_exp_f32_e32 v150, v150
	v_exp_f32_e32 v131, v131
	v_exp_f32_e32 v239, v239
	v_exp_f32_e32 v155, v155
	v_exp_f32_e32 v151, v151
	v_add_f32_e32 v128, 1.0, v128
	v_add_f32_e32 v236, 1.0, v236
	v_add_f32_e32 v152, 1.0, v152
	v_add_f32_e32 v148, 1.0, v148
	v_add_f32_e32 v129, 1.0, v129
	v_add_f32_e32 v237, 1.0, v237
	v_add_f32_e32 v153, 1.0, v153
	v_add_f32_e32 v149, 1.0, v149
	v_add_f32_e32 v130, 1.0, v130
	v_add_f32_e32 v238, 1.0, v238
	v_add_f32_e32 v154, 1.0, v154
	v_add_f32_e32 v150, 1.0, v150
	v_add_f32_e32 v131, 1.0, v131
	v_add_f32_e32 v239, 1.0, v239
	v_add_f32_e32 v155, 1.0, v155
	v_add_f32_e32 v151, 1.0, v151
	v_rcp_f32_e32 v128, v128
	v_rcp_f32_e32 v236, v236
	v_rcp_f32_e32 v129, v129
	v_rcp_f32_e32 v237, v237
	v_rcp_f32_e32 v130, v130
	v_rcp_f32_e32 v238, v238
	v_rcp_f32_e32 v131, v131
	v_rcp_f32_e32 v239, v239
	v_mul_f32_e32 v128, v128, v152
	v_mul_f32_e32 v236, v236, v148
	v_mul_f32_e32 v129, v129, v153
	v_mul_f32_e32 v237, v237, v149
	v_mul_f32_e32 v130, v130, v154
	v_mul_f32_e32 v238, v238, v150
	v_mul_f32_e32 v131, v131, v155
	v_mul_f32_e32 v239, v239, v151
	v_mul_f32_e32 v76, v76, v128
	v_mul_f32_e32 v77, v77, v236
	v_mul_f32_e32 v78, v78, v129
	v_mul_f32_e32 v79, v79, v237
	v_mul_f32_e32 v72, v72, v130
	v_mul_f32_e32 v73, v73, v238
	v_mul_f32_e32 v74, v74, v131
	v_mul_f32_e32 v75, v75, v239
	global_load_dwordx4 v[232:235], v[218:219], off
	global_load_dwordx4 v[240:243], v[218:219], off offset:2048
	global_load_dwordx4 v[236:239], v[218:219], off offset:256
	global_load_dwordx4 v[148:151], v[218:219], off offset:2304
	v_lshl_add_u64 v[218:219], v[218:219], 0, s[20:21]
	s_waitcnt vmcnt(8)
	v_lshlrev_b32_e32 v128, 16, v180
	v_and_b32_e32 v180, 0xffff0000, v180
	v_lshlrev_b32_e32 v152, 16, v188
	v_and_b32_e32 v188, 0xffff0000, v188
	v_lshlrev_b32_e32 v129, 16, v181
	v_and_b32_e32 v181, 0xffff0000, v181
	v_lshlrev_b32_e32 v153, 16, v189
	v_and_b32_e32 v189, 0xffff0000, v189
	v_lshlrev_b32_e32 v130, 16, v182
	v_and_b32_e32 v182, 0xffff0000, v182
	v_lshlrev_b32_e32 v154, 16, v190
	v_and_b32_e32 v190, 0xffff0000, v190
	v_lshlrev_b32_e32 v131, 16, v183
	v_and_b32_e32 v183, 0xffff0000, v183
	v_lshlrev_b32_e32 v155, 16, v191
	v_and_b32_e32 v191, 0xffff0000, v191
	v_mul_f32_e32 v128, 0xbfb8aa3b, v128
	v_mul_f32_e32 v180, 0xbfb8aa3b, v180
	v_mul_f32_e32 v152, 0xbfb8aa3b, v152
	v_mul_f32_e32 v188, 0xbfb8aa3b, v188
	v_mul_f32_e32 v129, 0xbfb8aa3b, v129
	v_mul_f32_e32 v181, 0xbfb8aa3b, v181
	v_mul_f32_e32 v153, 0xbfb8aa3b, v153
	v_mul_f32_e32 v189, 0xbfb8aa3b, v189
	v_mul_f32_e32 v130, 0xbfb8aa3b, v130
	v_mul_f32_e32 v182, 0xbfb8aa3b, v182
	v_mul_f32_e32 v154, 0xbfb8aa3b, v154
	v_mul_f32_e32 v190, 0xbfb8aa3b, v190
	v_mul_f32_e32 v131, 0xbfb8aa3b, v131
	v_mul_f32_e32 v183, 0xbfb8aa3b, v183
	v_mul_f32_e32 v155, 0xbfb8aa3b, v155
	v_mul_f32_e32 v191, 0xbfb8aa3b, v191
	v_exp_f32_e32 v128, v128
	v_exp_f32_e32 v180, v180
	v_exp_f32_e32 v152, v152
	v_exp_f32_e32 v188, v188
	v_exp_f32_e32 v129, v129
	v_exp_f32_e32 v181, v181
	v_exp_f32_e32 v153, v153
	v_exp_f32_e32 v189, v189
	v_exp_f32_e32 v130, v130
	v_exp_f32_e32 v182, v182
	v_exp_f32_e32 v154, v154
	v_exp_f32_e32 v190, v190
	v_exp_f32_e32 v131, v131
	v_exp_f32_e32 v183, v183
	v_exp_f32_e32 v155, v155
	v_exp_f32_e32 v191, v191
	v_add_f32_e32 v128, 1.0, v128
	v_add_f32_e32 v180, 1.0, v180
	v_add_f32_e32 v152, 1.0, v152
	v_add_f32_e32 v188, 1.0, v188
	v_add_f32_e32 v129, 1.0, v129
	v_add_f32_e32 v181, 1.0, v181
	v_add_f32_e32 v153, 1.0, v153
	v_add_f32_e32 v189, 1.0, v189
	v_add_f32_e32 v130, 1.0, v130
	v_add_f32_e32 v182, 1.0, v182
	v_add_f32_e32 v154, 1.0, v154
	v_add_f32_e32 v190, 1.0, v190
	v_add_f32_e32 v131, 1.0, v131
	v_add_f32_e32 v183, 1.0, v183
	v_add_f32_e32 v155, 1.0, v155
	v_add_f32_e32 v191, 1.0, v191
	v_rcp_f32_e32 v128, v128
	v_rcp_f32_e32 v180, v180
	v_rcp_f32_e32 v129, v129
	v_rcp_f32_e32 v181, v181
	v_rcp_f32_e32 v130, v130
	v_rcp_f32_e32 v182, v182
	v_rcp_f32_e32 v131, v131
	v_rcp_f32_e32 v183, v183
	v_mul_f32_e32 v128, v128, v152
	v_mul_f32_e32 v180, v180, v188
	v_mul_f32_e32 v129, v129, v153
	v_mul_f32_e32 v181, v181, v189
	v_mul_f32_e32 v130, v130, v154
	v_mul_f32_e32 v182, v182, v190
	v_mul_f32_e32 v131, v131, v155
	v_mul_f32_e32 v183, v183, v191
	v_mul_f32_e32 v100, v100, v128
	v_mul_f32_e32 v101, v101, v180
	v_mul_f32_e32 v102, v102, v129
	v_mul_f32_e32 v103, v103, v181
	v_mul_f32_e32 v96, v96, v130
	v_mul_f32_e32 v97, v97, v182
	v_mul_f32_e32 v98, v98, v131
	v_mul_f32_e32 v99, v99, v183
	v_lshlrev_b32_e32 v128, 16, v184
	v_and_b32_e32 v184, 0xffff0000, v184
	v_lshlrev_b32_e32 v152, 16, v192
	v_and_b32_e32 v192, 0xffff0000, v192
	v_lshlrev_b32_e32 v129, 16, v185
	v_and_b32_e32 v185, 0xffff0000, v185
	v_lshlrev_b32_e32 v153, 16, v193
	v_and_b32_e32 v193, 0xffff0000, v193
	v_lshlrev_b32_e32 v130, 16, v186
	v_and_b32_e32 v186, 0xffff0000, v186
	v_lshlrev_b32_e32 v154, 16, v194
	v_and_b32_e32 v194, 0xffff0000, v194
	v_lshlrev_b32_e32 v131, 16, v187
	v_and_b32_e32 v187, 0xffff0000, v187
	v_lshlrev_b32_e32 v155, 16, v195
; DEV float bflo(unsigned w) { return __uint_as_float(w << 16); }
; DEV float bfhi(unsigned w) { return __uint_as_float(w & 0xffff0000u); }
; #define RS_(xa, xb) ((1.0f + one * __expf(-(xb))) * __builtin_amdgcn_rcpf(1.0f + __expf(-(xa))))
;   DEV bool rescale(f32x4 (&acc)[2][2][4][2], const Unit& u, int wr, int wc, int fr, int fq) const {
;     ...
;         for (int bj = 0; bj < 2; ++bj) {
;           const int c = col0 + bj * HALF;
;           const u32x4 ga = *(const u32x4*)(Z + r * NIN + GT + u.seg * D + c);
;           const u32x4 gb = *(const u32x4*)(Z + r * NIN + GT + sb * D + c);
;     ...
;           acc[ai][bj][m][0][0] *= RS_(bflo(ga.x), bflo(gb.x)); acc[ai][bj][m][0][1] *= RS_(bfhi(ga.x), bfhi(gb.x));
;           acc[ai][bj][m][0][2] *= RS_(bflo(ga.y), bflo(gb.y)); acc[ai][bj][m][0][3] *= RS_(bfhi(ga.y), bfhi(gb.y));
;           acc[ai][bj][m][1][0] *= RS_(bflo(ga.z), bflo(gb.z)); acc[ai][bj][m][1][1] *= RS_(bfhi(ga.z), bfhi(gb.z));
;           acc[ai][bj][m][1][2] *= RS_(bflo(ga.w), bflo(gb.w)); acc[ai][bj][m][1][3] *= RS_(bfhi(ga.w), bfhi(gb.w));
	v_and_b32_e32 v195, 0xffff0000, v195
	v_mul_f32_e32 v128, 0xbfb8aa3b, v128
	v_mul_f32_e32 v184, 0xbfb8aa3b, v184
	v_mul_f32_e32 v152, 0xbfb8aa3b, v152
	v_mul_f32_e32 v192, 0xbfb8aa3b, v192
	v_mul_f32_e32 v129, 0xbfb8aa3b, v129
	v_mul_f32_e32 v185, 0xbfb8aa3b, v185
	v_mul_f32_e32 v153, 0xbfb8aa3b, v153
	v_mul_f32_e32 v193, 0xbfb8aa3b, v193
	v_mul_f32_e32 v130, 0xbfb8aa3b, v130
	v_mul_f32_e32 v186, 0xbfb8aa3b, v186
	v_mul_f32_e32 v154, 0xbfb8aa3b, v154
	v_mul_f32_e32 v194, 0xbfb8aa3b, v194
	v_mul_f32_e32 v131, 0xbfb8aa3b, v131
	v_mul_f32_e32 v187, 0xbfb8aa3b, v187
	v_mul_f32_e32 v155, 0xbfb8aa3b, v155
	v_mul_f32_e32 v195, 0xbfb8aa3b, v195
	v_exp_f32_e32 v128, v128
	v_exp_f32_e32 v184, v184
	v_exp_f32_e32 v152, v152
	v_exp_f32_e32 v192, v192
	v_exp_f32_e32 v129, v129
	v_exp_f32_e32 v185, v185
	v_exp_f32_e32 v153, v153
	v_exp_f32_e32 v193, v193
	v_exp_f32_e32 v130, v130
	v_exp_f32_e32 v186, v186
	v_exp_f32_e32 v154, v154
	v_exp_f32_e32 v194, v194
	v_exp_f32_e32 v131, v131
	v_exp_f32_e32 v187, v187
	v_exp_f32_e32 v155, v155
	v_exp_f32_e32 v195, v195
	v_add_f32_e32 v128, 1.0, v128
	v_add_f32_e32 v184, 1.0, v184
	v_add_f32_e32 v152, 1.0, v152
	v_add_f32_e32 v192, 1.0, v192
	v_add_f32_e32 v129, 1.0, v129
	v_add_f32_e32 v185, 1.0, v185
	v_add_f32_e32 v153, 1.0, v153
	v_add_f32_e32 v193, 1.0, v193
	v_add_f32_e32 v130, 1.0, v130
	v_add_f32_e32 v186, 1.0, v186
	v_add_f32_e32 v154, 1.0, v154
	v_add_f32_e32 v194, 1.0, v194
	v_add_f32_e32 v131, 1.0, v131
	v_add_f32_e32 v187, 1.0, v187
	v_add_f32_e32 v155, 1.0, v155
	v_add_f32_e32 v195, 1.0, v195
	v_rcp_f32_e32 v128, v128
	v_rcp_f32_e32 v184, v184
	v_rcp_f32_e32 v129, v129
	v_rcp_f32_e32 v185, v185
	v_rcp_f32_e32 v130, v130
	v_rcp_f32_e32 v186, v186
	v_rcp_f32_e32 v131, v131
	v_rcp_f32_e32 v187, v187
	v_mul_f32_e32 v128, v128, v152
	v_mul_f32_e32 v184, v184, v192
	v_mul_f32_e32 v129, v129, v153
	v_mul_f32_e32 v185, v185, v193
	v_mul_f32_e32 v130, v130, v154
	v_mul_f32_e32 v186, v186, v194
	v_mul_f32_e32 v131, v131, v155
	v_mul_f32_e32 v187, v187, v195
	v_mul_f32_e32 v68, v68, v128
	v_mul_f32_e32 v69, v69, v184
	v_mul_f32_e32 v70, v70, v129
	v_mul_f32_e32 v71, v71, v185
	v_mul_f32_e32 v64, v64, v130
	v_mul_f32_e32 v65, v65, v186
	v_mul_f32_e32 v66, v66, v131
	v_mul_f32_e32 v67, v67, v187
	global_load_dwordx4 v[180:183], v[218:219], off
	global_load_dwordx4 v[188:191], v[218:219], off offset:2048
	global_load_dwordx4 v[184:187], v[218:219], off offset:256
	global_load_dwordx4 v[192:195], v[218:219], off offset:2304
	v_lshl_add_u64 v[218:219], v[218:219], 0, s[20:21]
	s_waitcnt vmcnt(8)
	v_lshlrev_b32_e32 v128, 16, v196
	v_and_b32_e32 v196, 0xffff0000, v196
	v_lshlrev_b32_e32 v152, 16, v224
	v_and_b32_e32 v224, 0xffff0000, v224
	v_lshlrev_b32_e32 v129, 16, v197
	v_and_b32_e32 v197, 0xffff0000, v197
	v_lshlrev_b32_e32 v153, 16, v225
	v_and_b32_e32 v225, 0xffff0000, v225
	v_lshlrev_b32_e32 v130, 16, v198
	v_and_b32_e32 v198, 0xffff0000, v198
	v_lshlrev_b32_e32 v154, 16, v226
	v_and_b32_e32 v226, 0xffff0000, v226
	v_lshlrev_b32_e32 v131, 16, v199
	v_and_b32_e32 v199, 0xffff0000, v199
	v_lshlrev_b32_e32 v155, 16, v227
	v_and_b32_e32 v227, 0xffff0000, v227
	v_mul_f32_e32 v128, 0xbfb8aa3b, v128
	v_mul_f32_e32 v196, 0xbfb8aa3b, v196
	v_mul_f32_e32 v152, 0xbfb8aa3b, v152
	v_mul_f32_e32 v224, 0xbfb8aa3b, v224
	v_mul_f32_e32 v129, 0xbfb8aa3b, v129
	v_mul_f32_e32 v197, 0xbfb8aa3b, v197
	v_mul_f32_e32 v153, 0xbfb8aa3b, v153
	v_mul_f32_e32 v225, 0xbfb8aa3b, v225
	v_mul_f32_e32 v130, 0xbfb8aa3b, v130
	v_mul_f32_e32 v198, 0xbfb8aa3b, v198
	v_mul_f32_e32 v154, 0xbfb8aa3b, v154
	v_mul_f32_e32 v226, 0xbfb8aa3b, v226
	v_mul_f32_e32 v131, 0xbfb8aa3b, v131
	v_mul_f32_e32 v199, 0xbfb8aa3b, v199
	v_mul_f32_e32 v155, 0xbfb8aa3b, v155
	v_mul_f32_e32 v227, 0xbfb8aa3b, v227
	v_exp_f32_e32 v128, v128
	v_exp_f32_e32 v196, v196
	v_exp_f32_e32 v152, v152
	v_exp_f32_e32 v224, v224
	v_exp_f32_e32 v129, v129
	v_exp_f32_e32 v197, v197
	v_exp_f32_e32 v153, v153
	v_exp_f32_e32 v225, v225
	v_exp_f32_e32 v130, v130
	v_exp_f32_e32 v198, v198
	v_exp_f32_e32 v154, v154
	v_exp_f32_e32 v226, v226
	v_exp_f32_e32 v131, v131
	v_exp_f32_e32 v199, v199
	v_exp_f32_e32 v155, v155
	v_exp_f32_e32 v227, v227
	v_add_f32_e32 v128, 1.0, v128
	v_add_f32_e32 v196, 1.0, v196
	v_add_f32_e32 v152, 1.0, v152
	v_add_f32_e32 v224, 1.0, v224
	v_add_f32_e32 v129, 1.0, v129
	v_add_f32_e32 v197, 1.0, v197
	v_add_f32_e32 v153, 1.0, v153
	v_add_f32_e32 v225, 1.0, v225
	v_add_f32_e32 v130, 1.0, v130
	v_add_f32_e32 v198, 1.0, v198
	v_add_f32_e32 v154, 1.0, v154
	v_add_f32_e32 v226, 1.0, v226
	v_add_f32_e32 v131, 1.0, v131
	v_add_f32_e32 v199, 1.0, v199
	v_add_f32_e32 v155, 1.0, v155
	v_add_f32_e32 v227, 1.0, v227
	v_rcp_f32_e32 v128, v128
	v_rcp_f32_e32 v196, v196
	v_rcp_f32_e32 v129, v129
	v_rcp_f32_e32 v197, v197
	v_rcp_f32_e32 v130, v130
	v_rcp_f32_e32 v198, v198
	v_rcp_f32_e32 v131, v131
	v_rcp_f32_e32 v199, v199
	v_mul_f32_e32 v128, v128, v152
	v_mul_f32_e32 v196, v196, v224
	v_mul_f32_e32 v129, v129, v153
	v_mul_f32_e32 v197, v197, v225
	v_mul_f32_e32 v130, v130, v154
	v_mul_f32_e32 v198, v198, v226
	v_mul_f32_e32 v131, v131, v155
	v_mul_f32_e32 v199, v199, v227
	v_mul_f32_e32 v60, v60, v128
	v_mul_f32_e32 v61, v61, v196
	v_mul_f32_e32 v62, v62, v129
	v_mul_f32_e32 v63, v63, v197
	v_mul_f32_e32 v56, v56, v130
	v_mul_f32_e32 v57, v57, v198
	v_mul_f32_e32 v58, v58, v131
	v_mul_f32_e32 v59, v59, v199
	v_lshlrev_b32_e32 v128, 16, v220
	v_and_b32_e32 v220, 0xffff0000, v220
	v_lshlrev_b32_e32 v152, 16, v228
	v_and_b32_e32 v228, 0xffff0000, v228
	v_lshlrev_b32_e32 v129, 16, v221
	v_and_b32_e32 v221, 0xffff0000, v221
	v_lshlrev_b32_e32 v153, 16, v229
	v_and_b32_e32 v229, 0xffff0000, v229
; DEV float bflo(unsigned w) { return __uint_as_float(w << 16); }
; DEV float bfhi(unsigned w) { return __uint_as_float(w & 0xffff0000u); }
; #define RS_(xa, xb) ((1.0f + one * __expf(-(xb))) * __builtin_amdgcn_rcpf(1.0f + __expf(-(xa))))
;   DEV bool rescale(f32x4 (&acc)[2][2][4][2], const Unit& u, int wr, int wc, int fr, int fq) const {
;     ...
;         for (int bj = 0; bj < 2; ++bj) {
;           const int c = col0 + bj * HALF;
;           const u32x4 ga = *(const u32x4*)(Z + r * NIN + GT + u.seg * D + c);
;           const u32x4 gb = *(const u32x4*)(Z + r * NIN + GT + sb * D + c);
;     ...
;           acc[ai][bj][m][0][0] *= RS_(bflo(ga.x), bflo(gb.x)); acc[ai][bj][m][0][1] *= RS_(bfhi(ga.x), bfhi(gb.x));
;           acc[ai][bj][m][0][2] *= RS_(bflo(ga.y), bflo(gb.y)); acc[ai][bj][m][0][3] *= RS_(bfhi(ga.y), bfhi(gb.y));
;           acc[ai][bj][m][1][0] *= RS_(bflo(ga.z), bflo(gb.z)); acc[ai][bj][m][1][1] *= RS_(bfhi(ga.z), bfhi(gb.z));
;           acc[ai][bj][m][1][2] *= RS_(bflo(ga.w), bflo(gb.w)); acc[ai][bj][m][1][3] *= RS_(bfhi(ga.w), bfhi(gb.w));
	v_lshlrev_b32_e32 v130, 16, v222
	v_and_b32_e32 v222, 0xffff0000, v222
	v_lshlrev_b32_e32 v154, 16, v230
	v_and_b32_e32 v230, 0xffff0000, v230
	v_lshlrev_b32_e32 v131, 16, v223
	v_and_b32_e32 v223, 0xffff0000, v223
	v_lshlrev_b32_e32 v155, 16, v231
	v_and_b32_e32 v231, 0xffff0000, v231
	v_mul_f32_e32 v128, 0xbfb8aa3b, v128
	v_mul_f32_e32 v220, 0xbfb8aa3b, v220
	v_mul_f32_e32 v152, 0xbfb8aa3b, v152
	v_mul_f32_e32 v228, 0xbfb8aa3b, v228
	v_mul_f32_e32 v129, 0xbfb8aa3b, v129
	v_mul_f32_e32 v221, 0xbfb8aa3b, v221
	v_mul_f32_e32 v153, 0xbfb8aa3b, v153
	v_mul_f32_e32 v229, 0xbfb8aa3b, v229
	v_mul_f32_e32 v130, 0xbfb8aa3b, v130
	v_mul_f32_e32 v222, 0xbfb8aa3b, v222
	v_mul_f32_e32 v154, 0xbfb8aa3b, v154
	v_mul_f32_e32 v230, 0xbfb8aa3b, v230
	v_mul_f32_e32 v131, 0xbfb8aa3b, v131
	v_mul_f32_e32 v223, 0xbfb8aa3b, v223
	v_mul_f32_e32 v155, 0xbfb8aa3b, v155
	v_mul_f32_e32 v231, 0xbfb8aa3b, v231
	v_exp_f32_e32 v128, v128
	v_exp_f32_e32 v220, v220
	v_exp_f32_e32 v152, v152
	v_exp_f32_e32 v228, v228
	v_exp_f32_e32 v129, v129
	v_exp_f32_e32 v221, v221
	v_exp_f32_e32 v153, v153
	v_exp_f32_e32 v229, v229
	v_exp_f32_e32 v130, v130
	v_exp_f32_e32 v222, v222
	v_exp_f32_e32 v154, v154
	v_exp_f32_e32 v230, v230
	v_exp_f32_e32 v131, v131
	v_exp_f32_e32 v223, v223
	v_exp_f32_e32 v155, v155
	v_exp_f32_e32 v231, v231
	v_add_f32_e32 v128, 1.0, v128
	v_add_f32_e32 v220, 1.0, v220
	v_add_f32_e32 v152, 1.0, v152
	v_add_f32_e32 v228, 1.0, v228
	v_add_f32_e32 v129, 1.0, v129
	v_add_f32_e32 v221, 1.0, v221
	v_add_f32_e32 v153, 1.0, v153
	v_add_f32_e32 v229, 1.0, v229
	v_add_f32_e32 v130, 1.0, v130
	v_add_f32_e32 v222, 1.0, v222
	v_add_f32_e32 v154, 1.0, v154
	v_add_f32_e32 v230, 1.0, v230
	v_add_f32_e32 v131, 1.0, v131
	v_add_f32_e32 v223, 1.0, v223
	v_add_f32_e32 v155, 1.0, v155
	v_add_f32_e32 v231, 1.0, v231
	v_rcp_f32_e32 v128, v128
	v_rcp_f32_e32 v220, v220
	v_rcp_f32_e32 v129, v129
	v_rcp_f32_e32 v221, v221
	v_rcp_f32_e32 v130, v130
	v_rcp_f32_e32 v222, v222
	v_rcp_f32_e32 v131, v131
	v_rcp_f32_e32 v223, v223
	v_mul_f32_e32 v128, v128, v152
	v_mul_f32_e32 v220, v220, v228
	v_mul_f32_e32 v129, v129, v153
	v_mul_f32_e32 v221, v221, v229
	v_mul_f32_e32 v130, v130, v154
	v_mul_f32_e32 v222, v222, v230
	v_mul_f32_e32 v131, v131, v155
	v_mul_f32_e32 v223, v223, v231
	v_mul_f32_e32 v28, v28, v128
	v_mul_f32_e32 v29, v29, v220
	v_mul_f32_e32 v30, v30, v129
	v_mul_f32_e32 v31, v31, v221
	v_mul_f32_e32 v24, v24, v130
	v_mul_f32_e32 v25, v25, v222
	v_mul_f32_e32 v26, v26, v131
	v_mul_f32_e32 v27, v27, v223
	global_load_dwordx4 v[196:199], v[218:219], off
	global_load_dwordx4 v[224:227], v[218:219], off offset:2048
	global_load_dwordx4 v[220:223], v[218:219], off offset:256
	global_load_dwordx4 v[228:231], v[218:219], off offset:2304
	s_waitcnt vmcnt(8)
	v_lshlrev_b32_e32 v128, 16, v232
	v_and_b32_e32 v232, 0xffff0000, v232
	v_lshlrev_b32_e32 v152, 16, v240
	v_and_b32_e32 v240, 0xffff0000, v240
	v_lshlrev_b32_e32 v129, 16, v233
	v_and_b32_e32 v233, 0xffff0000, v233
	v_lshlrev_b32_e32 v153, 16, v241
	v_and_b32_e32 v241, 0xffff0000, v241
	v_lshlrev_b32_e32 v130, 16, v234
	v_and_b32_e32 v234, 0xffff0000, v234
	v_lshlrev_b32_e32 v154, 16, v242
	v_and_b32_e32 v242, 0xffff0000, v242
	v_lshlrev_b32_e32 v131, 16, v235
	v_and_b32_e32 v235, 0xffff0000, v235
	v_lshlrev_b32_e32 v155, 16, v243
	v_and_b32_e32 v243, 0xffff0000, v243
	v_mul_f32_e32 v128, 0xbfb8aa3b, v128
	v_mul_f32_e32 v232, 0xbfb8aa3b, v232
	v_mul_f32_e32 v152, 0xbfb8aa3b, v152
	v_mul_f32_e32 v240, 0xbfb8aa3b, v240
	v_mul_f32_e32 v129, 0xbfb8aa3b, v129
	v_mul_f32_e32 v233, 0xbfb8aa3b, v233
	v_mul_f32_e32 v153, 0xbfb8aa3b, v153
	v_mul_f32_e32 v241, 0xbfb8aa3b, v241
	v_mul_f32_e32 v130, 0xbfb8aa3b, v130
	v_mul_f32_e32 v234, 0xbfb8aa3b, v234
	v_mul_f32_e32 v154, 0xbfb8aa3b, v154
	v_mul_f32_e32 v242, 0xbfb8aa3b, v242
	v_mul_f32_e32 v131, 0xbfb8aa3b, v131
	v_mul_f32_e32 v235, 0xbfb8aa3b, v235
	v_mul_f32_e32 v155, 0xbfb8aa3b, v155
	v_mul_f32_e32 v243, 0xbfb8aa3b, v243
	v_exp_f32_e32 v128, v128
	v_exp_f32_e32 v232, v232
	v_exp_f32_e32 v152, v152
	v_exp_f32_e32 v240, v240
	v_exp_f32_e32 v129, v129
	v_exp_f32_e32 v233, v233
	v_exp_f32_e32 v153, v153
	v_exp_f32_e32 v241, v241
	v_exp_f32_e32 v130, v130
	v_exp_f32_e32 v234, v234
	v_exp_f32_e32 v154, v154
	v_exp_f32_e32 v242, v242
	v_exp_f32_e32 v131, v131
	v_exp_f32_e32 v235, v235
	v_exp_f32_e32 v155, v155
	v_exp_f32_e32 v243, v243
	v_add_f32_e32 v128, 1.0, v128
	v_add_f32_e32 v232, 1.0, v232
	v_add_f32_e32 v152, 1.0, v152
	v_add_f32_e32 v240, 1.0, v240
	v_add_f32_e32 v129, 1.0, v129
	v_add_f32_e32 v233, 1.0, v233
	v_add_f32_e32 v153, 1.0, v153
	v_add_f32_e32 v241, 1.0, v241
	v_add_f32_e32 v130, 1.0, v130
	v_add_f32_e32 v234, 1.0, v234
	v_add_f32_e32 v154, 1.0, v154
	v_add_f32_e32 v242, 1.0, v242
	v_add_f32_e32 v131, 1.0, v131
	v_add_f32_e32 v235, 1.0, v235
	v_add_f32_e32 v155, 1.0, v155
	v_add_f32_e32 v243, 1.0, v243
	v_rcp_f32_e32 v128, v128
	v_rcp_f32_e32 v232, v232
	v_rcp_f32_e32 v129, v129
	v_rcp_f32_e32 v233, v233
	v_rcp_f32_e32 v130, v130
	v_rcp_f32_e32 v234, v234
	v_rcp_f32_e32 v131, v131
	v_rcp_f32_e32 v235, v235
	v_mul_f32_e32 v128, v128, v152
	v_mul_f32_e32 v232, v232, v240
	v_mul_f32_e32 v129, v129, v153
	v_mul_f32_e32 v233, v233, v241
	v_mul_f32_e32 v130, v130, v154
	v_mul_f32_e32 v234, v234, v242
	v_mul_f32_e32 v131, v131, v155
	v_mul_f32_e32 v235, v235, v243
	v_mul_f32_e32 v52, v52, v128
	v_mul_f32_e32 v53, v53, v232
	v_mul_f32_e32 v54, v54, v129
	v_mul_f32_e32 v55, v55, v233
	v_mul_f32_e32 v48, v48, v130
	v_mul_f32_e32 v49, v49, v234
	v_mul_f32_e32 v50, v50, v131
	v_mul_f32_e32 v51, v51, v235
	v_lshlrev_b32_e32 v128, 16, v236
	v_and_b32_e32 v236, 0xffff0000, v236
; DEV float bflo(unsigned w) { return __uint_as_float(w << 16); }
; DEV float bfhi(unsigned w) { return __uint_as_float(w & 0xffff0000u); }
; #define RS_(xa, xb) ((1.0f + one * __expf(-(xb))) * __builtin_amdgcn_rcpf(1.0f + __expf(-(xa))))
;   DEV bool rescale(f32x4 (&acc)[2][2][4][2], const Unit& u, int wr, int wc, int fr, int fq) const {
;     ...
;         for (int bj = 0; bj < 2; ++bj) {
;           const int c = col0 + bj * HALF;
;           const u32x4 ga = *(const u32x4*)(Z + r * NIN + GT + u.seg * D + c);
;           const u32x4 gb = *(const u32x4*)(Z + r * NIN + GT + sb * D + c);
;     ...
;           acc[ai][bj][m][0][0] *= RS_(bflo(ga.x), bflo(gb.x)); acc[ai][bj][m][0][1] *= RS_(bfhi(ga.x), bfhi(gb.x));
;           acc[ai][bj][m][0][2] *= RS_(bflo(ga.y), bflo(gb.y)); acc[ai][bj][m][0][3] *= RS_(bfhi(ga.y), bfhi(gb.y));
;           acc[ai][bj][m][1][0] *= RS_(bflo(ga.z), bflo(gb.z)); acc[ai][bj][m][1][1] *= RS_(bfhi(ga.z), bfhi(gb.z));
;           acc[ai][bj][m][1][2] *= RS_(bflo(ga.w), bflo(gb.w)); acc[ai][bj][m][1][3] *= RS_(bfhi(ga.w), bfhi(gb.w));
	v_lshlrev_b32_e32 v152, 16, v148
	v_and_b32_e32 v148, 0xffff0000, v148
	v_lshlrev_b32_e32 v129, 16, v237
	v_and_b32_e32 v237, 0xffff0000, v237
	v_lshlrev_b32_e32 v153, 16, v149
	v_and_b32_e32 v149, 0xffff0000, v149
	v_lshlrev_b32_e32 v130, 16, v238
	v_and_b32_e32 v238, 0xffff0000, v238
	v_lshlrev_b32_e32 v154, 16, v150
	v_and_b32_e32 v150, 0xffff0000, v150
	v_lshlrev_b32_e32 v131, 16, v239
	v_and_b32_e32 v239, 0xffff0000, v239
	v_lshlrev_b32_e32 v155, 16, v151
	v_and_b32_e32 v151, 0xffff0000, v151
	v_mul_f32_e32 v128, 0xbfb8aa3b, v128
	v_mul_f32_e32 v236, 0xbfb8aa3b, v236
	v_mul_f32_e32 v152, 0xbfb8aa3b, v152
	v_mul_f32_e32 v148, 0xbfb8aa3b, v148
	v_mul_f32_e32 v129, 0xbfb8aa3b, v129
	v_mul_f32_e32 v237, 0xbfb8aa3b, v237
	v_mul_f32_e32 v153, 0xbfb8aa3b, v153
	v_mul_f32_e32 v149, 0xbfb8aa3b, v149
	v_mul_f32_e32 v130, 0xbfb8aa3b, v130
	v_mul_f32_e32 v238, 0xbfb8aa3b, v238
	v_mul_f32_e32 v154, 0xbfb8aa3b, v154
	v_mul_f32_e32 v150, 0xbfb8aa3b, v150
	v_mul_f32_e32 v131, 0xbfb8aa3b, v131
	v_mul_f32_e32 v239, 0xbfb8aa3b, v239
	v_mul_f32_e32 v155, 0xbfb8aa3b, v155
	v_mul_f32_e32 v151, 0xbfb8aa3b, v151
	v_exp_f32_e32 v128, v128
	v_exp_f32_e32 v236, v236
	v_exp_f32_e32 v152, v152
	v_exp_f32_e32 v148, v148
	v_exp_f32_e32 v129, v129
	v_exp_f32_e32 v237, v237
	v_exp_f32_e32 v153, v153
	v_exp_f32_e32 v149, v149
	v_exp_f32_e32 v130, v130
	v_exp_f32_e32 v238, v238
	v_exp_f32_e32 v154, v154
	v_exp_f32_e32 v150, v150
	v_exp_f32_e32 v131, v131
	v_exp_f32_e32 v239, v239
	v_exp_f32_e32 v155, v155
	v_exp_f32_e32 v151, v151
	v_add_f32_e32 v128, 1.0, v128
	v_add_f32_e32 v236, 1.0, v236
	v_add_f32_e32 v152, 1.0, v152
	v_add_f32_e32 v148, 1.0, v148
	v_add_f32_e32 v129, 1.0, v129
	v_add_f32_e32 v237, 1.0, v237
	v_add_f32_e32 v153, 1.0, v153
	v_add_f32_e32 v149, 1.0, v149
	v_add_f32_e32 v130, 1.0, v130
	v_add_f32_e32 v238, 1.0, v238
	v_add_f32_e32 v154, 1.0, v154
	v_add_f32_e32 v150, 1.0, v150
	v_add_f32_e32 v131, 1.0, v131
	v_add_f32_e32 v239, 1.0, v239
	v_add_f32_e32 v155, 1.0, v155
	v_add_f32_e32 v151, 1.0, v151
	v_rcp_f32_e32 v128, v128
	v_rcp_f32_e32 v236, v236
	v_rcp_f32_e32 v129, v129
	v_rcp_f32_e32 v237, v237
	v_rcp_f32_e32 v130, v130
	v_rcp_f32_e32 v238, v238
	v_rcp_f32_e32 v131, v131
	v_rcp_f32_e32 v239, v239
	v_mul_f32_e32 v128, v128, v152
	v_mul_f32_e32 v236, v236, v148
	v_mul_f32_e32 v129, v129, v153
	v_mul_f32_e32 v237, v237, v149
	v_mul_f32_e32 v130, v130, v154
	v_mul_f32_e32 v238, v238, v150
	v_mul_f32_e32 v131, v131, v155
	v_mul_f32_e32 v239, v239, v151
	v_mul_f32_e32 v20, v20, v128
	v_mul_f32_e32 v21, v21, v236
	v_mul_f32_e32 v22, v22, v129
	v_mul_f32_e32 v23, v23, v237
	v_mul_f32_e32 v16, v16, v130
	v_mul_f32_e32 v17, v17, v238
	v_mul_f32_e32 v18, v18, v131
	v_mul_f32_e32 v19, v19, v239
	s_waitcnt vmcnt(4)
	v_lshlrev_b32_e32 v128, 16, v180
	v_and_b32_e32 v180, 0xffff0000, v180
	v_lshlrev_b32_e32 v152, 16, v188
	v_and_b32_e32 v188, 0xffff0000, v188
	v_lshlrev_b32_e32 v129, 16, v181
	v_and_b32_e32 v181, 0xffff0000, v181
	v_lshlrev_b32_e32 v153, 16, v189
	v_and_b32_e32 v189, 0xffff0000, v189
	v_lshlrev_b32_e32 v130, 16, v182
	v_and_b32_e32 v182, 0xffff0000, v182
	v_lshlrev_b32_e32 v154, 16, v190
	v_and_b32_e32 v190, 0xffff0000, v190
	v_lshlrev_b32_e32 v131, 16, v183
	v_and_b32_e32 v183, 0xffff0000, v183
	v_lshlrev_b32_e32 v155, 16, v191
	v_and_b32_e32 v191, 0xffff0000, v191
	v_mul_f32_e32 v128, 0xbfb8aa3b, v128
	v_mul_f32_e32 v180, 0xbfb8aa3b, v180
	v_mul_f32_e32 v152, 0xbfb8aa3b, v152
	v_mul_f32_e32 v188, 0xbfb8aa3b, v188
	v_mul_f32_e32 v129, 0xbfb8aa3b, v129
	v_mul_f32_e32 v181, 0xbfb8aa3b, v181
	v_mul_f32_e32 v153, 0xbfb8aa3b, v153
	v_mul_f32_e32 v189, 0xbfb8aa3b, v189
	v_mul_f32_e32 v130, 0xbfb8aa3b, v130
	v_mul_f32_e32 v182, 0xbfb8aa3b, v182
	v_mul_f32_e32 v154, 0xbfb8aa3b, v154
	v_mul_f32_e32 v190, 0xbfb8aa3b, v190
	v_mul_f32_e32 v131, 0xbfb8aa3b, v131
	v_mul_f32_e32 v183, 0xbfb8aa3b, v183
	v_mul_f32_e32 v155, 0xbfb8aa3b, v155
	v_mul_f32_e32 v191, 0xbfb8aa3b, v191
	v_exp_f32_e32 v128, v128
	v_exp_f32_e32 v180, v180
	v_exp_f32_e32 v152, v152
	v_exp_f32_e32 v188, v188
	v_exp_f32_e32 v129, v129
	v_exp_f32_e32 v181, v181
	v_exp_f32_e32 v153, v153
	v_exp_f32_e32 v189, v189
	v_exp_f32_e32 v130, v130
	v_exp_f32_e32 v182, v182
	v_exp_f32_e32 v154, v154
	v_exp_f32_e32 v190, v190
	v_exp_f32_e32 v131, v131
	v_exp_f32_e32 v183, v183
	v_exp_f32_e32 v155, v155
	v_exp_f32_e32 v191, v191
	v_add_f32_e32 v128, 1.0, v128
	v_add_f32_e32 v180, 1.0, v180
	v_add_f32_e32 v152, 1.0, v152
	v_add_f32_e32 v188, 1.0, v188
	v_add_f32_e32 v129, 1.0, v129
	v_add_f32_e32 v181, 1.0, v181
	v_add_f32_e32 v153, 1.0, v153
	v_add_f32_e32 v189, 1.0, v189
	v_add_f32_e32 v130, 1.0, v130
	v_add_f32_e32 v182, 1.0, v182
	v_add_f32_e32 v154, 1.0, v154
	v_add_f32_e32 v190, 1.0, v190
	v_add_f32_e32 v131, 1.0, v131
	v_add_f32_e32 v183, 1.0, v183
	v_add_f32_e32 v155, 1.0, v155
	v_add_f32_e32 v191, 1.0, v191
	v_rcp_f32_e32 v128, v128
	v_rcp_f32_e32 v180, v180
	v_rcp_f32_e32 v129, v129
	v_rcp_f32_e32 v181, v181
	v_rcp_f32_e32 v130, v130
	v_rcp_f32_e32 v182, v182
	v_rcp_f32_e32 v131, v131
	v_rcp_f32_e32 v183, v183
	v_mul_f32_e32 v128, v128, v152
	v_mul_f32_e32 v180, v180, v188
	v_mul_f32_e32 v129, v129, v153
	v_mul_f32_e32 v181, v181, v189
	v_mul_f32_e32 v130, v130, v154
	v_mul_f32_e32 v182, v182, v190
	v_mul_f32_e32 v131, v131, v155
	v_mul_f32_e32 v183, v183, v191
	v_mul_f32_e32 v44, v44, v128
	v_mul_f32_e32 v45, v45, v180
	v_mul_f32_e32 v46, v46, v129
	v_mul_f32_e32 v47, v47, v181
	v_mul_f32_e32 v40, v40, v130
	v_mul_f32_e32 v41, v41, v182
	v_mul_f32_e32 v42, v42, v131
	v_mul_f32_e32 v43, v43, v183
	v_lshlrev_b32_e32 v128, 16, v184
	v_and_b32_e32 v184, 0xffff0000, v184
	v_lshlrev_b32_e32 v152, 16, v192
; DEV float bflo(unsigned w) { return __uint_as_float(w << 16); }
; DEV float bfhi(unsigned w) { return __uint_as_float(w & 0xffff0000u); }
; #define RS_(xa, xb) ((1.0f + one * __expf(-(xb))) * __builtin_amdgcn_rcpf(1.0f + __expf(-(xa))))
;   DEV bool rescale(f32x4 (&acc)[2][2][4][2], const Unit& u, int wr, int wc, int fr, int fq) const {
;     ...
;         for (int bj = 0; bj < 2; ++bj) {
;           const int c = col0 + bj * HALF;
;           const u32x4 ga = *(const u32x4*)(Z + r * NIN + GT + u.seg * D + c);
;           const u32x4 gb = *(const u32x4*)(Z + r * NIN + GT + sb * D + c);
;     ...
;           acc[ai][bj][m][0][0] *= RS_(bflo(ga.x), bflo(gb.x)); acc[ai][bj][m][0][1] *= RS_(bfhi(ga.x), bfhi(gb.x));
;           acc[ai][bj][m][0][2] *= RS_(bflo(ga.y), bflo(gb.y)); acc[ai][bj][m][0][3] *= RS_(bfhi(ga.y), bfhi(gb.y));
;           acc[ai][bj][m][1][0] *= RS_(bflo(ga.z), bflo(gb.z)); acc[ai][bj][m][1][1] *= RS_(bfhi(ga.z), bfhi(gb.z));
;           acc[ai][bj][m][1][2] *= RS_(bflo(ga.w), bflo(gb.w)); acc[ai][bj][m][1][3] *= RS_(bfhi(ga.w), bfhi(gb.w));
	v_and_b32_e32 v192, 0xffff0000, v192
	v_lshlrev_b32_e32 v129, 16, v185
	v_and_b32_e32 v185, 0xffff0000, v185
	v_lshlrev_b32_e32 v153, 16, v193
	v_and_b32_e32 v193, 0xffff0000, v193
	v_lshlrev_b32_e32 v130, 16, v186
	v_and_b32_e32 v186, 0xffff0000, v186
	v_lshlrev_b32_e32 v154, 16, v194
	v_and_b32_e32 v194, 0xffff0000, v194
	v_lshlrev_b32_e32 v131, 16, v187
	v_and_b32_e32 v187, 0xffff0000, v187
	v_lshlrev_b32_e32 v155, 16, v195
	v_and_b32_e32 v195, 0xffff0000, v195
	v_mul_f32_e32 v128, 0xbfb8aa3b, v128
	v_mul_f32_e32 v184, 0xbfb8aa3b, v184
	v_mul_f32_e32 v152, 0xbfb8aa3b, v152
	v_mul_f32_e32 v192, 0xbfb8aa3b, v192
	v_mul_f32_e32 v129, 0xbfb8aa3b, v129
	v_mul_f32_e32 v185, 0xbfb8aa3b, v185
	v_mul_f32_e32 v153, 0xbfb8aa3b, v153
	v_mul_f32_e32 v193, 0xbfb8aa3b, v193
	v_mul_f32_e32 v130, 0xbfb8aa3b, v130
	v_mul_f32_e32 v186, 0xbfb8aa3b, v186
	v_mul_f32_e32 v154, 0xbfb8aa3b, v154
	v_mul_f32_e32 v194, 0xbfb8aa3b, v194
	v_mul_f32_e32 v131, 0xbfb8aa3b, v131
	v_mul_f32_e32 v187, 0xbfb8aa3b, v187
	v_mul_f32_e32 v155, 0xbfb8aa3b, v155
	v_mul_f32_e32 v195, 0xbfb8aa3b, v195
	v_exp_f32_e32 v128, v128
	v_exp_f32_e32 v184, v184
	v_exp_f32_e32 v152, v152
	v_exp_f32_e32 v192, v192
	v_exp_f32_e32 v129, v129
	v_exp_f32_e32 v185, v185
	v_exp_f32_e32 v153, v153
	v_exp_f32_e32 v193, v193
	v_exp_f32_e32 v130, v130
	v_exp_f32_e32 v186, v186
	v_exp_f32_e32 v154, v154
	v_exp_f32_e32 v194, v194
	v_exp_f32_e32 v131, v131
	v_exp_f32_e32 v187, v187
	v_exp_f32_e32 v155, v155
	v_exp_f32_e32 v195, v195
	v_add_f32_e32 v128, 1.0, v128
	v_add_f32_e32 v184, 1.0, v184
	v_add_f32_e32 v152, 1.0, v152
	v_add_f32_e32 v192, 1.0, v192
	v_add_f32_e32 v129, 1.0, v129
	v_add_f32_e32 v185, 1.0, v185
	v_add_f32_e32 v153, 1.0, v153
	v_add_f32_e32 v193, 1.0, v193
	v_add_f32_e32 v130, 1.0, v130
	v_add_f32_e32 v186, 1.0, v186
	v_add_f32_e32 v154, 1.0, v154
	v_add_f32_e32 v194, 1.0, v194
	v_add_f32_e32 v131, 1.0, v131
	v_add_f32_e32 v187, 1.0, v187
	v_add_f32_e32 v155, 1.0, v155
	v_add_f32_e32 v195, 1.0, v195
	v_rcp_f32_e32 v128, v128
	v_rcp_f32_e32 v184, v184
	v_rcp_f32_e32 v129, v129
	v_rcp_f32_e32 v185, v185
	v_rcp_f32_e32 v130, v130
	v_rcp_f32_e32 v186, v186
	v_rcp_f32_e32 v131, v131
	v_rcp_f32_e32 v187, v187
	v_mul_f32_e32 v128, v128, v152
	v_mul_f32_e32 v184, v184, v192
	v_mul_f32_e32 v129, v129, v153
	v_mul_f32_e32 v185, v185, v193
	v_mul_f32_e32 v130, v130, v154
	v_mul_f32_e32 v186, v186, v194
	v_mul_f32_e32 v131, v131, v155
	v_mul_f32_e32 v187, v187, v195
	v_mul_f32_e32 v12, v12, v128
	v_mul_f32_e32 v13, v13, v184
	v_mul_f32_e32 v14, v14, v129
	v_mul_f32_e32 v15, v15, v185
	v_mul_f32_e32 v8, v8, v130
	v_mul_f32_e32 v9, v9, v186
	v_mul_f32_e32 v10, v10, v131
	v_mul_f32_e32 v11, v11, v187
	s_waitcnt vmcnt(0)
	v_lshlrev_b32_e32 v128, 16, v196
	v_and_b32_e32 v196, 0xffff0000, v196
	v_lshlrev_b32_e32 v152, 16, v224
	v_and_b32_e32 v224, 0xffff0000, v224
	v_lshlrev_b32_e32 v129, 16, v197
	v_and_b32_e32 v197, 0xffff0000, v197
	v_lshlrev_b32_e32 v153, 16, v225
	v_and_b32_e32 v225, 0xffff0000, v225
	v_lshlrev_b32_e32 v130, 16, v198
	v_and_b32_e32 v198, 0xffff0000, v198
	v_lshlrev_b32_e32 v154, 16, v226
	v_and_b32_e32 v226, 0xffff0000, v226
	v_lshlrev_b32_e32 v131, 16, v199
	v_and_b32_e32 v199, 0xffff0000, v199
	v_lshlrev_b32_e32 v155, 16, v227
	v_and_b32_e32 v227, 0xffff0000, v227
	v_mul_f32_e32 v128, 0xbfb8aa3b, v128
	v_mul_f32_e32 v196, 0xbfb8aa3b, v196
	v_mul_f32_e32 v152, 0xbfb8aa3b, v152
	v_mul_f32_e32 v224, 0xbfb8aa3b, v224
	v_mul_f32_e32 v129, 0xbfb8aa3b, v129
	v_mul_f32_e32 v197, 0xbfb8aa3b, v197
	v_mul_f32_e32 v153, 0xbfb8aa3b, v153
	v_mul_f32_e32 v225, 0xbfb8aa3b, v225
	v_mul_f32_e32 v130, 0xbfb8aa3b, v130
	v_mul_f32_e32 v198, 0xbfb8aa3b, v198
	v_mul_f32_e32 v154, 0xbfb8aa3b, v154
	v_mul_f32_e32 v226, 0xbfb8aa3b, v226
	v_mul_f32_e32 v131, 0xbfb8aa3b, v131
	v_mul_f32_e32 v199, 0xbfb8aa3b, v199
	v_mul_f32_e32 v155, 0xbfb8aa3b, v155
	v_mul_f32_e32 v227, 0xbfb8aa3b, v227
	v_exp_f32_e32 v128, v128
	v_exp_f32_e32 v196, v196
	v_exp_f32_e32 v152, v152
	v_exp_f32_e32 v224, v224
	v_exp_f32_e32 v129, v129
	v_exp_f32_e32 v197, v197
	v_exp_f32_e32 v153, v153
	v_exp_f32_e32 v225, v225
	v_exp_f32_e32 v130, v130
	v_exp_f32_e32 v198, v198
	v_exp_f32_e32 v154, v154
	v_exp_f32_e32 v226, v226
	v_exp_f32_e32 v131, v131
	v_exp_f32_e32 v199, v199
	v_exp_f32_e32 v155, v155
	v_exp_f32_e32 v227, v227
	v_add_f32_e32 v128, 1.0, v128
	v_add_f32_e32 v196, 1.0, v196
	v_add_f32_e32 v152, 1.0, v152
	v_add_f32_e32 v224, 1.0, v224
	v_add_f32_e32 v129, 1.0, v129
	v_add_f32_e32 v197, 1.0, v197
	v_add_f32_e32 v153, 1.0, v153
	v_add_f32_e32 v225, 1.0, v225
	v_add_f32_e32 v130, 1.0, v130
	v_add_f32_e32 v198, 1.0, v198
	v_add_f32_e32 v154, 1.0, v154
	v_add_f32_e32 v226, 1.0, v226
	v_add_f32_e32 v131, 1.0, v131
	v_add_f32_e32 v199, 1.0, v199
	v_add_f32_e32 v155, 1.0, v155
	v_add_f32_e32 v227, 1.0, v227
	v_rcp_f32_e32 v128, v128
	v_rcp_f32_e32 v196, v196
	v_rcp_f32_e32 v129, v129
	v_rcp_f32_e32 v197, v197
	v_rcp_f32_e32 v130, v130
	v_rcp_f32_e32 v198, v198
	v_rcp_f32_e32 v131, v131
	v_rcp_f32_e32 v199, v199
	v_mul_f32_e32 v128, v128, v152
	v_mul_f32_e32 v196, v196, v224
	v_mul_f32_e32 v129, v129, v153
	v_mul_f32_e32 v197, v197, v225
	v_mul_f32_e32 v130, v130, v154
	v_mul_f32_e32 v198, v198, v226
	v_mul_f32_e32 v131, v131, v155
	v_mul_f32_e32 v199, v199, v227
	v_mul_f32_e32 v36, v36, v128
	v_mul_f32_e32 v37, v37, v196
	v_mul_f32_e32 v38, v38, v129
	v_mul_f32_e32 v39, v39, v197
	v_mul_f32_e32 v32, v32, v130
	v_mul_f32_e32 v33, v33, v198
	v_mul_f32_e32 v34, v34, v131
	v_mul_f32_e32 v35, v35, v199
	v_lshlrev_b32_e32 v128, 16, v220
	v_and_b32_e32 v220, 0xffff0000, v220
	v_lshlrev_b32_e32 v152, 16, v228
	v_and_b32_e32 v228, 0xffff0000, v228
; DEV unsigned cvt_pk_bf16(float lo, float hi) { const f32x2_ v = {lo, hi}; return __builtin_bit_cast(unsigned, __builtin_convertvector(v, bf16x2n_)); }
; DEV float bflo(unsigned w) { return __uint_as_float(w << 16); }
; DEV float bfhi(unsigned w) { return __uint_as_float(w & 0xffff0000u); }
;   DEV bool rescale(f32x4 (&acc)[2][2][4][2], const Unit& u, int wr, int wc, int fr, int fq) const {
;     const int row0 = u.pm * BM + wr * 64 + fr, col0 = u.pn * BM + wc * 32 + 8 * fq;
;     const bool lastseg = u.seg == 2;
;     const int sb = lastseg ? 2 : u.seg + 1;
;     const float one = lastseg ? 0.f : 1.f;
; #pragma unroll
;     for (int ai = 0; ai < 2; ++ai)
; #pragma unroll
;       for (int m = 0; m < 4; ++m) {
;         const size_t r = (size_t)(row0 + ai * HALF + m * 16);
; #pragma unroll
;         for (int bj = 0; bj < 2; ++bj) {
;           const int c = col0 + bj * HALF;
;           const u32x4 ga = *(const u32x4*)(Z + r * NIN + GT + u.seg * D + c);
;           const u32x4 gb = *(const u32x4*)(Z + r * NIN + GT + sb * D + c);
;     ...
;           acc[ai][bj][m][0][0] *= RS_(bflo(ga.x), bflo(gb.x)); acc[ai][bj][m][0][1] *= RS_(bfhi(ga.x), bfhi(gb.x));
;           acc[ai][bj][m][0][2] *= RS_(bflo(ga.y), bflo(gb.y)); acc[ai][bj][m][0][3] *= RS_(bfhi(ga.y), bfhi(gb.y));
;           acc[ai][bj][m][1][0] *= RS_(bflo(ga.z), bflo(gb.z)); acc[ai][bj][m][1][1] *= RS_(bfhi(ga.z), bfhi(gb.z));
;           acc[ai][bj][m][1][2] *= RS_(bflo(ga.w), bflo(gb.w)); acc[ai][bj][m][1][3] *= RS_(bfhi(ga.w), bfhi(gb.w));
;     ...
;           asm volatile("" ::: "memory");
;         }
;       }
;     return !lastseg;
;   }
;   DEV void operator()(const f32x4 (&acc)[2][2][4][2], const Unit& u, int wr, int wc, int fr, int fq) const {
;     const int row0 = u.pm * BM + wr * 64 + fr, col0 = u.pn * BM + wc * 32 + 8 * fq;
; #pragma unroll
;     for (int ai = 0; ai < 2; ++ai)
; #pragma unroll
;       for (int m = 0; m < 4; ++m) {
;         bf16_t* rowp = H + (size_t)(row0 + ai * HALF + m * 16) * D + col0;
; #pragma unroll
;         for (int bj = 0; bj < 2; ++bj) {
;           const f32x4 v0 = acc[ai][bj][m][0], v1 = acc[ai][bj][m][1];
;           u32x4 w; w.x = cvt_pk_bf16(v0[0], v0[1]); w.y = cvt_pk_bf16(v0[2], v0[3]); w.z = cvt_pk_bf16(v1[0], v1[1]); w.w = cvt_pk_bf16(v1[2], v1[3]);
;           *(u32x4*)(rowp + bj * HALF) = w;
;         }
;       }
;   }
	v_lshlrev_b32_e32 v129, 16, v221
	v_and_b32_e32 v221, 0xffff0000, v221
	v_lshlrev_b32_e32 v153, 16, v229
	v_and_b32_e32 v229, 0xffff0000, v229
	v_lshlrev_b32_e32 v130, 16, v222
	v_and_b32_e32 v222, 0xffff0000, v222
	v_lshlrev_b32_e32 v154, 16, v230
	v_and_b32_e32 v230, 0xffff0000, v230
	v_lshlrev_b32_e32 v131, 16, v223
	v_and_b32_e32 v223, 0xffff0000, v223
	v_lshlrev_b32_e32 v155, 16, v231
	v_and_b32_e32 v231, 0xffff0000, v231
	v_mul_f32_e32 v128, 0xbfb8aa3b, v128
	v_mul_f32_e32 v220, 0xbfb8aa3b, v220
	v_mul_f32_e32 v152, 0xbfb8aa3b, v152
	v_mul_f32_e32 v228, 0xbfb8aa3b, v228
	v_mul_f32_e32 v129, 0xbfb8aa3b, v129
	v_mul_f32_e32 v221, 0xbfb8aa3b, v221
	v_mul_f32_e32 v153, 0xbfb8aa3b, v153
	v_mul_f32_e32 v229, 0xbfb8aa3b, v229
	v_mul_f32_e32 v130, 0xbfb8aa3b, v130
	v_mul_f32_e32 v222, 0xbfb8aa3b, v222
	v_mul_f32_e32 v154, 0xbfb8aa3b, v154
	v_mul_f32_e32 v230, 0xbfb8aa3b, v230
	v_mul_f32_e32 v131, 0xbfb8aa3b, v131
	v_mul_f32_e32 v223, 0xbfb8aa3b, v223
	v_mul_f32_e32 v155, 0xbfb8aa3b, v155
	v_mul_f32_e32 v231, 0xbfb8aa3b, v231
	v_exp_f32_e32 v128, v128
	v_exp_f32_e32 v220, v220
	v_exp_f32_e32 v152, v152
	v_exp_f32_e32 v228, v228
	v_exp_f32_e32 v129, v129
	v_exp_f32_e32 v221, v221
	v_exp_f32_e32 v153, v153
	v_exp_f32_e32 v229, v229
	v_exp_f32_e32 v130, v130
	v_exp_f32_e32 v222, v222
	v_exp_f32_e32 v154, v154
	v_exp_f32_e32 v230, v230
	v_exp_f32_e32 v131, v131
	v_exp_f32_e32 v223, v223
	v_exp_f32_e32 v155, v155
	v_exp_f32_e32 v231, v231
	v_add_f32_e32 v128, 1.0, v128
	v_add_f32_e32 v220, 1.0, v220
	v_add_f32_e32 v152, 1.0, v152
	v_add_f32_e32 v228, 1.0, v228
	v_add_f32_e32 v129, 1.0, v129
	v_add_f32_e32 v221, 1.0, v221
	v_add_f32_e32 v153, 1.0, v153
	v_add_f32_e32 v229, 1.0, v229
	v_add_f32_e32 v130, 1.0, v130
	v_add_f32_e32 v222, 1.0, v222
	v_add_f32_e32 v154, 1.0, v154
	v_add_f32_e32 v230, 1.0, v230
	v_add_f32_e32 v131, 1.0, v131
	v_add_f32_e32 v223, 1.0, v223
	v_add_f32_e32 v155, 1.0, v155
	v_add_f32_e32 v231, 1.0, v231
	v_rcp_f32_e32 v128, v128
	v_rcp_f32_e32 v220, v220
	v_rcp_f32_e32 v129, v129
	v_rcp_f32_e32 v221, v221
	v_rcp_f32_e32 v130, v130
	v_rcp_f32_e32 v222, v222
	v_rcp_f32_e32 v131, v131
	v_rcp_f32_e32 v223, v223
	v_mul_f32_e32 v128, v128, v152
	v_mul_f32_e32 v220, v220, v228
	v_mul_f32_e32 v129, v129, v153
	v_mul_f32_e32 v221, v221, v229
	v_mul_f32_e32 v130, v130, v154
	v_mul_f32_e32 v222, v222, v230
	v_mul_f32_e32 v131, v131, v155
	v_mul_f32_e32 v223, v223, v231
	v_mul_f32_e32 v4, v4, v128
	v_mul_f32_e32 v5, v5, v220
	v_mul_f32_e32 v6, v6, v129
	v_mul_f32_e32 v7, v7, v221
	v_mul_f32_e32 v0, v0, v130
	v_mul_f32_e32 v1, v1, v222
	v_mul_f32_e32 v2, v2, v131
	v_mul_f32_e32 v3, v3, v223
	s_branch .LBB0_322
.Lp4epi_last:
	v_lshlrev_b32_e32 v144, 11, v144
	s_mov_b32 s18, 0x8000
	s_mov_b32 s50, 0x28000
	s_mov_b32 s51, 0
	v_add_u32_e32 v144, v144, v145
	v_mov_b32_e32 v145, 0
	global_load_dwordx4 v[180:183], v[218:219], off
	global_load_dwordx4 v[184:187], v[218:219], off offset:256
	v_lshl_add_u64 v[218:219], v[218:219], 0, s[20:21]
	global_load_dwordx4 v[196:199], v[218:219], off
	global_load_dwordx4 v[220:223], v[218:219], off offset:256
	v_lshl_add_u64 v[218:219], v[218:219], 0, s[20:21]
	global_load_dwordx4 v[232:235], v[218:219], off
	global_load_dwordx4 v[236:239], v[218:219], off offset:256
	v_lshl_add_u64 v[218:219], v[218:219], 0, s[20:21]
	v_lshl_add_u64 v[144:145], v[144:145], 0, s[24:25]
	s_waitcnt vmcnt(4)
	v_lshlrev_b32_e32 v128, 16, v180
	v_and_b32_e32 v180, 0xffff0000, v180
	v_lshlrev_b32_e32 v129, 16, v181
	v_and_b32_e32 v181, 0xffff0000, v181
	v_lshlrev_b32_e32 v130, 16, v182
	v_and_b32_e32 v182, 0xffff0000, v182
	v_lshlrev_b32_e32 v131, 16, v183
	v_and_b32_e32 v183, 0xffff0000, v183
	v_mul_f32_e32 v128, 0xbfb8aa3b, v128
	v_mul_f32_e32 v180, 0xbfb8aa3b, v180
	v_mul_f32_e32 v129, 0xbfb8aa3b, v129
	v_mul_f32_e32 v181, 0xbfb8aa3b, v181
	v_mul_f32_e32 v130, 0xbfb8aa3b, v130
	v_mul_f32_e32 v182, 0xbfb8aa3b, v182
	v_mul_f32_e32 v131, 0xbfb8aa3b, v131
	v_mul_f32_e32 v183, 0xbfb8aa3b, v183
	v_exp_f32_e32 v128, v128
	v_exp_f32_e32 v180, v180
	v_exp_f32_e32 v129, v129
	v_exp_f32_e32 v181, v181
	v_exp_f32_e32 v130, v130
	v_exp_f32_e32 v182, v182
	v_exp_f32_e32 v131, v131
	v_exp_f32_e32 v183, v183
	v_add_f32_e32 v128, 1.0, v128
	v_add_f32_e32 v180, 1.0, v180
	v_add_f32_e32 v129, 1.0, v129
	v_add_f32_e32 v181, 1.0, v181
	v_add_f32_e32 v130, 1.0, v130
	v_add_f32_e32 v182, 1.0, v182
	v_add_f32_e32 v131, 1.0, v131
	v_add_f32_e32 v183, 1.0, v183
	v_rcp_f32_e32 v128, v128
	v_rcp_f32_e32 v180, v180
	v_rcp_f32_e32 v129, v129
	v_rcp_f32_e32 v181, v181
	v_rcp_f32_e32 v130, v130
	v_rcp_f32_e32 v182, v182
	v_rcp_f32_e32 v131, v131
	v_rcp_f32_e32 v183, v183
	v_mul_f32_e32 v124, v124, v128
	v_mul_f32_e32 v125, v125, v180
	v_mul_f32_e32 v126, v126, v129
	v_mul_f32_e32 v127, v127, v181
	v_mul_f32_e32 v120, v120, v130
	v_mul_f32_e32 v121, v121, v182
	v_mul_f32_e32 v122, v122, v131
	v_mul_f32_e32 v123, v123, v183
	v_lshlrev_b32_e32 v128, 16, v184
	v_and_b32_e32 v184, 0xffff0000, v184
	v_lshlrev_b32_e32 v129, 16, v185
	v_and_b32_e32 v185, 0xffff0000, v185
	v_lshlrev_b32_e32 v130, 16, v186
	v_and_b32_e32 v186, 0xffff0000, v186
	v_lshlrev_b32_e32 v131, 16, v187
	v_and_b32_e32 v187, 0xffff0000, v187
	v_mul_f32_e32 v128, 0xbfb8aa3b, v128
	v_mul_f32_e32 v184, 0xbfb8aa3b, v184
	v_mul_f32_e32 v129, 0xbfb8aa3b, v129
	v_mul_f32_e32 v185, 0xbfb8aa3b, v185
	v_mul_f32_e32 v130, 0xbfb8aa3b, v130
	v_mul_f32_e32 v186, 0xbfb8aa3b, v186
	v_mul_f32_e32 v131, 0xbfb8aa3b, v131
	v_mul_f32_e32 v187, 0xbfb8aa3b, v187
	v_exp_f32_e32 v128, v128
	v_exp_f32_e32 v184, v184
	v_exp_f32_e32 v129, v129
	v_exp_f32_e32 v185, v185
	v_exp_f32_e32 v130, v130
	v_exp_f32_e32 v186, v186
	v_exp_f32_e32 v131, v131
	v_exp_f32_e32 v187, v187
	v_add_f32_e32 v128, 1.0, v128
	v_add_f32_e32 v184, 1.0, v184
	v_add_f32_e32 v129, 1.0, v129
	v_add_f32_e32 v185, 1.0, v185
	v_add_f32_e32 v130, 1.0, v130
	v_add_f32_e32 v186, 1.0, v186
	v_add_f32_e32 v131, 1.0, v131
	v_add_f32_e32 v187, 1.0, v187
	v_rcp_f32_e32 v128, v128
	v_rcp_f32_e32 v184, v184
	v_rcp_f32_e32 v129, v129
	v_rcp_f32_e32 v185, v185
	v_rcp_f32_e32 v130, v130
	v_rcp_f32_e32 v186, v186
	v_rcp_f32_e32 v131, v131
	v_rcp_f32_e32 v187, v187
	v_mul_f32_e32 v92, v92, v128
	v_mul_f32_e32 v93, v93, v184
	v_mul_f32_e32 v94, v94, v129
	v_mul_f32_e32 v95, v95, v185
	v_mul_f32_e32 v88, v88, v130
	v_mul_f32_e32 v89, v89, v186
	v_mul_f32_e32 v90, v90, v131
	v_mul_f32_e32 v91, v91, v187
	v_cvt_pk_bf16_f32 v180, v124, v125
	v_cvt_pk_bf16_f32 v181, v126, v127
	v_cvt_pk_bf16_f32 v182, v120, v121
	v_cvt_pk_bf16_f32 v183, v122, v123
	global_store_dwordx4 v[144:145], v[180:183], off
	v_cvt_pk_bf16_f32 v184, v92, v93
	v_cvt_pk_bf16_f32 v185, v94, v95
	v_cvt_pk_bf16_f32 v186, v88, v89
	v_cvt_pk_bf16_f32 v187, v90, v91
	global_store_dwordx4 v[144:145], v[184:187], off offset:256
	v_lshl_add_u64 v[144:145], v[144:145], 0, s[18:19]
	global_load_dwordx4 v[180:183], v[218:219], off
	global_load_dwordx4 v[184:187], v[218:219], off offset:256
	v_lshl_add_u64 v[218:219], v[218:219], 0, s[26:27]
	s_waitcnt vmcnt(6)
; DEV unsigned cvt_pk_bf16(float lo, float hi) { const f32x2_ v = {lo, hi}; return __builtin_bit_cast(unsigned, __builtin_convertvector(v, bf16x2n_)); }
; DEV float bflo(unsigned w) { return __uint_as_float(w << 16); }
; DEV float bfhi(unsigned w) { return __uint_as_float(w & 0xffff0000u); }
; #define RS_(xa, xb) ((1.0f + one * __expf(-(xb))) * __builtin_amdgcn_rcpf(1.0f + __expf(-(xa))))
;   DEV bool rescale(f32x4 (&acc)[2][2][4][2], const Unit& u, int wr, int wc, int fr, int fq) const {
;     ...
;         for (int bj = 0; bj < 2; ++bj) {
;           const int c = col0 + bj * HALF;
;           const u32x4 ga = *(const u32x4*)(Z + r * NIN + GT + u.seg * D + c);
;           const u32x4 gb = *(const u32x4*)(Z + r * NIN + GT + sb * D + c);
;     ...
;           acc[ai][bj][m][0][0] *= RS_(bflo(ga.x), bflo(gb.x)); acc[ai][bj][m][0][1] *= RS_(bfhi(ga.x), bfhi(gb.x));
;           acc[ai][bj][m][0][2] *= RS_(bflo(ga.y), bflo(gb.y)); acc[ai][bj][m][0][3] *= RS_(bfhi(ga.y), bfhi(gb.y));
;           acc[ai][bj][m][1][0] *= RS_(bflo(ga.z), bflo(gb.z)); acc[ai][bj][m][1][1] *= RS_(bfhi(ga.z), bfhi(gb.z));
;           acc[ai][bj][m][1][2] *= RS_(bflo(ga.w), bflo(gb.w)); acc[ai][bj][m][1][3] *= RS_(bfhi(ga.w), bfhi(gb.w));
;     ...
;           asm volatile("" ::: "memory");
;         }
;       }
;     return !lastseg;
;   }
;   DEV void operator()(const f32x4 (&acc)[2][2][4][2], const Unit& u, int wr, int wc, int fr, int fq) const {
;     const int row0 = u.pm * BM + wr * 64 + fr, col0 = u.pn * BM + wc * 32 + 8 * fq;
; #pragma unroll
;     for (int ai = 0; ai < 2; ++ai)
; #pragma unroll
;       for (int m = 0; m < 4; ++m) {
;         bf16_t* rowp = H + (size_t)(row0 + ai * HALF + m * 16) * D + col0;
; #pragma unroll
;         for (int bj = 0; bj < 2; ++bj) {
;           const f32x4 v0 = acc[ai][bj][m][0], v1 = acc[ai][bj][m][1];
;           u32x4 w; w.x = cvt_pk_bf16(v0[0], v0[1]); w.y = cvt_pk_bf16(v0[2], v0[3]); w.z = cvt_pk_bf16(v1[0], v1[1]); w.w = cvt_pk_bf16(v1[2], v1[3]);
;           *(u32x4*)(rowp + bj * HALF) = w;
;         }
;       }
;   }
	v_lshlrev_b32_e32 v128, 16, v196
	v_and_b32_e32 v196, 0xffff0000, v196
	v_lshlrev_b32_e32 v129, 16, v197
	v_and_b32_e32 v197, 0xffff0000, v197
	v_lshlrev_b32_e32 v130, 16, v198
	v_and_b32_e32 v198, 0xffff0000, v198
	v_lshlrev_b32_e32 v131, 16, v199
	v_and_b32_e32 v199, 0xffff0000, v199
	v_mul_f32_e32 v128, 0xbfb8aa3b, v128
	v_mul_f32_e32 v196, 0xbfb8aa3b, v196
	v_mul_f32_e32 v129, 0xbfb8aa3b, v129
	v_mul_f32_e32 v197, 0xbfb8aa3b, v197
	v_mul_f32_e32 v130, 0xbfb8aa3b, v130
	v_mul_f32_e32 v198, 0xbfb8aa3b, v198
	v_mul_f32_e32 v131, 0xbfb8aa3b, v131
	v_mul_f32_e32 v199, 0xbfb8aa3b, v199
	v_exp_f32_e32 v128, v128
	v_exp_f32_e32 v196, v196
	v_exp_f32_e32 v129, v129
	v_exp_f32_e32 v197, v197
	v_exp_f32_e32 v130, v130
	v_exp_f32_e32 v198, v198
	v_exp_f32_e32 v131, v131
	v_exp_f32_e32 v199, v199
	v_add_f32_e32 v128, 1.0, v128
	v_add_f32_e32 v196, 1.0, v196
	v_add_f32_e32 v129, 1.0, v129
	v_add_f32_e32 v197, 1.0, v197
	v_add_f32_e32 v130, 1.0, v130
	v_add_f32_e32 v198, 1.0, v198
	v_add_f32_e32 v131, 1.0, v131
	v_add_f32_e32 v199, 1.0, v199
	v_rcp_f32_e32 v128, v128
	v_rcp_f32_e32 v196, v196
	v_rcp_f32_e32 v129, v129
	v_rcp_f32_e32 v197, v197
	v_rcp_f32_e32 v130, v130
	v_rcp_f32_e32 v198, v198
	v_rcp_f32_e32 v131, v131
	v_rcp_f32_e32 v199, v199
	v_mul_f32_e32 v116, v116, v128
	v_mul_f32_e32 v117, v117, v196
	v_mul_f32_e32 v118, v118, v129
	v_mul_f32_e32 v119, v119, v197
	v_mul_f32_e32 v112, v112, v130
	v_mul_f32_e32 v113, v113, v198
	v_mul_f32_e32 v114, v114, v131
	v_mul_f32_e32 v115, v115, v199
	v_lshlrev_b32_e32 v128, 16, v220
	v_and_b32_e32 v220, 0xffff0000, v220
	v_lshlrev_b32_e32 v129, 16, v221
	v_and_b32_e32 v221, 0xffff0000, v221
	v_lshlrev_b32_e32 v130, 16, v222
	v_and_b32_e32 v222, 0xffff0000, v222
	v_lshlrev_b32_e32 v131, 16, v223
	v_and_b32_e32 v223, 0xffff0000, v223
	v_mul_f32_e32 v128, 0xbfb8aa3b, v128
	v_mul_f32_e32 v220, 0xbfb8aa3b, v220
	v_mul_f32_e32 v129, 0xbfb8aa3b, v129
	v_mul_f32_e32 v221, 0xbfb8aa3b, v221
	v_mul_f32_e32 v130, 0xbfb8aa3b, v130
	v_mul_f32_e32 v222, 0xbfb8aa3b, v222
	v_mul_f32_e32 v131, 0xbfb8aa3b, v131
	v_mul_f32_e32 v223, 0xbfb8aa3b, v223
	v_exp_f32_e32 v128, v128
	v_exp_f32_e32 v220, v220
	v_exp_f32_e32 v129, v129
	v_exp_f32_e32 v221, v221
	v_exp_f32_e32 v130, v130
	v_exp_f32_e32 v222, v222
	v_exp_f32_e32 v131, v131
	v_exp_f32_e32 v223, v223
	v_add_f32_e32 v128, 1.0, v128
	v_add_f32_e32 v220, 1.0, v220
	v_add_f32_e32 v129, 1.0, v129
	v_add_f32_e32 v221, 1.0, v221
	v_add_f32_e32 v130, 1.0, v130
	v_add_f32_e32 v222, 1.0, v222
	v_add_f32_e32 v131, 1.0, v131
	v_add_f32_e32 v223, 1.0, v223
	v_rcp_f32_e32 v128, v128
	v_rcp_f32_e32 v220, v220
	v_rcp_f32_e32 v129, v129
	v_rcp_f32_e32 v221, v221
	v_rcp_f32_e32 v130, v130
	v_rcp_f32_e32 v222, v222
	v_rcp_f32_e32 v131, v131
	v_rcp_f32_e32 v223, v223
	v_mul_f32_e32 v84, v84, v128
	v_mul_f32_e32 v85, v85, v220
	v_mul_f32_e32 v86, v86, v129
	v_mul_f32_e32 v87, v87, v221
	v_mul_f32_e32 v80, v80, v130
	v_mul_f32_e32 v81, v81, v222
	v_mul_f32_e32 v82, v82, v131
	v_mul_f32_e32 v83, v83, v223
	v_cvt_pk_bf16_f32 v196, v116, v117
	v_cvt_pk_bf16_f32 v197, v118, v119
	v_cvt_pk_bf16_f32 v198, v112, v113
	v_cvt_pk_bf16_f32 v199, v114, v115
	global_store_dwordx4 v[144:145], v[196:199], off
	v_cvt_pk_bf16_f32 v220, v84, v85
	v_cvt_pk_bf16_f32 v221, v86, v87
	v_cvt_pk_bf16_f32 v222, v80, v81
	v_cvt_pk_bf16_f32 v223, v82, v83
	global_store_dwordx4 v[144:145], v[220:223], off offset:256
	v_lshl_add_u64 v[144:145], v[144:145], 0, s[18:19]
	global_load_dwordx4 v[196:199], v[218:219], off
	global_load_dwordx4 v[220:223], v[218:219], off offset:256
	v_lshl_add_u64 v[218:219], v[218:219], 0, s[20:21]
	s_waitcnt vmcnt(8)
	v_lshlrev_b32_e32 v128, 16, v232
	v_and_b32_e32 v232, 0xffff0000, v232
	v_lshlrev_b32_e32 v129, 16, v233
	v_and_b32_e32 v233, 0xffff0000, v233
	v_lshlrev_b32_e32 v130, 16, v234
	v_and_b32_e32 v234, 0xffff0000, v234
	v_lshlrev_b32_e32 v131, 16, v235
	v_and_b32_e32 v235, 0xffff0000, v235
	v_mul_f32_e32 v128, 0xbfb8aa3b, v128
	v_mul_f32_e32 v232, 0xbfb8aa3b, v232
	v_mul_f32_e32 v129, 0xbfb8aa3b, v129
	v_mul_f32_e32 v233, 0xbfb8aa3b, v233
	v_mul_f32_e32 v130, 0xbfb8aa3b, v130
	v_mul_f32_e32 v234, 0xbfb8aa3b, v234
	v_mul_f32_e32 v131, 0xbfb8aa3b, v131
	v_mul_f32_e32 v235, 0xbfb8aa3b, v235
	v_exp_f32_e32 v128, v128
	v_exp_f32_e32 v232, v232
	v_exp_f32_e32 v129, v129
	v_exp_f32_e32 v233, v233
	v_exp_f32_e32 v130, v130
	v_exp_f32_e32 v234, v234
	v_exp_f32_e32 v131, v131
	v_exp_f32_e32 v235, v235
	v_add_f32_e32 v128, 1.0, v128
	v_add_f32_e32 v232, 1.0, v232
	v_add_f32_e32 v129, 1.0, v129
	v_add_f32_e32 v233, 1.0, v233
	v_add_f32_e32 v130, 1.0, v130
	v_add_f32_e32 v234, 1.0, v234
	v_add_f32_e32 v131, 1.0, v131
	v_add_f32_e32 v235, 1.0, v235
	v_rcp_f32_e32 v128, v128
	v_rcp_f32_e32 v232, v232
	v_rcp_f32_e32 v129, v129
	v_rcp_f32_e32 v233, v233
	v_rcp_f32_e32 v130, v130
	v_rcp_f32_e32 v234, v234
	v_rcp_f32_e32 v131, v131
	v_rcp_f32_e32 v235, v235
	v_mul_f32_e32 v108, v108, v128
	v_mul_f32_e32 v109, v109, v232
	v_mul_f32_e32 v110, v110, v129
	v_mul_f32_e32 v111, v111, v233
	v_mul_f32_e32 v104, v104, v130
	v_mul_f32_e32 v105, v105, v234
	v_mul_f32_e32 v106, v106, v131
	v_mul_f32_e32 v107, v107, v235
	v_lshlrev_b32_e32 v128, 16, v236
	v_and_b32_e32 v236, 0xffff0000, v236
	v_lshlrev_b32_e32 v129, 16, v237
	v_and_b32_e32 v237, 0xffff0000, v237
	v_lshlrev_b32_e32 v130, 16, v238
	v_and_b32_e32 v238, 0xffff0000, v238
	v_lshlrev_b32_e32 v131, 16, v239
	v_and_b32_e32 v239, 0xffff0000, v239
	v_mul_f32_e32 v128, 0xbfb8aa3b, v128
	v_mul_f32_e32 v236, 0xbfb8aa3b, v236
	v_mul_f32_e32 v129, 0xbfb8aa3b, v129
	v_mul_f32_e32 v237, 0xbfb8aa3b, v237
	v_mul_f32_e32 v130, 0xbfb8aa3b, v130
; DEV unsigned cvt_pk_bf16(float lo, float hi) { const f32x2_ v = {lo, hi}; return __builtin_bit_cast(unsigned, __builtin_convertvector(v, bf16x2n_)); }
; DEV float bflo(unsigned w) { return __uint_as_float(w << 16); }
; DEV float bfhi(unsigned w) { return __uint_as_float(w & 0xffff0000u); }
; #define RS_(xa, xb) ((1.0f + one * __expf(-(xb))) * __builtin_amdgcn_rcpf(1.0f + __expf(-(xa))))
;   DEV bool rescale(f32x4 (&acc)[2][2][4][2], const Unit& u, int wr, int wc, int fr, int fq) const {
;     ...
;         const size_t r = (size_t)(row0 + ai * HALF + m * 16);
; #pragma unroll
;         for (int bj = 0; bj < 2; ++bj) {
;           const int c = col0 + bj * HALF;
;           const u32x4 ga = *(const u32x4*)(Z + r * NIN + GT + u.seg * D + c);
;           const u32x4 gb = *(const u32x4*)(Z + r * NIN + GT + sb * D + c);
;     ...
;           acc[ai][bj][m][0][0] *= RS_(bflo(ga.x), bflo(gb.x)); acc[ai][bj][m][0][1] *= RS_(bfhi(ga.x), bfhi(gb.x));
;           acc[ai][bj][m][0][2] *= RS_(bflo(ga.y), bflo(gb.y)); acc[ai][bj][m][0][3] *= RS_(bfhi(ga.y), bfhi(gb.y));
;           acc[ai][bj][m][1][0] *= RS_(bflo(ga.z), bflo(gb.z)); acc[ai][bj][m][1][1] *= RS_(bfhi(ga.z), bfhi(gb.z));
;           acc[ai][bj][m][1][2] *= RS_(bflo(ga.w), bflo(gb.w)); acc[ai][bj][m][1][3] *= RS_(bfhi(ga.w), bfhi(gb.w));
;   DEV void operator()(const f32x4 (&acc)[2][2][4][2], const Unit& u, int wr, int wc, int fr, int fq) const {
;     ...
;         bf16_t* rowp = H + (size_t)(row0 + ai * HALF + m * 16) * D + col0;
; #pragma unroll
;         for (int bj = 0; bj < 2; ++bj) {
;           const f32x4 v0 = acc[ai][bj][m][0], v1 = acc[ai][bj][m][1];
;           u32x4 w; w.x = cvt_pk_bf16(v0[0], v0[1]); w.y = cvt_pk_bf16(v0[2], v0[3]); w.z = cvt_pk_bf16(v1[0], v1[1]); w.w = cvt_pk_bf16(v1[2], v1[3]);
;           *(u32x4*)(rowp + bj * HALF) = w;
	v_mul_f32_e32 v238, 0xbfb8aa3b, v238
	v_mul_f32_e32 v131, 0xbfb8aa3b, v131
	v_mul_f32_e32 v239, 0xbfb8aa3b, v239
	v_exp_f32_e32 v128, v128
	v_exp_f32_e32 v236, v236
	v_exp_f32_e32 v129, v129
	v_exp_f32_e32 v237, v237
	v_exp_f32_e32 v130, v130
	v_exp_f32_e32 v238, v238
	v_exp_f32_e32 v131, v131
	v_exp_f32_e32 v239, v239
	v_add_f32_e32 v128, 1.0, v128
	v_add_f32_e32 v236, 1.0, v236
	v_add_f32_e32 v129, 1.0, v129
	v_add_f32_e32 v237, 1.0, v237
	v_add_f32_e32 v130, 1.0, v130
	v_add_f32_e32 v238, 1.0, v238
	v_add_f32_e32 v131, 1.0, v131
	v_add_f32_e32 v239, 1.0, v239
	v_rcp_f32_e32 v128, v128
	v_rcp_f32_e32 v236, v236
	v_rcp_f32_e32 v129, v129
	v_rcp_f32_e32 v237, v237
	v_rcp_f32_e32 v130, v130
	v_rcp_f32_e32 v238, v238
	v_rcp_f32_e32 v131, v131
	v_rcp_f32_e32 v239, v239
	v_mul_f32_e32 v76, v76, v128
	v_mul_f32_e32 v77, v77, v236
	v_mul_f32_e32 v78, v78, v129
	v_mul_f32_e32 v79, v79, v237
	v_mul_f32_e32 v72, v72, v130
	v_mul_f32_e32 v73, v73, v238
	v_mul_f32_e32 v74, v74, v131
	v_mul_f32_e32 v75, v75, v239
	v_cvt_pk_bf16_f32 v232, v108, v109
	v_cvt_pk_bf16_f32 v233, v110, v111
	v_cvt_pk_bf16_f32 v234, v104, v105
	v_cvt_pk_bf16_f32 v235, v106, v107
	global_store_dwordx4 v[144:145], v[232:235], off
	v_cvt_pk_bf16_f32 v236, v76, v77
	v_cvt_pk_bf16_f32 v237, v78, v79
	v_cvt_pk_bf16_f32 v238, v72, v73
	v_cvt_pk_bf16_f32 v239, v74, v75
	global_store_dwordx4 v[144:145], v[236:239], off offset:256
	v_lshl_add_u64 v[144:145], v[144:145], 0, s[18:19]
	global_load_dwordx4 v[232:235], v[218:219], off
	global_load_dwordx4 v[236:239], v[218:219], off offset:256
	v_lshl_add_u64 v[218:219], v[218:219], 0, s[20:21]
	s_waitcnt vmcnt(8)
	v_lshlrev_b32_e32 v128, 16, v180
	v_and_b32_e32 v180, 0xffff0000, v180
	v_lshlrev_b32_e32 v129, 16, v181
	v_and_b32_e32 v181, 0xffff0000, v181
	v_lshlrev_b32_e32 v130, 16, v182
	v_and_b32_e32 v182, 0xffff0000, v182
	v_lshlrev_b32_e32 v131, 16, v183
	v_and_b32_e32 v183, 0xffff0000, v183
	v_mul_f32_e32 v128, 0xbfb8aa3b, v128
	v_mul_f32_e32 v180, 0xbfb8aa3b, v180
	v_mul_f32_e32 v129, 0xbfb8aa3b, v129
	v_mul_f32_e32 v181, 0xbfb8aa3b, v181
	v_mul_f32_e32 v130, 0xbfb8aa3b, v130
	v_mul_f32_e32 v182, 0xbfb8aa3b, v182
	v_mul_f32_e32 v131, 0xbfb8aa3b, v131
	v_mul_f32_e32 v183, 0xbfb8aa3b, v183
	v_exp_f32_e32 v128, v128
	v_exp_f32_e32 v180, v180
	v_exp_f32_e32 v129, v129
	v_exp_f32_e32 v181, v181
	v_exp_f32_e32 v130, v130
	v_exp_f32_e32 v182, v182
	v_exp_f32_e32 v131, v131
	v_exp_f32_e32 v183, v183
	v_add_f32_e32 v128, 1.0, v128
	v_add_f32_e32 v180, 1.0, v180
	v_add_f32_e32 v129, 1.0, v129
	v_add_f32_e32 v181, 1.0, v181
	v_add_f32_e32 v130, 1.0, v130
	v_add_f32_e32 v182, 1.0, v182
	v_add_f32_e32 v131, 1.0, v131
	v_add_f32_e32 v183, 1.0, v183
	v_rcp_f32_e32 v128, v128
	v_rcp_f32_e32 v180, v180
	v_rcp_f32_e32 v129, v129
	v_rcp_f32_e32 v181, v181
	v_rcp_f32_e32 v130, v130
	v_rcp_f32_e32 v182, v182
	v_rcp_f32_e32 v131, v131
	v_rcp_f32_e32 v183, v183
	v_mul_f32_e32 v100, v100, v128
	v_mul_f32_e32 v101, v101, v180
	v_mul_f32_e32 v102, v102, v129
	v_mul_f32_e32 v103, v103, v181
	v_mul_f32_e32 v96, v96, v130
	v_mul_f32_e32 v97, v97, v182
	v_mul_f32_e32 v98, v98, v131
	v_mul_f32_e32 v99, v99, v183
	v_lshlrev_b32_e32 v128, 16, v184
	v_and_b32_e32 v184, 0xffff0000, v184
	v_lshlrev_b32_e32 v129, 16, v185
	v_and_b32_e32 v185, 0xffff0000, v185
	v_lshlrev_b32_e32 v130, 16, v186
	v_and_b32_e32 v186, 0xffff0000, v186
	v_lshlrev_b32_e32 v131, 16, v187
	v_and_b32_e32 v187, 0xffff0000, v187
	v_mul_f32_e32 v128, 0xbfb8aa3b, v128
	v_mul_f32_e32 v184, 0xbfb8aa3b, v184
	v_mul_f32_e32 v129, 0xbfb8aa3b, v129
	v_mul_f32_e32 v185, 0xbfb8aa3b, v185
	v_mul_f32_e32 v130, 0xbfb8aa3b, v130
	v_mul_f32_e32 v186, 0xbfb8aa3b, v186
	v_mul_f32_e32 v131, 0xbfb8aa3b, v131
	v_mul_f32_e32 v187, 0xbfb8aa3b, v187
	v_exp_f32_e32 v128, v128
	v_exp_f32_e32 v184, v184
	v_exp_f32_e32 v129, v129
	v_exp_f32_e32 v185, v185
	v_exp_f32_e32 v130, v130
	v_exp_f32_e32 v186, v186
	v_exp_f32_e32 v131, v131
	v_exp_f32_e32 v187, v187
	v_add_f32_e32 v128, 1.0, v128
	v_add_f32_e32 v184, 1.0, v184
	v_add_f32_e32 v129, 1.0, v129
	v_add_f32_e32 v185, 1.0, v185
	v_add_f32_e32 v130, 1.0, v130
	v_add_f32_e32 v186, 1.0, v186
	v_add_f32_e32 v131, 1.0, v131
	v_add_f32_e32 v187, 1.0, v187
	v_rcp_f32_e32 v128, v128
	v_rcp_f32_e32 v184, v184
	v_rcp_f32_e32 v129, v129
	v_rcp_f32_e32 v185, v185
	v_rcp_f32_e32 v130, v130
	v_rcp_f32_e32 v186, v186
	v_rcp_f32_e32 v131, v131
	v_rcp_f32_e32 v187, v187
	v_mul_f32_e32 v68, v68, v128
	v_mul_f32_e32 v69, v69, v184
	v_mul_f32_e32 v70, v70, v129
	v_mul_f32_e32 v71, v71, v185
	v_mul_f32_e32 v64, v64, v130
	v_mul_f32_e32 v65, v65, v186
	v_mul_f32_e32 v66, v66, v131
	v_mul_f32_e32 v67, v67, v187
	v_cvt_pk_bf16_f32 v180, v100, v101
	v_cvt_pk_bf16_f32 v181, v102, v103
	v_cvt_pk_bf16_f32 v182, v96, v97
	v_cvt_pk_bf16_f32 v183, v98, v99
	global_store_dwordx4 v[144:145], v[180:183], off
	v_cvt_pk_bf16_f32 v184, v68, v69
	v_cvt_pk_bf16_f32 v185, v70, v71
	v_cvt_pk_bf16_f32 v186, v64, v65
	v_cvt_pk_bf16_f32 v187, v66, v67
	global_store_dwordx4 v[144:145], v[184:187], off offset:256
	v_lshl_add_u64 v[144:145], v[144:145], 0, s[50:51]
	global_load_dwordx4 v[180:183], v[218:219], off
	global_load_dwordx4 v[184:187], v[218:219], off offset:256
	v_lshl_add_u64 v[218:219], v[218:219], 0, s[20:21]
	s_waitcnt vmcnt(8)
; DEV unsigned cvt_pk_bf16(float lo, float hi) { const f32x2_ v = {lo, hi}; return __builtin_bit_cast(unsigned, __builtin_convertvector(v, bf16x2n_)); }
; DEV float bflo(unsigned w) { return __uint_as_float(w << 16); }
; DEV float bfhi(unsigned w) { return __uint_as_float(w & 0xffff0000u); }
; #define RS_(xa, xb) ((1.0f + one * __expf(-(xb))) * __builtin_amdgcn_rcpf(1.0f + __expf(-(xa))))
;   DEV bool rescale(f32x4 (&acc)[2][2][4][2], const Unit& u, int wr, int wc, int fr, int fq) const {
;     ...
;         const size_t r = (size_t)(row0 + ai * HALF + m * 16);
; #pragma unroll
;         for (int bj = 0; bj < 2; ++bj) {
;           const int c = col0 + bj * HALF;
;           const u32x4 ga = *(const u32x4*)(Z + r * NIN + GT + u.seg * D + c);
;           const u32x4 gb = *(const u32x4*)(Z + r * NIN + GT + sb * D + c);
;     ...
;           acc[ai][bj][m][0][0] *= RS_(bflo(ga.x), bflo(gb.x)); acc[ai][bj][m][0][1] *= RS_(bfhi(ga.x), bfhi(gb.x));
;           acc[ai][bj][m][0][2] *= RS_(bflo(ga.y), bflo(gb.y)); acc[ai][bj][m][0][3] *= RS_(bfhi(ga.y), bfhi(gb.y));
;           acc[ai][bj][m][1][0] *= RS_(bflo(ga.z), bflo(gb.z)); acc[ai][bj][m][1][1] *= RS_(bfhi(ga.z), bfhi(gb.z));
;           acc[ai][bj][m][1][2] *= RS_(bflo(ga.w), bflo(gb.w)); acc[ai][bj][m][1][3] *= RS_(bfhi(ga.w), bfhi(gb.w));
;   DEV void operator()(const f32x4 (&acc)[2][2][4][2], const Unit& u, int wr, int wc, int fr, int fq) const {
;     ...
;         bf16_t* rowp = H + (size_t)(row0 + ai * HALF + m * 16) * D + col0;
; #pragma unroll
;         for (int bj = 0; bj < 2; ++bj) {
;           const f32x4 v0 = acc[ai][bj][m][0], v1 = acc[ai][bj][m][1];
;           u32x4 w; w.x = cvt_pk_bf16(v0[0], v0[1]); w.y = cvt_pk_bf16(v0[2], v0[3]); w.z = cvt_pk_bf16(v1[0], v1[1]); w.w = cvt_pk_bf16(v1[2], v1[3]);
;           *(u32x4*)(rowp + bj * HALF) = w;
	v_lshlrev_b32_e32 v128, 16, v196
	v_and_b32_e32 v196, 0xffff0000, v196
	v_lshlrev_b32_e32 v129, 16, v197
	v_and_b32_e32 v197, 0xffff0000, v197
	v_lshlrev_b32_e32 v130, 16, v198
	v_and_b32_e32 v198, 0xffff0000, v198
	v_lshlrev_b32_e32 v131, 16, v199
	v_and_b32_e32 v199, 0xffff0000, v199
	v_mul_f32_e32 v128, 0xbfb8aa3b, v128
	v_mul_f32_e32 v196, 0xbfb8aa3b, v196
	v_mul_f32_e32 v129, 0xbfb8aa3b, v129
	v_mul_f32_e32 v197, 0xbfb8aa3b, v197
	v_mul_f32_e32 v130, 0xbfb8aa3b, v130
	v_mul_f32_e32 v198, 0xbfb8aa3b, v198
	v_mul_f32_e32 v131, 0xbfb8aa3b, v131
	v_mul_f32_e32 v199, 0xbfb8aa3b, v199
	v_exp_f32_e32 v128, v128
	v_exp_f32_e32 v196, v196
	v_exp_f32_e32 v129, v129
	v_exp_f32_e32 v197, v197
	v_exp_f32_e32 v130, v130
	v_exp_f32_e32 v198, v198
	v_exp_f32_e32 v131, v131
	v_exp_f32_e32 v199, v199
	v_add_f32_e32 v128, 1.0, v128
	v_add_f32_e32 v196, 1.0, v196
	v_add_f32_e32 v129, 1.0, v129
	v_add_f32_e32 v197, 1.0, v197
	v_add_f32_e32 v130, 1.0, v130
	v_add_f32_e32 v198, 1.0, v198
	v_add_f32_e32 v131, 1.0, v131
	v_add_f32_e32 v199, 1.0, v199
	v_rcp_f32_e32 v128, v128
	v_rcp_f32_e32 v196, v196
	v_rcp_f32_e32 v129, v129
	v_rcp_f32_e32 v197, v197
	v_rcp_f32_e32 v130, v130
	v_rcp_f32_e32 v198, v198
	v_rcp_f32_e32 v131, v131
	v_rcp_f32_e32 v199, v199
	v_mul_f32_e32 v60, v60, v128
	v_mul_f32_e32 v61, v61, v196
	v_mul_f32_e32 v62, v62, v129
	v_mul_f32_e32 v63, v63, v197
	v_mul_f32_e32 v56, v56, v130
	v_mul_f32_e32 v57, v57, v198
	v_mul_f32_e32 v58, v58, v131
	v_mul_f32_e32 v59, v59, v199
	v_lshlrev_b32_e32 v128, 16, v220
	v_and_b32_e32 v220, 0xffff0000, v220
	v_lshlrev_b32_e32 v129, 16, v221
	v_and_b32_e32 v221, 0xffff0000, v221
	v_lshlrev_b32_e32 v130, 16, v222
	v_and_b32_e32 v222, 0xffff0000, v222
	v_lshlrev_b32_e32 v131, 16, v223
	v_and_b32_e32 v223, 0xffff0000, v223
	v_mul_f32_e32 v128, 0xbfb8aa3b, v128
	v_mul_f32_e32 v220, 0xbfb8aa3b, v220
	v_mul_f32_e32 v129, 0xbfb8aa3b, v129
	v_mul_f32_e32 v221, 0xbfb8aa3b, v221
	v_mul_f32_e32 v130, 0xbfb8aa3b, v130
	v_mul_f32_e32 v222, 0xbfb8aa3b, v222
	v_mul_f32_e32 v131, 0xbfb8aa3b, v131
	v_mul_f32_e32 v223, 0xbfb8aa3b, v223
	v_exp_f32_e32 v128, v128
	v_exp_f32_e32 v220, v220
	v_exp_f32_e32 v129, v129
	v_exp_f32_e32 v221, v221
	v_exp_f32_e32 v130, v130
	v_exp_f32_e32 v222, v222
	v_exp_f32_e32 v131, v131
	v_exp_f32_e32 v223, v223
	v_add_f32_e32 v128, 1.0, v128
	v_add_f32_e32 v220, 1.0, v220
	v_add_f32_e32 v129, 1.0, v129
	v_add_f32_e32 v221, 1.0, v221
	v_add_f32_e32 v130, 1.0, v130
	v_add_f32_e32 v222, 1.0, v222
	v_add_f32_e32 v131, 1.0, v131
	v_add_f32_e32 v223, 1.0, v223
	v_rcp_f32_e32 v128, v128
	v_rcp_f32_e32 v220, v220
	v_rcp_f32_e32 v129, v129
	v_rcp_f32_e32 v221, v221
	v_rcp_f32_e32 v130, v130
	v_rcp_f32_e32 v222, v222
	v_rcp_f32_e32 v131, v131
	v_rcp_f32_e32 v223, v223
	v_mul_f32_e32 v28, v28, v128
	v_mul_f32_e32 v29, v29, v220
	v_mul_f32_e32 v30, v30, v129
	v_mul_f32_e32 v31, v31, v221
	v_mul_f32_e32 v24, v24, v130
	v_mul_f32_e32 v25, v25, v222
	v_mul_f32_e32 v26, v26, v131
	v_mul_f32_e32 v27, v27, v223
	v_cvt_pk_bf16_f32 v196, v60, v61
	v_cvt_pk_bf16_f32 v197, v62, v63
	v_cvt_pk_bf16_f32 v198, v56, v57
	v_cvt_pk_bf16_f32 v199, v58, v59
	global_store_dwordx4 v[144:145], v[196:199], off
	v_cvt_pk_bf16_f32 v220, v28, v29
	v_cvt_pk_bf16_f32 v221, v30, v31
	v_cvt_pk_bf16_f32 v222, v24, v25
	v_cvt_pk_bf16_f32 v223, v26, v27
	global_store_dwordx4 v[144:145], v[220:223], off offset:256
	v_lshl_add_u64 v[144:145], v[144:145], 0, s[18:19]
	global_load_dwordx4 v[196:199], v[218:219], off
	global_load_dwordx4 v[220:223], v[218:219], off offset:256
	s_waitcnt vmcnt(8)
	v_lshlrev_b32_e32 v128, 16, v232
	v_and_b32_e32 v232, 0xffff0000, v232
	v_lshlrev_b32_e32 v129, 16, v233
	v_and_b32_e32 v233, 0xffff0000, v233
	v_lshlrev_b32_e32 v130, 16, v234
	v_and_b32_e32 v234, 0xffff0000, v234
	v_lshlrev_b32_e32 v131, 16, v235
	v_and_b32_e32 v235, 0xffff0000, v235
	v_mul_f32_e32 v128, 0xbfb8aa3b, v128
	v_mul_f32_e32 v232, 0xbfb8aa3b, v232
	v_mul_f32_e32 v129, 0xbfb8aa3b, v129
	v_mul_f32_e32 v233, 0xbfb8aa3b, v233
	v_mul_f32_e32 v130, 0xbfb8aa3b, v130
	v_mul_f32_e32 v234, 0xbfb8aa3b, v234
	v_mul_f32_e32 v131, 0xbfb8aa3b, v131
	v_mul_f32_e32 v235, 0xbfb8aa3b, v235
	v_exp_f32_e32 v128, v128
	v_exp_f32_e32 v232, v232
	v_exp_f32_e32 v129, v129
	v_exp_f32_e32 v233, v233
	v_exp_f32_e32 v130, v130
	v_exp_f32_e32 v234, v234
	v_exp_f32_e32 v131, v131
	v_exp_f32_e32 v235, v235
	v_add_f32_e32 v128, 1.0, v128
	v_add_f32_e32 v232, 1.0, v232
	v_add_f32_e32 v129, 1.0, v129
	v_add_f32_e32 v233, 1.0, v233
	v_add_f32_e32 v130, 1.0, v130
	v_add_f32_e32 v234, 1.0, v234
	v_add_f32_e32 v131, 1.0, v131
	v_add_f32_e32 v235, 1.0, v235
	v_rcp_f32_e32 v128, v128
	v_rcp_f32_e32 v232, v232
	v_rcp_f32_e32 v129, v129
	v_rcp_f32_e32 v233, v233
	v_rcp_f32_e32 v130, v130
	v_rcp_f32_e32 v234, v234
	v_rcp_f32_e32 v131, v131
	v_rcp_f32_e32 v235, v235
	v_mul_f32_e32 v52, v52, v128
	v_mul_f32_e32 v53, v53, v232
	v_mul_f32_e32 v54, v54, v129
	v_mul_f32_e32 v55, v55, v233
	v_mul_f32_e32 v48, v48, v130
	v_mul_f32_e32 v49, v49, v234
	v_mul_f32_e32 v50, v50, v131
	v_mul_f32_e32 v51, v51, v235
	v_lshlrev_b32_e32 v128, 16, v236
	v_and_b32_e32 v236, 0xffff0000, v236
	v_lshlrev_b32_e32 v129, 16, v237
	v_and_b32_e32 v237, 0xffff0000, v237
	v_lshlrev_b32_e32 v130, 16, v238
	v_and_b32_e32 v238, 0xffff0000, v238
	v_lshlrev_b32_e32 v131, 16, v239
	v_and_b32_e32 v239, 0xffff0000, v239
	v_mul_f32_e32 v128, 0xbfb8aa3b, v128
	v_mul_f32_e32 v236, 0xbfb8aa3b, v236
	v_mul_f32_e32 v129, 0xbfb8aa3b, v129
	v_mul_f32_e32 v237, 0xbfb8aa3b, v237
	v_mul_f32_e32 v130, 0xbfb8aa3b, v130
	v_mul_f32_e32 v238, 0xbfb8aa3b, v238
	v_mul_f32_e32 v131, 0xbfb8aa3b, v131
	v_mul_f32_e32 v239, 0xbfb8aa3b, v239
	v_exp_f32_e32 v128, v128
	v_exp_f32_e32 v236, v236
	v_exp_f32_e32 v129, v129
	v_exp_f32_e32 v237, v237
	v_exp_f32_e32 v130, v130
	v_exp_f32_e32 v238, v238
	v_exp_f32_e32 v131, v131
	v_exp_f32_e32 v239, v239
	v_add_f32_e32 v128, 1.0, v128
	v_add_f32_e32 v236, 1.0, v236
	v_add_f32_e32 v129, 1.0, v129
	v_add_f32_e32 v237, 1.0, v237
	v_add_f32_e32 v130, 1.0, v130
	v_add_f32_e32 v238, 1.0, v238
	v_add_f32_e32 v131, 1.0, v131
	v_add_f32_e32 v239, 1.0, v239
	v_rcp_f32_e32 v128, v128
	v_rcp_f32_e32 v236, v236
	v_rcp_f32_e32 v129, v129
	v_rcp_f32_e32 v237, v237
	v_rcp_f32_e32 v130, v130
	v_rcp_f32_e32 v238, v238
	v_rcp_f32_e32 v131, v131
	v_rcp_f32_e32 v239, v239
	v_mul_f32_e32 v20, v20, v128
	v_mul_f32_e32 v21, v21, v236
	v_mul_f32_e32 v22, v22, v129
	v_mul_f32_e32 v23, v23, v237
	v_mul_f32_e32 v16, v16, v130
	v_mul_f32_e32 v17, v17, v238
	v_mul_f32_e32 v18, v18, v131
	v_mul_f32_e32 v19, v19, v239
	v_cvt_pk_bf16_f32 v232, v52, v53
	v_cvt_pk_bf16_f32 v233, v54, v55
	v_cvt_pk_bf16_f32 v234, v48, v49
	v_cvt_pk_bf16_f32 v235, v50, v51
	global_store_dwordx4 v[144:145], v[232:235], off
	v_cvt_pk_bf16_f32 v236, v20, v21
	v_cvt_pk_bf16_f32 v237, v22, v23
	v_cvt_pk_bf16_f32 v238, v16, v17
	v_cvt_pk_bf16_f32 v239, v18, v19
	global_store_dwordx4 v[144:145], v[236:239], off offset:256
	v_lshl_add_u64 v[144:145], v[144:145], 0, s[18:19]
	s_waitcnt vmcnt(6)
; DEV unsigned cvt_pk_bf16(float lo, float hi) { const f32x2_ v = {lo, hi}; return __builtin_bit_cast(unsigned, __builtin_convertvector(v, bf16x2n_)); }
; DEV float bflo(unsigned w) { return __uint_as_float(w << 16); }
; DEV float bfhi(unsigned w) { return __uint_as_float(w & 0xffff0000u); }
; #define RS_(xa, xb) ((1.0f + one * __expf(-(xb))) * __builtin_amdgcn_rcpf(1.0f + __expf(-(xa))))
;   DEV bool rescale(f32x4 (&acc)[2][2][4][2], const Unit& u, int wr, int wc, int fr, int fq) const {
;     ...
;         const size_t r = (size_t)(row0 + ai * HALF + m * 16);
; #pragma unroll
;         for (int bj = 0; bj < 2; ++bj) {
;           const int c = col0 + bj * HALF;
;           const u32x4 ga = *(const u32x4*)(Z + r * NIN + GT + u.seg * D + c);
;           const u32x4 gb = *(const u32x4*)(Z + r * NIN + GT + sb * D + c);
;     ...
;           acc[ai][bj][m][0][0] *= RS_(bflo(ga.x), bflo(gb.x)); acc[ai][bj][m][0][1] *= RS_(bfhi(ga.x), bfhi(gb.x));
;           acc[ai][bj][m][0][2] *= RS_(bflo(ga.y), bflo(gb.y)); acc[ai][bj][m][0][3] *= RS_(bfhi(ga.y), bfhi(gb.y));
;           acc[ai][bj][m][1][0] *= RS_(bflo(ga.z), bflo(gb.z)); acc[ai][bj][m][1][1] *= RS_(bfhi(ga.z), bfhi(gb.z));
;           acc[ai][bj][m][1][2] *= RS_(bflo(ga.w), bflo(gb.w)); acc[ai][bj][m][1][3] *= RS_(bfhi(ga.w), bfhi(gb.w));
;   DEV void operator()(const f32x4 (&acc)[2][2][4][2], const Unit& u, int wr, int wc, int fr, int fq) const {
;     ...
;         bf16_t* rowp = H + (size_t)(row0 + ai * HALF + m * 16) * D + col0;
; #pragma unroll
;         for (int bj = 0; bj < 2; ++bj) {
;           const f32x4 v0 = acc[ai][bj][m][0], v1 = acc[ai][bj][m][1];
;           u32x4 w; w.x = cvt_pk_bf16(v0[0], v0[1]); w.y = cvt_pk_bf16(v0[2], v0[3]); w.z = cvt_pk_bf16(v1[0], v1[1]); w.w = cvt_pk_bf16(v1[2], v1[3]);
;           *(u32x4*)(rowp + bj * HALF) = w;
	v_lshlrev_b32_e32 v128, 16, v180
	v_and_b32_e32 v180, 0xffff0000, v180
	v_lshlrev_b32_e32 v129, 16, v181
	v_and_b32_e32 v181, 0xffff0000, v181
	v_lshlrev_b32_e32 v130, 16, v182
	v_and_b32_e32 v182, 0xffff0000, v182
	v_lshlrev_b32_e32 v131, 16, v183
	v_and_b32_e32 v183, 0xffff0000, v183
	v_mul_f32_e32 v128, 0xbfb8aa3b, v128
	v_mul_f32_e32 v180, 0xbfb8aa3b, v180
	v_mul_f32_e32 v129, 0xbfb8aa3b, v129
	v_mul_f32_e32 v181, 0xbfb8aa3b, v181
	v_mul_f32_e32 v130, 0xbfb8aa3b, v130
	v_mul_f32_e32 v182, 0xbfb8aa3b, v182
	v_mul_f32_e32 v131, 0xbfb8aa3b, v131
	v_mul_f32_e32 v183, 0xbfb8aa3b, v183
	v_exp_f32_e32 v128, v128
	v_exp_f32_e32 v180, v180
	v_exp_f32_e32 v129, v129
	v_exp_f32_e32 v181, v181
	v_exp_f32_e32 v130, v130
	v_exp_f32_e32 v182, v182
	v_exp_f32_e32 v131, v131
	v_exp_f32_e32 v183, v183
	v_add_f32_e32 v128, 1.0, v128
	v_add_f32_e32 v180, 1.0, v180
	v_add_f32_e32 v129, 1.0, v129
	v_add_f32_e32 v181, 1.0, v181
	v_add_f32_e32 v130, 1.0, v130
	v_add_f32_e32 v182, 1.0, v182
	v_add_f32_e32 v131, 1.0, v131
	v_add_f32_e32 v183, 1.0, v183
	v_rcp_f32_e32 v128, v128
	v_rcp_f32_e32 v180, v180
	v_rcp_f32_e32 v129, v129
	v_rcp_f32_e32 v181, v181
	v_rcp_f32_e32 v130, v130
	v_rcp_f32_e32 v182, v182
	v_rcp_f32_e32 v131, v131
	v_rcp_f32_e32 v183, v183
	v_mul_f32_e32 v44, v44, v128
	v_mul_f32_e32 v45, v45, v180
	v_mul_f32_e32 v46, v46, v129
	v_mul_f32_e32 v47, v47, v181
	v_mul_f32_e32 v40, v40, v130
	v_mul_f32_e32 v41, v41, v182
	v_mul_f32_e32 v42, v42, v131
	v_mul_f32_e32 v43, v43, v183
	v_lshlrev_b32_e32 v128, 16, v184
	v_and_b32_e32 v184, 0xffff0000, v184
	v_lshlrev_b32_e32 v129, 16, v185
	v_and_b32_e32 v185, 0xffff0000, v185
	v_lshlrev_b32_e32 v130, 16, v186
	v_and_b32_e32 v186, 0xffff0000, v186
	v_lshlrev_b32_e32 v131, 16, v187
	v_and_b32_e32 v187, 0xffff0000, v187
	v_mul_f32_e32 v128, 0xbfb8aa3b, v128
	v_mul_f32_e32 v184, 0xbfb8aa3b, v184
	v_mul_f32_e32 v129, 0xbfb8aa3b, v129
	v_mul_f32_e32 v185, 0xbfb8aa3b, v185
	v_mul_f32_e32 v130, 0xbfb8aa3b, v130
	v_mul_f32_e32 v186, 0xbfb8aa3b, v186
	v_mul_f32_e32 v131, 0xbfb8aa3b, v131
	v_mul_f32_e32 v187, 0xbfb8aa3b, v187
	v_exp_f32_e32 v128, v128
	v_exp_f32_e32 v184, v184
	v_exp_f32_e32 v129, v129
	v_exp_f32_e32 v185, v185
	v_exp_f32_e32 v130, v130
	v_exp_f32_e32 v186, v186
	v_exp_f32_e32 v131, v131
	v_exp_f32_e32 v187, v187
	v_add_f32_e32 v128, 1.0, v128
	v_add_f32_e32 v184, 1.0, v184
	v_add_f32_e32 v129, 1.0, v129
	v_add_f32_e32 v185, 1.0, v185
	v_add_f32_e32 v130, 1.0, v130
	v_add_f32_e32 v186, 1.0, v186
	v_add_f32_e32 v131, 1.0, v131
	v_add_f32_e32 v187, 1.0, v187
	v_rcp_f32_e32 v128, v128
	v_rcp_f32_e32 v184, v184
	v_rcp_f32_e32 v129, v129
	v_rcp_f32_e32 v185, v185
	v_rcp_f32_e32 v130, v130
	v_rcp_f32_e32 v186, v186
	v_rcp_f32_e32 v131, v131
	v_rcp_f32_e32 v187, v187
	v_mul_f32_e32 v12, v12, v128
	v_mul_f32_e32 v13, v13, v184
	v_mul_f32_e32 v14, v14, v129
	v_mul_f32_e32 v15, v15, v185
	v_mul_f32_e32 v8, v8, v130
	v_mul_f32_e32 v9, v9, v186
	v_mul_f32_e32 v10, v10, v131
	v_mul_f32_e32 v11, v11, v187
	v_cvt_pk_bf16_f32 v180, v44, v45
	v_cvt_pk_bf16_f32 v181, v46, v47
	v_cvt_pk_bf16_f32 v182, v40, v41
	v_cvt_pk_bf16_f32 v183, v42, v43
	global_store_dwordx4 v[144:145], v[180:183], off
	v_cvt_pk_bf16_f32 v184, v12, v13
	v_cvt_pk_bf16_f32 v185, v14, v15
	v_cvt_pk_bf16_f32 v186, v8, v9
	v_cvt_pk_bf16_f32 v187, v10, v11
	global_store_dwordx4 v[144:145], v[184:187], off offset:256
	v_lshl_add_u64 v[144:145], v[144:145], 0, s[18:19]
	s_waitcnt vmcnt(4)
	v_lshlrev_b32_e32 v128, 16, v196
	v_and_b32_e32 v196, 0xffff0000, v196
	v_lshlrev_b32_e32 v129, 16, v197
	v_and_b32_e32 v197, 0xffff0000, v197
	v_lshlrev_b32_e32 v130, 16, v198
	v_and_b32_e32 v198, 0xffff0000, v198
	v_lshlrev_b32_e32 v131, 16, v199
	v_and_b32_e32 v199, 0xffff0000, v199
	v_mul_f32_e32 v128, 0xbfb8aa3b, v128
	v_mul_f32_e32 v196, 0xbfb8aa3b, v196
	v_mul_f32_e32 v129, 0xbfb8aa3b, v129
	v_mul_f32_e32 v197, 0xbfb8aa3b, v197
	v_mul_f32_e32 v130, 0xbfb8aa3b, v130
	v_mul_f32_e32 v198, 0xbfb8aa3b, v198
	v_mul_f32_e32 v131, 0xbfb8aa3b, v131
	v_mul_f32_e32 v199, 0xbfb8aa3b, v199
	v_exp_f32_e32 v128, v128
	v_exp_f32_e32 v196, v196
	v_exp_f32_e32 v129, v129
	v_exp_f32_e32 v197, v197
	v_exp_f32_e32 v130, v130
	v_exp_f32_e32 v198, v198
	v_exp_f32_e32 v131, v131
	v_exp_f32_e32 v199, v199
	v_add_f32_e32 v128, 1.0, v128
	v_add_f32_e32 v196, 1.0, v196
	v_add_f32_e32 v129, 1.0, v129
	v_add_f32_e32 v197, 1.0, v197
	v_add_f32_e32 v130, 1.0, v130
	v_add_f32_e32 v198, 1.0, v198
	v_add_f32_e32 v131, 1.0, v131
	v_add_f32_e32 v199, 1.0, v199
	v_rcp_f32_e32 v128, v128
	v_rcp_f32_e32 v196, v196
	v_rcp_f32_e32 v129, v129
	v_rcp_f32_e32 v197, v197
	v_rcp_f32_e32 v130, v130
	v_rcp_f32_e32 v198, v198
	v_rcp_f32_e32 v131, v131
	v_rcp_f32_e32 v199, v199
	v_mul_f32_e32 v36, v36, v128
	v_mul_f32_e32 v37, v37, v196
	v_mul_f32_e32 v38, v38, v129
	v_mul_f32_e32 v39, v39, v197
	v_mul_f32_e32 v32, v32, v130
	v_mul_f32_e32 v33, v33, v198
	v_mul_f32_e32 v34, v34, v131
	v_mul_f32_e32 v35, v35, v199
	v_lshlrev_b32_e32 v128, 16, v220
	v_and_b32_e32 v220, 0xffff0000, v220
	v_lshlrev_b32_e32 v129, 16, v221
	v_and_b32_e32 v221, 0xffff0000, v221
	v_lshlrev_b32_e32 v130, 16, v222
	v_and_b32_e32 v222, 0xffff0000, v222
	v_lshlrev_b32_e32 v131, 16, v223
	v_and_b32_e32 v223, 0xffff0000, v223
	v_mul_f32_e32 v128, 0xbfb8aa3b, v128
	v_mul_f32_e32 v220, 0xbfb8aa3b, v220
	v_mul_f32_e32 v129, 0xbfb8aa3b, v129
	v_mul_f32_e32 v221, 0xbfb8aa3b, v221
	v_mul_f32_e32 v130, 0xbfb8aa3b, v130
	v_mul_f32_e32 v222, 0xbfb8aa3b, v222
	v_mul_f32_e32 v131, 0xbfb8aa3b, v131
	v_mul_f32_e32 v223, 0xbfb8aa3b, v223
	v_exp_f32_e32 v128, v128
	v_exp_f32_e32 v220, v220
	v_exp_f32_e32 v129, v129
	v_exp_f32_e32 v221, v221
	v_exp_f32_e32 v130, v130
	v_exp_f32_e32 v222, v222
	v_exp_f32_e32 v131, v131
	v_exp_f32_e32 v223, v223
	v_add_f32_e32 v128, 1.0, v128
	v_add_f32_e32 v220, 1.0, v220
	v_add_f32_e32 v129, 1.0, v129
	v_add_f32_e32 v221, 1.0, v221
	v_add_f32_e32 v130, 1.0, v130
	v_add_f32_e32 v222, 1.0, v222
	v_add_f32_e32 v131, 1.0, v131
	v_add_f32_e32 v223, 1.0, v223
	v_rcp_f32_e32 v128, v128
	v_rcp_f32_e32 v220, v220
	v_rcp_f32_e32 v129, v129
	v_rcp_f32_e32 v221, v221
	v_rcp_f32_e32 v130, v130
	v_rcp_f32_e32 v222, v222
	v_rcp_f32_e32 v131, v131
	v_rcp_f32_e32 v223, v223
	v_mul_f32_e32 v4, v4, v128
	v_mul_f32_e32 v5, v5, v220
	v_mul_f32_e32 v6, v6, v129
	v_mul_f32_e32 v7, v7, v221
	v_mul_f32_e32 v0, v0, v130
	v_mul_f32_e32 v1, v1, v222
	v_mul_f32_e32 v2, v2, v131
	v_mul_f32_e32 v3, v3, v223
	v_cvt_pk_bf16_f32 v196, v36, v37
	v_cvt_pk_bf16_f32 v197, v38, v39
	v_cvt_pk_bf16_f32 v198, v32, v33
	v_cvt_pk_bf16_f32 v199, v34, v35
	global_store_dwordx4 v[144:145], v[196:199], off
	v_cvt_pk_bf16_f32 v220, v4, v5
	v_cvt_pk_bf16_f32 v221, v6, v7
	v_cvt_pk_bf16_f32 v222, v0, v1
	v_cvt_pk_bf16_f32 v223, v2, v3
	global_store_dwordx4 v[144:145], v[220:223], off offset:256
